# NR=4 rings for all gemm loops, staging atoms placed later (0.60/0.95)
# baseline (speedup 1.0000x reference)
; DI f32x4 mfma16(bf16x8 a, bf16x8 b, f32x4 c) { return __builtin_amdgcn_mfma_f32_16x16x32_bf16(a, b, c, 0, 0, 0); }
; template <int MI, int NJ, bool SWAP, class AP, class BP>
; DI void gemm_main(f32x4 (&acc)[MI][NJ], const AP& ap, int a_kstep, const BP& bp, int b_kstep, int nk, bf16_t* smem) {
;     ...
;   auto gload = [&](int kt) {
;     const bf16_t* ab = ap.base + (size_t)kt * a_kstep; const bf16_t* bb = bp.base + (size_t)kt * b_kstep;
; #pragma unroll
;     for (int i = 0; i < CA; ++i) ra[i] = *(const u32x4*)(ab + pa[i]);
; #pragma unroll
;     for (int i = 0; i < CB; ++i) rb[i] = *(const u32x4*)(bb + pb[i]);
;   };
;   auto sstore = [&](int buf) {
;     bf16_t* As = smem + buf * L::STAGE; bf16_t* Bs = As + L::A_ELEMS;
; #pragma unroll
;     for (int i = 0; i < CA; ++i) { const int c = tid + NTHR * i; *(u32x4*)(As + (c >> 3) * LDT + (c & 7) * 8) = oka[i] ? ra[i] : (u32x4){0u, 0u, 0u, 0u}; }
; #pragma unroll
;     for (int i = 0; i < CB; ++i) { const int c = tid + NTHR * i; *(u32x4*)(Bs + (c >> 3) * LDT + (c & 7) * 8) = rb[i]; }
;   };
;   gload(0); sstore(0); gload(nk > 1 ? 1 : 0); __syncthreads();
; #pragma unroll 1
;   for (int kt = 0; kt < nk; ++kt) {
;     const int buf = kt & 1;
;     sstore(buf ^ 1);
;     gload(kt + 2 < nk ? kt + 2 : nk - 1);
;     __builtin_amdgcn_sched_barrier(0);
;     const bf16_t* As = smem + buf * L::STAGE + (wm * 16 * MI + l15) * LDT + quad * 8;
;     const bf16_t* Bs = smem + buf * L::STAGE + L::A_ELEMS + (wn * 16 * NJ + l15) * LDT + quad * 8;
; #pragma unroll
;     for (int ks = 0; ks < 2; ++ks) {
;       if (MI * NJ >= 32 && ks == 1) asm volatile("" ::: "memory");
;       bf16x8 b[NJ];
; #pragma unroll
;       for (int j = 0; j < NJ; ++j) b[j] = *(const bf16x8*)(Bs + j * 16 * LDT + ks * 32);
; #pragma unroll
;       for (int i = 0; i < MI; ++i) {
;         const bf16x8 a = *(const bf16x8*)(As + i * 16 * LDT + ks * 32);
; #pragma unroll
;         for (int j = 0; j < NJ; ++j) acc[i][j] = SWAP ? mfma16(b[j], a, acc[i][j]) : mfma16(a, b[j], acc[i][j]);
;       }
;     }
;     __syncthreads();
;   }
.Lgm0_main:
	ds_read_b128 v[242:245], v176 offset:4608
	s_waitcnt lgkmcnt(4)
	v_mfma_f32_16x16x32_bf16 v[124:127], v[178:181], v[212:215], v[124:127]
	s_waitcnt lgkmcnt(3)
	v_mfma_f32_16x16x32_bf16 v[120:123], v[200:203], v[212:215], v[120:123]
	s_waitcnt lgkmcnt(2)
	v_mfma_f32_16x16x32_bf16 v[116:119], v[204:207], v[212:215], v[116:119]
	s_waitcnt lgkmcnt(1)
	v_mfma_f32_16x16x32_bf16 v[112:115], v[208:211], v[212:215], v[112:115]
	s_and_b32 s5, s4, 1
	s_min_u32 s6, s4, 13
	s_xor_b32 s7, s5, 1
	s_lshl_b32 s33, s6, 7
	s_mul_i32 s7, s7, 0x12000
	s_add_u32 s6, s0, s33
	v_add3_u32 v250, s7, v171, v169
	v_add3_u32 v251, s7, v173, v169
	v_add3_u32 v252, s7, v174, v169
	v_add3_u32 v253, s7, v175, v169
	s_addc_u32 s7, s1, 0
	s_waitcnt vmcnt(7)
	ds_write_b128 v250, v[128:131]
	ds_read_b128 v[246:249], v176 offset:6912
	v_mfma_f32_16x16x32_bf16 v[108:111], v[178:181], v[216:219], v[108:111]
	v_mfma_f32_16x16x32_bf16 v[104:107], v[200:203], v[216:219], v[104:107]
	v_mfma_f32_16x16x32_bf16 v[100:103], v[204:207], v[216:219], v[100:103]
	v_mfma_f32_16x16x32_bf16 v[96:99], v[208:211], v[216:219], v[96:99]
	s_waitcnt vmcnt(6)
	ds_write_b128 v251, v[132:135]
	ds_read_b128 v[212:215], v176 offset:9216
	s_waitcnt lgkmcnt(4)
	v_mfma_f32_16x16x32_bf16 v[92:95], v[178:181], v[242:245], v[92:95]
	v_mfma_f32_16x16x32_bf16 v[88:91], v[200:203], v[242:245], v[88:91]
	v_mfma_f32_16x16x32_bf16 v[84:87], v[204:207], v[242:245], v[84:87]
	v_mfma_f32_16x16x32_bf16 v[80:83], v[208:211], v[242:245], v[80:83]
	ds_read_b128 v[216:219], v176 offset:11520
	s_waitcnt lgkmcnt(3)
	v_mfma_f32_16x16x32_bf16 v[76:79], v[178:181], v[246:249], v[76:79]
	s_waitcnt vmcnt(5)
	ds_write_b128 v252, v[136:139]
	v_mfma_f32_16x16x32_bf16 v[72:75], v[200:203], v[246:249], v[72:75]
	v_mfma_f32_16x16x32_bf16 v[68:71], v[204:207], v[246:249], v[68:71]
	v_mfma_f32_16x16x32_bf16 v[64:67], v[208:211], v[246:249], v[64:67]
	ds_read_b128 v[242:245], v176 offset:13824
	s_waitcnt lgkmcnt(3)
	v_mfma_f32_16x16x32_bf16 v[60:63], v[178:181], v[212:215], v[60:63]
	s_waitcnt vmcnt(4)
	ds_write_b128 v253, v[140:143]
	v_mfma_f32_16x16x32_bf16 v[56:59], v[200:203], v[212:215], v[56:59]
	v_mfma_f32_16x16x32_bf16 v[52:55], v[204:207], v[212:215], v[52:55]
	v_mfma_f32_16x16x32_bf16 v[48:51], v[208:211], v[212:215], v[48:51]
	ds_read_b128 v[246:249], v176 offset:16128
	s_waitcnt lgkmcnt(4)
	v_mfma_f32_16x16x32_bf16 v[44:47], v[178:181], v[216:219], v[44:47]
	s_waitcnt vmcnt(3)
	ds_write_b128 v250, v[144:147] offset:36864
	v_mfma_f32_16x16x32_bf16 v[40:43], v[200:203], v[216:219], v[40:43]
	v_mfma_f32_16x16x32_bf16 v[36:39], v[204:207], v[216:219], v[36:39]
	v_mfma_f32_16x16x32_bf16 v[32:35], v[208:211], v[216:219], v[32:35]
	ds_read_b128 v[212:215], v176 offset:64
	s_waitcnt lgkmcnt(4)
	v_mfma_f32_16x16x32_bf16 v[28:31], v[178:181], v[242:245], v[28:31]
	s_waitcnt vmcnt(2)
	ds_write_b128 v251, v[148:151] offset:36864
	v_mfma_f32_16x16x32_bf16 v[24:27], v[200:203], v[242:245], v[24:27]
	v_mfma_f32_16x16x32_bf16 v[20:23], v[204:207], v[242:245], v[20:23]
	v_mfma_f32_16x16x32_bf16 v[16:19], v[208:211], v[242:245], v[16:19]
	ds_read_b128 v[216:219], v176 offset:2368
	s_waitcnt lgkmcnt(4)
	v_mfma_f32_16x16x32_bf16 v[12:15], v[178:181], v[246:249], v[12:15]
	ds_read_b128 v[178:181], v182 offset:36928
	s_waitcnt vmcnt(1)
	ds_write_b128 v252, v[152:155] offset:36864
	v_mfma_f32_16x16x32_bf16 v[8:11], v[200:203], v[246:249], v[8:11]
	ds_read_b128 v[200:203], v182 offset:39232
	v_mfma_f32_16x16x32_bf16 v[0:3], v[204:207], v[246:249], v[0:3]
	ds_read_b128 v[204:207], v182 offset:41536
	v_mfma_f32_16x16x32_bf16 v[4:7], v[208:211], v[246:249], v[4:7]
	ds_read_b128 v[208:211], v182 offset:43840
	ds_read_b128 v[242:245], v176 offset:4672
	s_waitcnt lgkmcnt(5)
	v_mfma_f32_16x16x32_bf16 v[124:127], v[178:181], v[212:215], v[124:127]
	s_waitcnt lgkmcnt(3)
	v_mfma_f32_16x16x32_bf16 v[120:123], v[200:203], v[212:215], v[120:123]
	s_waitcnt vmcnt(0)
	ds_write_b128 v253, v[156:159] offset:36864
	s_waitcnt lgkmcnt(3)
	v_mfma_f32_16x16x32_bf16 v[116:119], v[204:207], v[212:215], v[116:119]
	s_waitcnt lgkmcnt(2)
	v_mfma_f32_16x16x32_bf16 v[112:115], v[208:211], v[212:215], v[112:115]
	v_lshl_add_u64 v[128:129], s[6:7], 0, v[160:161]
	v_lshl_add_u64 v[132:133], s[6:7], 0, v[162:163]
	v_lshl_add_u64 v[136:137], s[6:7], 0, v[164:165]
	v_lshl_add_u64 v[140:141], s[6:7], 0, v[166:167]
	s_add_u32 s6, s2, s33
	s_addc_u32 s7, s3, 0
	v_lshl_add_u64 v[144:145], s[6:7], 0, v[160:161]
	v_lshl_add_u64 v[148:149], s[6:7], 0, v[162:163]
	v_lshl_add_u64 v[152:153], s[6:7], 0, v[164:165]
	v_lshl_add_u64 v[156:157], s[6:7], 0, v[166:167]
	global_load_dwordx4 v[128:131], v[128:129], off offset:256
	ds_read_b128 v[246:249], v176 offset:6976
	v_mfma_f32_16x16x32_bf16 v[108:111], v[178:181], v[216:219], v[108:111]
	v_mfma_f32_16x16x32_bf16 v[104:107], v[200:203], v[216:219], v[104:107]
	s_nop 0
	global_load_dwordx4 v[132:135], v[132:133], off offset:256
	v_mfma_f32_16x16x32_bf16 v[100:103], v[204:207], v[216:219], v[100:103]
	v_mfma_f32_16x16x32_bf16 v[96:99], v[208:211], v[216:219], v[96:99]
	ds_read_b128 v[212:215], v176 offset:9280
	s_waitcnt lgkmcnt(3)
	v_mfma_f32_16x16x32_bf16 v[92:95], v[178:181], v[242:245], v[92:95]
	s_nop 0
	global_load_dwordx4 v[136:139], v[136:137], off offset:256
	v_mfma_f32_16x16x32_bf16 v[88:91], v[200:203], v[242:245], v[88:91]
	v_mfma_f32_16x16x32_bf16 v[84:87], v[204:207], v[242:245], v[84:87]
	s_nop 0
	global_load_dwordx4 v[140:143], v[140:141], off offset:256
	v_mfma_f32_16x16x32_bf16 v[80:83], v[208:211], v[242:245], v[80:83]
	ds_read_b128 v[216:219], v176 offset:11584
	s_waitcnt lgkmcnt(2)
	v_mfma_f32_16x16x32_bf16 v[76:79], v[178:181], v[246:249], v[76:79]
	v_mfma_f32_16x16x32_bf16 v[72:75], v[200:203], v[246:249], v[72:75]
	s_nop 0
	global_load_dwordx4 v[144:147], v[144:145], off offset:256
	v_mfma_f32_16x16x32_bf16 v[68:71], v[204:207], v[246:249], v[68:71]
	v_mfma_f32_16x16x32_bf16 v[64:67], v[208:211], v[246:249], v[64:67]
	s_nop 0
	global_load_dwordx4 v[148:151], v[148:149], off offset:256
	ds_read_b128 v[242:245], v176 offset:13888
	s_waitcnt lgkmcnt(2)
	v_mfma_f32_16x16x32_bf16 v[60:63], v[178:181], v[212:215], v[60:63]
	v_mfma_f32_16x16x32_bf16 v[56:59], v[200:203], v[212:215], v[56:59]
	v_mfma_f32_16x16x32_bf16 v[52:55], v[204:207], v[212:215], v[52:55]
	s_nop 0
	global_load_dwordx4 v[152:155], v[152:153], off offset:256
	v_mfma_f32_16x16x32_bf16 v[48:51], v[208:211], v[212:215], v[48:51]
	ds_read_b128 v[246:249], v176 offset:16192
	s_waitcnt lgkmcnt(2)
	v_mfma_f32_16x16x32_bf16 v[44:47], v[178:181], v[216:219], v[44:47]
	s_nop 0
	global_load_dwordx4 v[156:159], v[156:157], off offset:256
	v_mfma_f32_16x16x32_bf16 v[40:43], v[200:203], v[216:219], v[40:43]
	v_mfma_f32_16x16x32_bf16 v[36:39], v[204:207], v[216:219], v[36:39]
	v_mfma_f32_16x16x32_bf16 v[32:35], v[208:211], v[216:219], v[32:35]
	s_waitcnt lgkmcnt(0)
	s_barrier
; DI f32x4 mfma16(bf16x8 a, bf16x8 b, f32x4 c) { return __builtin_amdgcn_mfma_f32_16x16x32_bf16(a, b, c, 0, 0, 0); }
; template <int MI, int NJ, bool SWAP, class AP, class BP>
; DI void gemm_main(f32x4 (&acc)[MI][NJ], const AP& ap, int a_kstep, const BP& bp, int b_kstep, int nk, bf16_t* smem) {
;     ...
;   for (int kt = 0; kt < nk; ++kt) {
;     const int buf = kt & 1;
;     sstore(buf ^ 1);
;     gload(kt + 2 < nk ? kt + 2 : nk - 1);
;     __builtin_amdgcn_sched_barrier(0);
;     const bf16_t* As = smem + buf * L::STAGE + (wm * 16 * MI + l15) * LDT + quad * 8;
;     const bf16_t* Bs = smem + buf * L::STAGE + L::A_ELEMS + (wn * 16 * NJ + l15) * LDT + quad * 8;
; #pragma unroll
;     for (int ks = 0; ks < 2; ++ks) {
;       if (MI * NJ >= 32 && ks == 1) asm volatile("" ::: "memory");
;       bf16x8 b[NJ];
; #pragma unroll
;       for (int j = 0; j < NJ; ++j) b[j] = *(const bf16x8*)(Bs + j * 16 * LDT + ks * 32);
; #pragma unroll
;       for (int i = 0; i < MI; ++i) {
;         const bf16x8 a = *(const bf16x8*)(As + i * 16 * LDT + ks * 32);
; #pragma unroll
;         for (int j = 0; j < NJ; ++j) acc[i][j] = SWAP ? mfma16(b[j], a, acc[i][j]) : mfma16(a, b[j], acc[i][j]);
	s_add_i32 s4, s4, 1
	s_cmp_lg_u32 s4, 16
	s_cbranch_scc0 .Lgm0_exit
	s_and_b32 s98, s4, 1
	s_mul_i32 s98, s98, 0x12000
	v_add3_u32 v182, s98, v168, v172
	v_add3_u32 v176, s98, v170, v172
	ds_read_b128 v[212:215], v176
	ds_read_b128 v[216:219], v176 offset:2304
	v_mfma_f32_16x16x32_bf16 v[28:31], v[178:181], v[242:245], v[28:31]
	v_mfma_f32_16x16x32_bf16 v[12:15], v[178:181], v[246:249], v[12:15]
	ds_read_b128 v[178:181], v182 offset:36864
	v_mfma_f32_16x16x32_bf16 v[24:27], v[200:203], v[242:245], v[24:27]
	v_mfma_f32_16x16x32_bf16 v[8:11], v[200:203], v[246:249], v[8:11]
	ds_read_b128 v[200:203], v182 offset:39168
	v_mfma_f32_16x16x32_bf16 v[20:23], v[204:207], v[242:245], v[20:23]
	v_mfma_f32_16x16x32_bf16 v[0:3], v[204:207], v[246:249], v[0:3]
	ds_read_b128 v[204:207], v182 offset:41472
	v_mfma_f32_16x16x32_bf16 v[16:19], v[208:211], v[242:245], v[16:19]
	v_mfma_f32_16x16x32_bf16 v[4:7], v[208:211], v[246:249], v[4:7]
	ds_read_b128 v[208:211], v182 offset:43776
	s_branch .Lgm0_main

; DI f32x4 mfma16(bf16x8 a, bf16x8 b, f32x4 c) { return __builtin_amdgcn_mfma_f32_16x16x32_bf16(a, b, c, 0, 0, 0); }
; template <int MI, int NJ, bool SWAP, class AP, class BP>
; DI void gemm_main(f32x4 (&acc)[MI][NJ], const AP& ap, int a_kstep, const BP& bp, int b_kstep, int nk, bf16_t* smem) {
;     ...
;   auto gload = [&](int kt) {
;     const bf16_t* ab = ap.base + (size_t)kt * a_kstep; const bf16_t* bb = bp.base + (size_t)kt * b_kstep;
; #pragma unroll
;     for (int i = 0; i < CA; ++i) ra[i] = *(const u32x4*)(ab + pa[i]);
; #pragma unroll
;     for (int i = 0; i < CB; ++i) rb[i] = *(const u32x4*)(bb + pb[i]);
;   };
;   auto sstore = [&](int buf) {
;     bf16_t* As = smem + buf * L::STAGE; bf16_t* Bs = As + L::A_ELEMS;
; #pragma unroll
;     for (int i = 0; i < CA; ++i) { const int c = tid + NTHR * i; *(u32x4*)(As + (c >> 3) * LDT + (c & 7) * 8) = oka[i] ? ra[i] : (u32x4){0u, 0u, 0u, 0u}; }
; #pragma unroll
;     for (int i = 0; i < CB; ++i) { const int c = tid + NTHR * i; *(u32x4*)(Bs + (c >> 3) * LDT + (c & 7) * 8) = rb[i]; }
;   };
;   gload(0); sstore(0); gload(nk > 1 ? 1 : 0); __syncthreads();
; #pragma unroll 1
;   for (int kt = 0; kt < nk; ++kt) {
;     const int buf = kt & 1;
;     sstore(buf ^ 1);
;     gload(kt + 2 < nk ? kt + 2 : nk - 1);
;     __builtin_amdgcn_sched_barrier(0);
;     const bf16_t* As = smem + buf * L::STAGE + (wm * 16 * MI + l15) * LDT + quad * 8;
;     const bf16_t* Bs = smem + buf * L::STAGE + L::A_ELEMS + (wn * 16 * NJ + l15) * LDT + quad * 8;
; #pragma unroll
;     for (int ks = 0; ks < 2; ++ks) {
;       if (MI * NJ >= 32 && ks == 1) asm volatile("" ::: "memory");
;       bf16x8 b[NJ];
; #pragma unroll
;       for (int j = 0; j < NJ; ++j) b[j] = *(const bf16x8*)(Bs + j * 16 * LDT + ks * 32);
; #pragma unroll
;       for (int i = 0; i < MI; ++i) {
;         const bf16x8 a = *(const bf16x8*)(As + i * 16 * LDT + ks * 32);
; #pragma unroll
;         for (int j = 0; j < NJ; ++j) acc[i][j] = SWAP ? mfma16(b[j], a, acc[i][j]) : mfma16(a, b[j], acc[i][j]);
;       }
;     }
;     __syncthreads();
;   }
.Lgm1_main:
	ds_read_b128 v[242:245], v176 offset:4608
	s_waitcnt lgkmcnt(4)
	v_mfma_f32_16x16x32_bf16 v[124:127], v[212:215], v[178:181], v[124:127]
	s_waitcnt lgkmcnt(3)
	v_mfma_f32_16x16x32_bf16 v[120:123], v[212:215], v[200:203], v[120:123]
	s_waitcnt lgkmcnt(2)
	v_mfma_f32_16x16x32_bf16 v[116:119], v[212:215], v[204:207], v[116:119]
	s_waitcnt lgkmcnt(1)
	v_mfma_f32_16x16x32_bf16 v[112:115], v[212:215], v[208:211], v[112:115]
	s_and_b32 s5, s4, 1
	s_min_u32 s6, s4, 13
	s_xor_b32 s7, s5, 1
	s_lshl_b32 s33, s6, 7
	v_lshlrev_b32_e32 v250, 1, v168
	v_lshlrev_b32_e32 v251, 1, v171
	v_lshlrev_b32_e32 v252, 1, v172
	v_lshlrev_b32_e32 v253, 1, v173
	s_mul_i32 s7, s7, 0x12000
	s_add_u32 s6, s0, s33
	v_add3_u32 v250, s7, v250, v170
	v_add3_u32 v251, s7, v251, v170
	v_add3_u32 v252, s7, v252, v170
	v_add3_u32 v253, s7, v253, v170
	s_addc_u32 s7, s1, 0
	s_waitcnt vmcnt(7)
	ds_write_b128 v250, v[128:131]
	ds_read_b128 v[246:249], v176 offset:6912
	v_mfma_f32_16x16x32_bf16 v[108:111], v[216:219], v[178:181], v[108:111]
	v_mfma_f32_16x16x32_bf16 v[104:107], v[216:219], v[200:203], v[104:107]
	v_mfma_f32_16x16x32_bf16 v[100:103], v[216:219], v[204:207], v[100:103]
	v_mfma_f32_16x16x32_bf16 v[96:99], v[216:219], v[208:211], v[96:99]
	s_waitcnt vmcnt(6)
	ds_write_b128 v251, v[132:135]
	ds_read_b128 v[212:215], v176 offset:9216
	s_waitcnt lgkmcnt(4)
	v_mfma_f32_16x16x32_bf16 v[92:95], v[242:245], v[178:181], v[92:95]
	v_mfma_f32_16x16x32_bf16 v[88:91], v[242:245], v[200:203], v[88:91]
	v_mfma_f32_16x16x32_bf16 v[84:87], v[242:245], v[204:207], v[84:87]
	v_mfma_f32_16x16x32_bf16 v[80:83], v[242:245], v[208:211], v[80:83]
	ds_read_b128 v[216:219], v176 offset:11520
	s_waitcnt lgkmcnt(3)
	v_mfma_f32_16x16x32_bf16 v[76:79], v[246:249], v[178:181], v[76:79]
	s_waitcnt vmcnt(5)
	ds_write_b128 v252, v[136:139]
	v_mfma_f32_16x16x32_bf16 v[72:75], v[246:249], v[200:203], v[72:75]
	v_mfma_f32_16x16x32_bf16 v[68:71], v[246:249], v[204:207], v[68:71]
	v_mfma_f32_16x16x32_bf16 v[64:67], v[246:249], v[208:211], v[64:67]
	ds_read_b128 v[242:245], v176 offset:13824
	s_waitcnt lgkmcnt(3)
	v_mfma_f32_16x16x32_bf16 v[60:63], v[212:215], v[178:181], v[60:63]
	s_waitcnt vmcnt(4)
	ds_write_b128 v253, v[140:143]
	v_mfma_f32_16x16x32_bf16 v[56:59], v[212:215], v[200:203], v[56:59]
	v_mfma_f32_16x16x32_bf16 v[52:55], v[212:215], v[204:207], v[52:55]
	v_mfma_f32_16x16x32_bf16 v[48:51], v[212:215], v[208:211], v[48:51]
	ds_read_b128 v[246:249], v176 offset:16128
	s_waitcnt lgkmcnt(4)
	v_mfma_f32_16x16x32_bf16 v[44:47], v[216:219], v[178:181], v[44:47]
	s_waitcnt vmcnt(3)
	ds_write_b128 v250, v[144:147] offset:36864
	v_mfma_f32_16x16x32_bf16 v[40:43], v[216:219], v[200:203], v[40:43]
	v_mfma_f32_16x16x32_bf16 v[36:39], v[216:219], v[204:207], v[36:39]
	v_mfma_f32_16x16x32_bf16 v[32:35], v[216:219], v[208:211], v[32:35]
	ds_read_b128 v[212:215], v176 offset:64
	s_waitcnt lgkmcnt(4)
	v_mfma_f32_16x16x32_bf16 v[28:31], v[242:245], v[178:181], v[28:31]
	s_waitcnt vmcnt(2)
	ds_write_b128 v251, v[148:151] offset:36864
	v_mfma_f32_16x16x32_bf16 v[24:27], v[242:245], v[200:203], v[24:27]
	v_mfma_f32_16x16x32_bf16 v[20:23], v[242:245], v[204:207], v[20:23]
	v_mfma_f32_16x16x32_bf16 v[16:19], v[242:245], v[208:211], v[16:19]
	ds_read_b128 v[216:219], v176 offset:2368
	s_waitcnt lgkmcnt(4)
	v_mfma_f32_16x16x32_bf16 v[8:11], v[246:249], v[178:181], v[8:11]
	ds_read_b128 v[178:181], v182 offset:36928
	s_waitcnt vmcnt(1)
	ds_write_b128 v252, v[152:155] offset:36864
	v_mfma_f32_16x16x32_bf16 v[4:7], v[246:249], v[200:203], v[4:7]
	ds_read_b128 v[200:203], v182 offset:39232
	v_mfma_f32_16x16x32_bf16 v[0:3], v[246:249], v[204:207], v[0:3]
	ds_read_b128 v[204:207], v182 offset:41536
	v_mfma_f32_16x16x32_bf16 v[12:15], v[246:249], v[208:211], v[12:15]
	ds_read_b128 v[208:211], v182 offset:43840
	ds_read_b128 v[242:245], v176 offset:4672
	s_waitcnt lgkmcnt(5)
	v_mfma_f32_16x16x32_bf16 v[124:127], v[212:215], v[178:181], v[124:127]
	s_waitcnt lgkmcnt(3)
	v_mfma_f32_16x16x32_bf16 v[120:123], v[212:215], v[200:203], v[120:123]
	s_waitcnt vmcnt(0)
	ds_write_b128 v253, v[156:159] offset:36864
	s_waitcnt lgkmcnt(3)
	v_mfma_f32_16x16x32_bf16 v[116:119], v[212:215], v[204:207], v[116:119]
	s_waitcnt lgkmcnt(2)
	v_mfma_f32_16x16x32_bf16 v[112:115], v[212:215], v[208:211], v[112:115]
	v_lshl_add_u64 v[128:129], s[6:7], 0, v[160:161]
	v_lshl_add_u64 v[132:133], s[6:7], 0, v[162:163]
	v_lshl_add_u64 v[136:137], s[6:7], 0, v[164:165]
	v_lshl_add_u64 v[140:141], s[6:7], 0, v[166:167]
	s_add_u32 s6, s2, s33
	s_addc_u32 s7, s3, 0
	v_lshl_add_u64 v[144:145], s[6:7], 0, v[160:161]
	v_lshl_add_u64 v[148:149], s[6:7], 0, v[162:163]
	v_lshl_add_u64 v[152:153], s[6:7], 0, v[164:165]
	v_lshl_add_u64 v[156:157], s[6:7], 0, v[166:167]
	global_load_dwordx4 v[128:131], v[128:129], off offset:256
	ds_read_b128 v[246:249], v176 offset:6976
	v_mfma_f32_16x16x32_bf16 v[108:111], v[216:219], v[178:181], v[108:111]
	v_mfma_f32_16x16x32_bf16 v[104:107], v[216:219], v[200:203], v[104:107]
	s_nop 0
	global_load_dwordx4 v[132:135], v[132:133], off offset:256
	v_mfma_f32_16x16x32_bf16 v[100:103], v[216:219], v[204:207], v[100:103]
	v_mfma_f32_16x16x32_bf16 v[96:99], v[216:219], v[208:211], v[96:99]
	ds_read_b128 v[212:215], v176 offset:9280
	s_waitcnt lgkmcnt(3)
	v_mfma_f32_16x16x32_bf16 v[92:95], v[242:245], v[178:181], v[92:95]
	s_nop 0
	global_load_dwordx4 v[136:139], v[136:137], off offset:256
	v_mfma_f32_16x16x32_bf16 v[88:91], v[242:245], v[200:203], v[88:91]
	v_mfma_f32_16x16x32_bf16 v[84:87], v[242:245], v[204:207], v[84:87]
	s_nop 0
	global_load_dwordx4 v[140:143], v[140:141], off offset:256
	v_mfma_f32_16x16x32_bf16 v[80:83], v[242:245], v[208:211], v[80:83]
	ds_read_b128 v[216:219], v176 offset:11584
	s_waitcnt lgkmcnt(2)
	v_mfma_f32_16x16x32_bf16 v[76:79], v[246:249], v[178:181], v[76:79]
	v_mfma_f32_16x16x32_bf16 v[72:75], v[246:249], v[200:203], v[72:75]
	s_nop 0
	global_load_dwordx4 v[144:147], v[144:145], off offset:256
	v_mfma_f32_16x16x32_bf16 v[68:71], v[246:249], v[204:207], v[68:71]
	v_mfma_f32_16x16x32_bf16 v[64:67], v[246:249], v[208:211], v[64:67]
	s_nop 0
	global_load_dwordx4 v[148:151], v[148:149], off offset:256
	ds_read_b128 v[242:245], v176 offset:13888
	s_waitcnt lgkmcnt(2)
	v_mfma_f32_16x16x32_bf16 v[60:63], v[212:215], v[178:181], v[60:63]
	v_mfma_f32_16x16x32_bf16 v[56:59], v[212:215], v[200:203], v[56:59]
	v_mfma_f32_16x16x32_bf16 v[52:55], v[212:215], v[204:207], v[52:55]
	s_nop 0
	global_load_dwordx4 v[152:155], v[152:153], off offset:256
	v_mfma_f32_16x16x32_bf16 v[48:51], v[212:215], v[208:211], v[48:51]
	ds_read_b128 v[246:249], v176 offset:16192
	s_waitcnt lgkmcnt(2)
	v_mfma_f32_16x16x32_bf16 v[44:47], v[216:219], v[178:181], v[44:47]
	s_nop 0
	global_load_dwordx4 v[156:159], v[156:157], off offset:256
	v_mfma_f32_16x16x32_bf16 v[40:43], v[216:219], v[200:203], v[40:43]
	v_mfma_f32_16x16x32_bf16 v[36:39], v[216:219], v[204:207], v[36:39]
	v_mfma_f32_16x16x32_bf16 v[32:35], v[216:219], v[208:211], v[32:35]
	s_waitcnt lgkmcnt(0)
	s_barrier
; DI f32x4 mfma16(bf16x8 a, bf16x8 b, f32x4 c) { return __builtin_amdgcn_mfma_f32_16x16x32_bf16(a, b, c, 0, 0, 0); }
; template <int MI, int NJ, bool SWAP, class AP, class BP>
; DI void gemm_main(f32x4 (&acc)[MI][NJ], const AP& ap, int a_kstep, const BP& bp, int b_kstep, int nk, bf16_t* smem) {
;     ...
;   for (int kt = 0; kt < nk; ++kt) {
;     const int buf = kt & 1;
;     sstore(buf ^ 1);
;     gload(kt + 2 < nk ? kt + 2 : nk - 1);
;     __builtin_amdgcn_sched_barrier(0);
;     const bf16_t* As = smem + buf * L::STAGE + (wm * 16 * MI + l15) * LDT + quad * 8;
;     const bf16_t* Bs = smem + buf * L::STAGE + L::A_ELEMS + (wn * 16 * NJ + l15) * LDT + quad * 8;
; #pragma unroll
;     for (int ks = 0; ks < 2; ++ks) {
;       if (MI * NJ >= 32 && ks == 1) asm volatile("" ::: "memory");
;       bf16x8 b[NJ];
; #pragma unroll
;       for (int j = 0; j < NJ; ++j) b[j] = *(const bf16x8*)(Bs + j * 16 * LDT + ks * 32);
; #pragma unroll
;       for (int i = 0; i < MI; ++i) {
;         const bf16x8 a = *(const bf16x8*)(As + i * 16 * LDT + ks * 32);
; #pragma unroll
;         for (int j = 0; j < NJ; ++j) acc[i][j] = SWAP ? mfma16(b[j], a, acc[i][j]) : mfma16(a, b[j], acc[i][j]);
	s_add_i32 s4, s4, 1
	s_cmp_lg_u32 s4, 16
	s_cbranch_scc0 .Lgm1_exit
	s_and_b32 s98, s4, 1
	s_mul_i32 s98, s98, 0x12000
	v_add3_u32 v176, s98, v174, v175
	v_add3_u32 v182, s98, v169, v175
	ds_read_b128 v[212:215], v176
	ds_read_b128 v[216:219], v176 offset:2304
	v_mfma_f32_16x16x32_bf16 v[28:31], v[242:245], v[178:181], v[28:31]
	v_mfma_f32_16x16x32_bf16 v[8:11], v[246:249], v[178:181], v[8:11]
	ds_read_b128 v[178:181], v182 offset:36864
	v_mfma_f32_16x16x32_bf16 v[24:27], v[242:245], v[200:203], v[24:27]
	v_mfma_f32_16x16x32_bf16 v[4:7], v[246:249], v[200:203], v[4:7]
	ds_read_b128 v[200:203], v182 offset:39168
	v_mfma_f32_16x16x32_bf16 v[20:23], v[242:245], v[204:207], v[20:23]
	v_mfma_f32_16x16x32_bf16 v[0:3], v[246:249], v[204:207], v[0:3]
	ds_read_b128 v[204:207], v182 offset:41472
	v_mfma_f32_16x16x32_bf16 v[16:19], v[242:245], v[208:211], v[16:19]
	v_mfma_f32_16x16x32_bf16 v[12:15], v[246:249], v[208:211], v[12:15]
	ds_read_b128 v[208:211], v182 offset:43776
	s_branch .Lgm1_main

; DI f32x4 mfma16(bf16x8 a, bf16x8 b, f32x4 c) { return __builtin_amdgcn_mfma_f32_16x16x32_bf16(a, b, c, 0, 0, 0); }
; template <int MI, int NJ, bool SWAP, class AP, class BP>
; DI void gemm_main(f32x4 (&acc)[MI][NJ], const AP& ap, int a_kstep, const BP& bp, int b_kstep, int nk, bf16_t* smem) {
;     ...
;   auto gload = [&](int kt) {
;     const bf16_t* ab = ap.base + (size_t)kt * a_kstep; const bf16_t* bb = bp.base + (size_t)kt * b_kstep;
; #pragma unroll
;     for (int i = 0; i < CA; ++i) ra[i] = *(const u32x4*)(ab + pa[i]);
; #pragma unroll
;     for (int i = 0; i < CB; ++i) rb[i] = *(const u32x4*)(bb + pb[i]);
;   };
;   auto sstore = [&](int buf) {
;     bf16_t* As = smem + buf * L::STAGE; bf16_t* Bs = As + L::A_ELEMS;
; #pragma unroll
;     for (int i = 0; i < CA; ++i) { const int c = tid + NTHR * i; *(u32x4*)(As + (c >> 3) * LDT + (c & 7) * 8) = oka[i] ? ra[i] : (u32x4){0u, 0u, 0u, 0u}; }
; #pragma unroll
;     for (int i = 0; i < CB; ++i) { const int c = tid + NTHR * i; *(u32x4*)(Bs + (c >> 3) * LDT + (c & 7) * 8) = rb[i]; }
;   };
;   gload(0); sstore(0); gload(nk > 1 ? 1 : 0); __syncthreads();
; #pragma unroll 1
;   for (int kt = 0; kt < nk; ++kt) {
;     const int buf = kt & 1;
;     sstore(buf ^ 1);
;     gload(kt + 2 < nk ? kt + 2 : nk - 1);
;     __builtin_amdgcn_sched_barrier(0);
;     const bf16_t* As = smem + buf * L::STAGE + (wm * 16 * MI + l15) * LDT + quad * 8;
;     const bf16_t* Bs = smem + buf * L::STAGE + L::A_ELEMS + (wn * 16 * NJ + l15) * LDT + quad * 8;
; #pragma unroll
;     for (int ks = 0; ks < 2; ++ks) {
;       if (MI * NJ >= 32 && ks == 1) asm volatile("" ::: "memory");
;       bf16x8 b[NJ];
; #pragma unroll
;       for (int j = 0; j < NJ; ++j) b[j] = *(const bf16x8*)(Bs + j * 16 * LDT + ks * 32);
; #pragma unroll
;       for (int i = 0; i < MI; ++i) {
;         const bf16x8 a = *(const bf16x8*)(As + i * 16 * LDT + ks * 32);
; #pragma unroll
;         for (int j = 0; j < NJ; ++j) acc[i][j] = SWAP ? mfma16(b[j], a, acc[i][j]) : mfma16(a, b[j], acc[i][j]);
;       }
;     }
;     __syncthreads();
;   }
.Lgm2_main:
	ds_read_b128 v[242:245], v182 offset:4608
	s_waitcnt lgkmcnt(4)
	v_mfma_f32_16x16x32_bf16 v[156:159], v[178:181], v[198:201], v[156:159]
	s_waitcnt lgkmcnt(3)
	v_mfma_f32_16x16x32_bf16 v[152:155], v[186:189], v[198:201], v[152:155]
	s_waitcnt lgkmcnt(2)
	v_mfma_f32_16x16x32_bf16 v[148:151], v[190:193], v[198:201], v[148:151]
	s_waitcnt lgkmcnt(1)
	v_mfma_f32_16x16x32_bf16 v[144:147], v[194:197], v[198:201], v[144:147]
	s_and_b32 s33, s16, 1
	s_min_u32 s52, s16, 3
	s_xor_b32 s53, s33, 1
	s_lshl_b32 s54, s52, 7
	s_mul_i32 s53, s53, 0x12000
	s_add_u32 s52, s0, s54
	v_add3_u32 v250, s53, v173, v171
	v_add3_u32 v251, s53, v174, v171
	v_add3_u32 v252, s53, v175, v171
	v_add3_u32 v253, s53, v176, v171
	s_addc_u32 s53, s1, 0
	s_waitcnt vmcnt(7)
	ds_write_b128 v250, v[112:115]
	ds_read_b128 v[246:249], v182 offset:6912
	v_mfma_f32_16x16x32_bf16 v[108:111], v[178:181], v[202:205], v[108:111]
	v_mfma_f32_16x16x32_bf16 v[104:107], v[186:189], v[202:205], v[104:107]
	v_mfma_f32_16x16x32_bf16 v[100:103], v[190:193], v[202:205], v[100:103]
	v_mfma_f32_16x16x32_bf16 v[96:99], v[194:197], v[202:205], v[96:99]
	s_waitcnt vmcnt(5)
	ds_write_b128 v251, v[116:119]
	ds_read_b128 v[198:201], v182 offset:9216
	s_waitcnt lgkmcnt(4)
	v_mfma_f32_16x16x32_bf16 v[92:95], v[178:181], v[242:245], v[92:95]
	v_mfma_f32_16x16x32_bf16 v[88:91], v[186:189], v[242:245], v[88:91]
	v_mfma_f32_16x16x32_bf16 v[84:87], v[190:193], v[242:245], v[84:87]
	v_mfma_f32_16x16x32_bf16 v[80:83], v[194:197], v[242:245], v[80:83]
	ds_read_b128 v[202:205], v182 offset:11520
	s_waitcnt lgkmcnt(3)
	v_mfma_f32_16x16x32_bf16 v[76:79], v[178:181], v[246:249], v[76:79]
	s_waitcnt vmcnt(4)
	ds_write_b128 v252, v[120:123]
	v_mfma_f32_16x16x32_bf16 v[72:75], v[186:189], v[246:249], v[72:75]
	v_mfma_f32_16x16x32_bf16 v[68:71], v[190:193], v[246:249], v[68:71]
	v_mfma_f32_16x16x32_bf16 v[64:67], v[194:197], v[246:249], v[64:67]
	ds_read_b128 v[242:245], v182 offset:13824
	s_waitcnt lgkmcnt(3)
	v_mfma_f32_16x16x32_bf16 v[60:63], v[178:181], v[198:201], v[60:63]
	s_waitcnt vmcnt(3)
	ds_write_b128 v253, v[124:127]
	v_mfma_f32_16x16x32_bf16 v[56:59], v[186:189], v[198:201], v[56:59]
	v_mfma_f32_16x16x32_bf16 v[52:55], v[190:193], v[198:201], v[52:55]
	v_mfma_f32_16x16x32_bf16 v[48:51], v[194:197], v[198:201], v[48:51]
	ds_read_b128 v[246:249], v182 offset:16128
	s_waitcnt lgkmcnt(4)
	v_mfma_f32_16x16x32_bf16 v[44:47], v[178:181], v[202:205], v[44:47]
	ds_write_b128 v250, v[128:131] offset:36864
	v_mfma_f32_16x16x32_bf16 v[40:43], v[186:189], v[202:205], v[40:43]
	v_mfma_f32_16x16x32_bf16 v[36:39], v[190:193], v[202:205], v[36:39]
	v_mfma_f32_16x16x32_bf16 v[32:35], v[194:197], v[202:205], v[32:35]
	ds_read_b128 v[198:201], v182 offset:64
	s_waitcnt lgkmcnt(4)
	v_mfma_f32_16x16x32_bf16 v[28:31], v[178:181], v[242:245], v[28:31]
	s_waitcnt vmcnt(2)
	ds_write_b128 v251, v[132:135] offset:36864
	v_mfma_f32_16x16x32_bf16 v[24:27], v[186:189], v[242:245], v[24:27]
	v_mfma_f32_16x16x32_bf16 v[20:23], v[190:193], v[242:245], v[20:23]
	v_mfma_f32_16x16x32_bf16 v[16:19], v[194:197], v[242:245], v[16:19]
	ds_read_b128 v[202:205], v182 offset:2368
	s_waitcnt lgkmcnt(4)
	v_mfma_f32_16x16x32_bf16 v[8:11], v[178:181], v[246:249], v[8:11]
	ds_read_b128 v[178:181], v183 offset:36928
	s_waitcnt vmcnt(1)
	ds_write_b128 v252, v[136:139] offset:36864
	v_mfma_f32_16x16x32_bf16 v[4:7], v[186:189], v[246:249], v[4:7]
	ds_read_b128 v[186:189], v183 offset:39232
	v_mfma_f32_16x16x32_bf16 v[0:3], v[190:193], v[246:249], v[0:3]
	ds_read_b128 v[190:193], v183 offset:41536
	v_mfma_f32_16x16x32_bf16 v[12:15], v[194:197], v[246:249], v[12:15]
	ds_read_b128 v[194:197], v183 offset:43840
	ds_read_b128 v[242:245], v182 offset:4672
	s_waitcnt lgkmcnt(5)
	v_mfma_f32_16x16x32_bf16 v[156:159], v[178:181], v[198:201], v[156:159]
	s_waitcnt lgkmcnt(3)
	v_mfma_f32_16x16x32_bf16 v[152:155], v[186:189], v[198:201], v[152:155]
	s_waitcnt vmcnt(0)
	ds_write_b128 v253, v[140:143] offset:36864
	s_waitcnt lgkmcnt(3)
	v_mfma_f32_16x16x32_bf16 v[148:151], v[190:193], v[198:201], v[148:151]
	s_waitcnt lgkmcnt(2)
	v_mfma_f32_16x16x32_bf16 v[144:147], v[194:197], v[198:201], v[144:147]
	v_lshl_add_u64 v[112:113], s[52:53], 0, v[162:163]
	v_lshl_add_u64 v[116:117], s[52:53], 0, v[164:165]
	v_lshl_add_u64 v[120:121], s[52:53], 0, v[166:167]
	v_lshl_add_u64 v[124:125], s[52:53], 0, v[168:169]
	s_add_u32 s52, s2, s54
	s_addc_u32 s53, s3, 0
	v_lshl_add_u64 v[128:129], s[52:53], 0, v[162:163]
	v_lshl_add_u64 v[132:133], s[52:53], 0, v[164:165]
	v_lshl_add_u64 v[136:137], s[52:53], 0, v[166:167]
	v_lshl_add_u64 v[140:141], s[52:53], 0, v[168:169]
	global_load_dwordx4 v[112:115], v[112:113], off offset:256
	ds_read_b128 v[246:249], v182 offset:6976
	v_mfma_f32_16x16x32_bf16 v[108:111], v[178:181], v[202:205], v[108:111]
	v_mfma_f32_16x16x32_bf16 v[104:107], v[186:189], v[202:205], v[104:107]
	s_nop 0
	global_load_dwordx4 v[116:119], v[116:117], off offset:256
	v_mfma_f32_16x16x32_bf16 v[100:103], v[190:193], v[202:205], v[100:103]
	v_mfma_f32_16x16x32_bf16 v[96:99], v[194:197], v[202:205], v[96:99]
	ds_read_b128 v[198:201], v182 offset:9280
	s_waitcnt lgkmcnt(3)
	v_mfma_f32_16x16x32_bf16 v[92:95], v[178:181], v[242:245], v[92:95]
	s_nop 0
	global_load_dwordx4 v[120:123], v[120:121], off offset:256
	v_mfma_f32_16x16x32_bf16 v[88:91], v[186:189], v[242:245], v[88:91]
	v_mfma_f32_16x16x32_bf16 v[84:87], v[190:193], v[242:245], v[84:87]
	s_nop 0
	global_load_dwordx4 v[124:127], v[124:125], off offset:256
	v_mfma_f32_16x16x32_bf16 v[80:83], v[194:197], v[242:245], v[80:83]
	ds_read_b128 v[202:205], v182 offset:11584
	s_waitcnt lgkmcnt(2)
	v_mfma_f32_16x16x32_bf16 v[76:79], v[178:181], v[246:249], v[76:79]
	v_mfma_f32_16x16x32_bf16 v[72:75], v[186:189], v[246:249], v[72:75]
	s_nop 0
	global_load_dwordx4 v[128:131], v[128:129], off offset:256
	v_mfma_f32_16x16x32_bf16 v[68:71], v[190:193], v[246:249], v[68:71]
	v_mfma_f32_16x16x32_bf16 v[64:67], v[194:197], v[246:249], v[64:67]
	s_nop 0
	global_load_dwordx4 v[132:135], v[132:133], off offset:256
	ds_read_b128 v[242:245], v182 offset:13888
	s_waitcnt lgkmcnt(2)
	v_mfma_f32_16x16x32_bf16 v[60:63], v[178:181], v[198:201], v[60:63]
	v_mfma_f32_16x16x32_bf16 v[56:59], v[186:189], v[198:201], v[56:59]
	v_mfma_f32_16x16x32_bf16 v[52:55], v[190:193], v[198:201], v[52:55]
	s_nop 0
	global_load_dwordx4 v[136:139], v[136:137], off offset:256
	v_mfma_f32_16x16x32_bf16 v[48:51], v[194:197], v[198:201], v[48:51]
	ds_read_b128 v[246:249], v182 offset:16192
	s_waitcnt lgkmcnt(2)
	v_mfma_f32_16x16x32_bf16 v[44:47], v[178:181], v[202:205], v[44:47]
	s_nop 0
	global_load_dwordx4 v[140:143], v[140:141], off offset:256
	v_mfma_f32_16x16x32_bf16 v[40:43], v[186:189], v[202:205], v[40:43]
	v_mfma_f32_16x16x32_bf16 v[36:39], v[190:193], v[202:205], v[36:39]
	v_mfma_f32_16x16x32_bf16 v[32:35], v[194:197], v[202:205], v[32:35]
	s_waitcnt lgkmcnt(0)
	s_barrier
; DI f32x4 mfma16(bf16x8 a, bf16x8 b, f32x4 c) { return __builtin_amdgcn_mfma_f32_16x16x32_bf16(a, b, c, 0, 0, 0); }
; template <int MI, int NJ, bool SWAP, class AP, class BP>
; DI void gemm_main(f32x4 (&acc)[MI][NJ], const AP& ap, int a_kstep, const BP& bp, int b_kstep, int nk, bf16_t* smem) {
;     ...
;   for (int kt = 0; kt < nk; ++kt) {
;     const int buf = kt & 1;
;     sstore(buf ^ 1);
;     gload(kt + 2 < nk ? kt + 2 : nk - 1);
;     __builtin_amdgcn_sched_barrier(0);
;     const bf16_t* As = smem + buf * L::STAGE + (wm * 16 * MI + l15) * LDT + quad * 8;
;     const bf16_t* Bs = smem + buf * L::STAGE + L::A_ELEMS + (wn * 16 * NJ + l15) * LDT + quad * 8;
; #pragma unroll
;     for (int ks = 0; ks < 2; ++ks) {
;       if (MI * NJ >= 32 && ks == 1) asm volatile("" ::: "memory");
;       bf16x8 b[NJ];
; #pragma unroll
;       for (int j = 0; j < NJ; ++j) b[j] = *(const bf16x8*)(Bs + j * 16 * LDT + ks * 32);
; #pragma unroll
;       for (int i = 0; i < MI; ++i) {
;         const bf16x8 a = *(const bf16x8*)(As + i * 16 * LDT + ks * 32);
; #pragma unroll
;         for (int j = 0; j < NJ; ++j) acc[i][j] = SWAP ? mfma16(b[j], a, acc[i][j]) : mfma16(a, b[j], acc[i][j]);
	s_add_i32 s16, s16, 1
	s_cmp_lg_u32 s16, 6
	s_cbranch_scc0 .Lgm2_exit
	s_and_b32 s98, s16, 1
	s_mul_i32 s98, s98, 0x12000
	v_add3_u32 v183, s98, v160, v177
	v_add3_u32 v182, s98, v172, v177
	ds_read_b128 v[198:201], v182
	ds_read_b128 v[202:205], v182 offset:2304
	v_mfma_f32_16x16x32_bf16 v[28:31], v[178:181], v[242:245], v[28:31]
	v_mfma_f32_16x16x32_bf16 v[8:11], v[178:181], v[246:249], v[8:11]
	ds_read_b128 v[178:181], v183 offset:36864
	v_mfma_f32_16x16x32_bf16 v[24:27], v[186:189], v[242:245], v[24:27]
	v_mfma_f32_16x16x32_bf16 v[4:7], v[186:189], v[246:249], v[4:7]
	ds_read_b128 v[186:189], v183 offset:39168
	v_mfma_f32_16x16x32_bf16 v[20:23], v[190:193], v[242:245], v[20:23]
	v_mfma_f32_16x16x32_bf16 v[0:3], v[190:193], v[246:249], v[0:3]
	ds_read_b128 v[190:193], v183 offset:41472
	v_mfma_f32_16x16x32_bf16 v[16:19], v[194:197], v[242:245], v[16:19]
	v_mfma_f32_16x16x32_bf16 v[12:15], v[194:197], v[246:249], v[12:15]
	ds_read_b128 v[194:197], v183 offset:43776
	s_branch .Lgm2_main

; DI f32x4 mfma16(bf16x8 a, bf16x8 b, f32x4 c) { return __builtin_amdgcn_mfma_f32_16x16x32_bf16(a, b, c, 0, 0, 0); }
; template <int MI, int NJ, bool SWAP, class AP, class BP>
; DI void gemm_main(f32x4 (&acc)[MI][NJ], const AP& ap, int a_kstep, const BP& bp, int b_kstep, int nk, bf16_t* smem) {
;     ...
;   auto gload = [&](int kt) {
;     const bf16_t* ab = ap.base + (size_t)kt * a_kstep; const bf16_t* bb = bp.base + (size_t)kt * b_kstep;
; #pragma unroll
;     for (int i = 0; i < CA; ++i) ra[i] = *(const u32x4*)(ab + pa[i]);
; #pragma unroll
;     for (int i = 0; i < CB; ++i) rb[i] = *(const u32x4*)(bb + pb[i]);
;   };
;   auto sstore = [&](int buf) {
;     bf16_t* As = smem + buf * L::STAGE; bf16_t* Bs = As + L::A_ELEMS;
; #pragma unroll
;     for (int i = 0; i < CA; ++i) { const int c = tid + NTHR * i; *(u32x4*)(As + (c >> 3) * LDT + (c & 7) * 8) = oka[i] ? ra[i] : (u32x4){0u, 0u, 0u, 0u}; }
; #pragma unroll
;     for (int i = 0; i < CB; ++i) { const int c = tid + NTHR * i; *(u32x4*)(Bs + (c >> 3) * LDT + (c & 7) * 8) = rb[i]; }
;   };
;   gload(0); sstore(0); gload(nk > 1 ? 1 : 0); __syncthreads();
; #pragma unroll 1
;   for (int kt = 0; kt < nk; ++kt) {
;     const int buf = kt & 1;
;     sstore(buf ^ 1);
;     gload(kt + 2 < nk ? kt + 2 : nk - 1);
;     __builtin_amdgcn_sched_barrier(0);
;     const bf16_t* As = smem + buf * L::STAGE + (wm * 16 * MI + l15) * LDT + quad * 8;
;     const bf16_t* Bs = smem + buf * L::STAGE + L::A_ELEMS + (wn * 16 * NJ + l15) * LDT + quad * 8;
; #pragma unroll
;     for (int ks = 0; ks < 2; ++ks) {
;       if (MI * NJ >= 32 && ks == 1) asm volatile("" ::: "memory");
;       bf16x8 b[NJ];
; #pragma unroll
;       for (int j = 0; j < NJ; ++j) b[j] = *(const bf16x8*)(Bs + j * 16 * LDT + ks * 32);
; #pragma unroll
;       for (int i = 0; i < MI; ++i) {
;         const bf16x8 a = *(const bf16x8*)(As + i * 16 * LDT + ks * 32);
; #pragma unroll
;         for (int j = 0; j < NJ; ++j) acc[i][j] = SWAP ? mfma16(b[j], a, acc[i][j]) : mfma16(a, b[j], acc[i][j]);
;       }
;     }
;     __syncthreads();
;   }
.Lgm3_main:
	ds_read_b128 v[242:245], v182 offset:4608
	s_waitcnt lgkmcnt(4)
	v_mfma_f32_16x16x32_bf16 v[156:159], v[178:181], v[198:201], v[156:159]
	s_waitcnt lgkmcnt(3)
	v_mfma_f32_16x16x32_bf16 v[152:155], v[186:189], v[198:201], v[152:155]
	s_waitcnt lgkmcnt(2)
	v_mfma_f32_16x16x32_bf16 v[148:151], v[190:193], v[198:201], v[148:151]
	s_waitcnt lgkmcnt(1)
	v_mfma_f32_16x16x32_bf16 v[144:147], v[194:197], v[198:201], v[144:147]
	s_and_b32 s54, s33, 1
	s_xor_b32 s52, s54, 1
	s_cmp_eq_u32 s33, 0
	v_lshlrev_b32_e32 v250, 1, v160
	v_lshlrev_b32_e32 v251, 1, v173
	v_lshlrev_b32_e32 v252, 1, v174
	v_lshlrev_b32_e32 v253, 1, v175
	s_mul_i32 s52, s52, 0x12000
	s_cselect_b32 s55, s48, 0x180
	v_add3_u32 v250, s52, v250, v172
	v_add3_u32 v251, s52, v251, v172
	v_add3_u32 v252, s52, v252, v172
	v_add3_u32 v253, s52, v253, v172
	s_add_u32 s52, s0, s55
	s_addc_u32 s53, s1, 0
	s_waitcnt vmcnt(7)
	ds_write_b128 v250, v[112:115]
	ds_read_b128 v[246:249], v182 offset:6912
	v_mfma_f32_16x16x32_bf16 v[108:111], v[178:181], v[202:205], v[108:111]
	v_mfma_f32_16x16x32_bf16 v[104:107], v[186:189], v[202:205], v[104:107]
	v_mfma_f32_16x16x32_bf16 v[100:103], v[190:193], v[202:205], v[100:103]
	v_mfma_f32_16x16x32_bf16 v[96:99], v[194:197], v[202:205], v[96:99]
	s_waitcnt vmcnt(6)
	ds_write_b128 v251, v[116:119]
	ds_read_b128 v[198:201], v182 offset:9216
	s_waitcnt lgkmcnt(4)
	v_mfma_f32_16x16x32_bf16 v[92:95], v[178:181], v[242:245], v[92:95]
	v_mfma_f32_16x16x32_bf16 v[88:91], v[186:189], v[242:245], v[88:91]
	v_mfma_f32_16x16x32_bf16 v[84:87], v[190:193], v[242:245], v[84:87]
	v_mfma_f32_16x16x32_bf16 v[80:83], v[194:197], v[242:245], v[80:83]
	ds_read_b128 v[202:205], v182 offset:11520
	s_waitcnt lgkmcnt(3)
	v_mfma_f32_16x16x32_bf16 v[76:79], v[178:181], v[246:249], v[76:79]
	s_waitcnt vmcnt(5)
	ds_write_b128 v252, v[120:123]
	v_mfma_f32_16x16x32_bf16 v[72:75], v[186:189], v[246:249], v[72:75]
	v_mfma_f32_16x16x32_bf16 v[68:71], v[190:193], v[246:249], v[68:71]
	v_mfma_f32_16x16x32_bf16 v[64:67], v[194:197], v[246:249], v[64:67]
	ds_read_b128 v[242:245], v182 offset:13824
	s_waitcnt lgkmcnt(3)
	v_mfma_f32_16x16x32_bf16 v[60:63], v[178:181], v[198:201], v[60:63]
	s_waitcnt vmcnt(4)
	ds_write_b128 v253, v[124:127]
	v_mfma_f32_16x16x32_bf16 v[56:59], v[186:189], v[198:201], v[56:59]
	v_mfma_f32_16x16x32_bf16 v[52:55], v[190:193], v[198:201], v[52:55]
	v_mfma_f32_16x16x32_bf16 v[48:51], v[194:197], v[198:201], v[48:51]
	ds_read_b128 v[246:249], v182 offset:16128
	s_waitcnt lgkmcnt(4)
	v_mfma_f32_16x16x32_bf16 v[44:47], v[178:181], v[202:205], v[44:47]
	s_waitcnt vmcnt(3)
	ds_write_b128 v250, v[128:131] offset:36864
	v_mfma_f32_16x16x32_bf16 v[40:43], v[186:189], v[202:205], v[40:43]
	v_mfma_f32_16x16x32_bf16 v[36:39], v[190:193], v[202:205], v[36:39]
	v_mfma_f32_16x16x32_bf16 v[32:35], v[194:197], v[202:205], v[32:35]
	ds_read_b128 v[198:201], v182 offset:64
	s_waitcnt lgkmcnt(4)
	v_mfma_f32_16x16x32_bf16 v[28:31], v[178:181], v[242:245], v[28:31]
	s_waitcnt vmcnt(2)
	ds_write_b128 v251, v[132:135] offset:36864
	v_mfma_f32_16x16x32_bf16 v[24:27], v[186:189], v[242:245], v[24:27]
	v_mfma_f32_16x16x32_bf16 v[20:23], v[190:193], v[242:245], v[20:23]
	v_mfma_f32_16x16x32_bf16 v[16:19], v[194:197], v[242:245], v[16:19]
	ds_read_b128 v[202:205], v182 offset:2368
	s_waitcnt lgkmcnt(4)
	v_mfma_f32_16x16x32_bf16 v[8:11], v[178:181], v[246:249], v[8:11]
	ds_read_b128 v[178:181], v183 offset:36928
	s_waitcnt vmcnt(1)
	ds_write_b128 v252, v[136:139] offset:36864
	v_mfma_f32_16x16x32_bf16 v[4:7], v[186:189], v[246:249], v[4:7]
	ds_read_b128 v[186:189], v183 offset:39232
	v_mfma_f32_16x16x32_bf16 v[0:3], v[190:193], v[246:249], v[0:3]
	ds_read_b128 v[190:193], v183 offset:41536
	v_mfma_f32_16x16x32_bf16 v[12:15], v[194:197], v[246:249], v[12:15]
	ds_read_b128 v[194:197], v183 offset:43840
	ds_read_b128 v[242:245], v182 offset:4672
	s_waitcnt lgkmcnt(5)
	v_mfma_f32_16x16x32_bf16 v[156:159], v[178:181], v[198:201], v[156:159]
	s_waitcnt lgkmcnt(3)
	v_mfma_f32_16x16x32_bf16 v[152:155], v[186:189], v[198:201], v[152:155]
	s_waitcnt vmcnt(0)
	ds_write_b128 v253, v[140:143] offset:36864
	s_waitcnt lgkmcnt(3)
	v_mfma_f32_16x16x32_bf16 v[148:151], v[190:193], v[198:201], v[148:151]
	s_waitcnt lgkmcnt(2)
	v_mfma_f32_16x16x32_bf16 v[144:147], v[194:197], v[198:201], v[144:147]
	v_lshl_add_u64 v[112:113], s[52:53], 0, v[162:163]
	v_lshl_add_u64 v[116:117], s[52:53], 0, v[164:165]
	v_lshl_add_u64 v[120:121], s[52:53], 0, v[166:167]
	v_lshl_add_u64 v[124:125], s[52:53], 0, v[168:169]
	s_add_u32 s52, s2, s55
	s_addc_u32 s53, s3, 0
	v_lshl_add_u64 v[128:129], s[52:53], 0, v[162:163]
	v_lshl_add_u64 v[132:133], s[52:53], 0, v[164:165]
	v_lshl_add_u64 v[136:137], s[52:53], 0, v[166:167]
	v_lshl_add_u64 v[140:141], s[52:53], 0, v[168:169]
	global_load_dwordx4 v[112:115], v[112:113], off
	ds_read_b128 v[246:249], v182 offset:6976
	v_mfma_f32_16x16x32_bf16 v[108:111], v[178:181], v[202:205], v[108:111]
	v_mfma_f32_16x16x32_bf16 v[104:107], v[186:189], v[202:205], v[104:107]
	s_nop 0
	global_load_dwordx4 v[116:119], v[116:117], off
	v_mfma_f32_16x16x32_bf16 v[100:103], v[190:193], v[202:205], v[100:103]
	v_mfma_f32_16x16x32_bf16 v[96:99], v[194:197], v[202:205], v[96:99]
	ds_read_b128 v[198:201], v182 offset:9280
	s_waitcnt lgkmcnt(3)
	v_mfma_f32_16x16x32_bf16 v[92:95], v[178:181], v[242:245], v[92:95]
	s_nop 0
	global_load_dwordx4 v[120:123], v[120:121], off
	v_mfma_f32_16x16x32_bf16 v[88:91], v[186:189], v[242:245], v[88:91]
	v_mfma_f32_16x16x32_bf16 v[84:87], v[190:193], v[242:245], v[84:87]
	s_nop 0
	global_load_dwordx4 v[124:127], v[124:125], off
	v_mfma_f32_16x16x32_bf16 v[80:83], v[194:197], v[242:245], v[80:83]
	ds_read_b128 v[202:205], v182 offset:11584
	s_waitcnt lgkmcnt(2)
	v_mfma_f32_16x16x32_bf16 v[76:79], v[178:181], v[246:249], v[76:79]
	v_mfma_f32_16x16x32_bf16 v[72:75], v[186:189], v[246:249], v[72:75]
	s_nop 0
	global_load_dwordx4 v[128:131], v[128:129], off
	v_mfma_f32_16x16x32_bf16 v[68:71], v[190:193], v[246:249], v[68:71]
	v_mfma_f32_16x16x32_bf16 v[64:67], v[194:197], v[246:249], v[64:67]
	s_nop 0
	global_load_dwordx4 v[132:135], v[132:133], off
	ds_read_b128 v[242:245], v182 offset:13888
	s_waitcnt lgkmcnt(2)
	v_mfma_f32_16x16x32_bf16 v[60:63], v[178:181], v[198:201], v[60:63]
	v_mfma_f32_16x16x32_bf16 v[56:59], v[186:189], v[198:201], v[56:59]
	v_mfma_f32_16x16x32_bf16 v[52:55], v[190:193], v[198:201], v[52:55]
	s_nop 0
	global_load_dwordx4 v[136:139], v[136:137], off
	v_mfma_f32_16x16x32_bf16 v[48:51], v[194:197], v[198:201], v[48:51]
	ds_read_b128 v[246:249], v182 offset:16192
	s_waitcnt lgkmcnt(2)
	v_mfma_f32_16x16x32_bf16 v[44:47], v[178:181], v[202:205], v[44:47]
	s_nop 0
	global_load_dwordx4 v[140:143], v[140:141], off
	v_mfma_f32_16x16x32_bf16 v[40:43], v[186:189], v[202:205], v[40:43]
	v_mfma_f32_16x16x32_bf16 v[36:39], v[190:193], v[202:205], v[36:39]
	v_mfma_f32_16x16x32_bf16 v[32:35], v[194:197], v[202:205], v[32:35]
	s_waitcnt lgkmcnt(0)
	s_barrier
; DI f32x4 mfma16(bf16x8 a, bf16x8 b, f32x4 c) { return __builtin_amdgcn_mfma_f32_16x16x32_bf16(a, b, c, 0, 0, 0); }
; template <int MI, int NJ, bool SWAP, class AP, class BP>
; DI void gemm_main(f32x4 (&acc)[MI][NJ], const AP& ap, int a_kstep, const BP& bp, int b_kstep, int nk, bf16_t* smem) {
;     ...
;   for (int kt = 0; kt < nk; ++kt) {
;     const int buf = kt & 1;
;     sstore(buf ^ 1);
;     gload(kt + 2 < nk ? kt + 2 : nk - 1);
;     __builtin_amdgcn_sched_barrier(0);
;     const bf16_t* As = smem + buf * L::STAGE + (wm * 16 * MI + l15) * LDT + quad * 8;
;     const bf16_t* Bs = smem + buf * L::STAGE + L::A_ELEMS + (wn * 16 * NJ + l15) * LDT + quad * 8;
; #pragma unroll
;     for (int ks = 0; ks < 2; ++ks) {
;       if (MI * NJ >= 32 && ks == 1) asm volatile("" ::: "memory");
;       bf16x8 b[NJ];
; #pragma unroll
;       for (int j = 0; j < NJ; ++j) b[j] = *(const bf16x8*)(Bs + j * 16 * LDT + ks * 32);
; #pragma unroll
;       for (int i = 0; i < MI; ++i) {
;         const bf16x8 a = *(const bf16x8*)(As + i * 16 * LDT + ks * 32);
; #pragma unroll
;         for (int j = 0; j < NJ; ++j) acc[i][j] = SWAP ? mfma16(b[j], a, acc[i][j]) : mfma16(a, b[j], acc[i][j]);
	s_add_i32 s33, s33, 1
	s_cmp_lg_u32 s33, 4
	s_cbranch_scc0 .Lgm3_exit
	s_and_b32 s98, s33, 1
	s_mul_i32 s98, s98, 0x12000
	v_add3_u32 v183, s98, v171, v177
	v_add3_u32 v182, s98, v176, v177
	ds_read_b128 v[198:201], v182
	ds_read_b128 v[202:205], v182 offset:2304
	v_mfma_f32_16x16x32_bf16 v[28:31], v[178:181], v[242:245], v[28:31]
	v_mfma_f32_16x16x32_bf16 v[8:11], v[178:181], v[246:249], v[8:11]
	ds_read_b128 v[178:181], v183 offset:36864
	v_mfma_f32_16x16x32_bf16 v[24:27], v[186:189], v[242:245], v[24:27]
	v_mfma_f32_16x16x32_bf16 v[4:7], v[186:189], v[246:249], v[4:7]
	ds_read_b128 v[186:189], v183 offset:39168
	v_mfma_f32_16x16x32_bf16 v[20:23], v[190:193], v[242:245], v[20:23]
	v_mfma_f32_16x16x32_bf16 v[0:3], v[190:193], v[246:249], v[0:3]
	ds_read_b128 v[190:193], v183 offset:41472
	v_mfma_f32_16x16x32_bf16 v[16:19], v[194:197], v[242:245], v[16:19]
	v_mfma_f32_16x16x32_bf16 v[12:15], v[194:197], v[246:249], v[12:15]
	ds_read_b128 v[194:197], v183 offset:43776
	s_branch .Lgm3_main

; DI f32x4 mfma16(bf16x8 a, bf16x8 b, f32x4 c) { return __builtin_amdgcn_mfma_f32_16x16x32_bf16(a, b, c, 0, 0, 0); }
; template <int MI, int NJ, bool SWAP, class AP, class BP>
; DI void gemm_main(f32x4 (&acc)[MI][NJ], const AP& ap, int a_kstep, const BP& bp, int b_kstep, int nk, bf16_t* smem) {
;     ...
;   auto gload = [&](int kt) {
;     const bf16_t* ab = ap.base + (size_t)kt * a_kstep; const bf16_t* bb = bp.base + (size_t)kt * b_kstep;
; #pragma unroll
;     for (int i = 0; i < CA; ++i) ra[i] = *(const u32x4*)(ab + pa[i]);
; #pragma unroll
;     for (int i = 0; i < CB; ++i) rb[i] = *(const u32x4*)(bb + pb[i]);
;   };
;   auto sstore = [&](int buf) {
;     bf16_t* As = smem + buf * L::STAGE; bf16_t* Bs = As + L::A_ELEMS;
; #pragma unroll
;     for (int i = 0; i < CA; ++i) { const int c = tid + NTHR * i; *(u32x4*)(As + (c >> 3) * LDT + (c & 7) * 8) = oka[i] ? ra[i] : (u32x4){0u, 0u, 0u, 0u}; }
; #pragma unroll
;     for (int i = 0; i < CB; ++i) { const int c = tid + NTHR * i; *(u32x4*)(Bs + (c >> 3) * LDT + (c & 7) * 8) = rb[i]; }
;   };
;   gload(0); sstore(0); gload(nk > 1 ? 1 : 0); __syncthreads();
; #pragma unroll 1
;   for (int kt = 0; kt < nk; ++kt) {
;     const int buf = kt & 1;
;     sstore(buf ^ 1);
;     gload(kt + 2 < nk ? kt + 2 : nk - 1);
;     __builtin_amdgcn_sched_barrier(0);
;     const bf16_t* As = smem + buf * L::STAGE + (wm * 16 * MI + l15) * LDT + quad * 8;
;     const bf16_t* Bs = smem + buf * L::STAGE + L::A_ELEMS + (wn * 16 * NJ + l15) * LDT + quad * 8;
; #pragma unroll
;     for (int ks = 0; ks < 2; ++ks) {
;       if (MI * NJ >= 32 && ks == 1) asm volatile("" ::: "memory");
;       bf16x8 b[NJ];
; #pragma unroll
;       for (int j = 0; j < NJ; ++j) b[j] = *(const bf16x8*)(Bs + j * 16 * LDT + ks * 32);
; #pragma unroll
;       for (int i = 0; i < MI; ++i) {
;         const bf16x8 a = *(const bf16x8*)(As + i * 16 * LDT + ks * 32);
; #pragma unroll
;         for (int j = 0; j < NJ; ++j) acc[i][j] = SWAP ? mfma16(b[j], a, acc[i][j]) : mfma16(a, b[j], acc[i][j]);
;       }
;     }
;     __syncthreads();
;   }
.Lgm4_main:
	ds_read_b128 v[242:245], v182 offset:4608
	s_waitcnt lgkmcnt(4)
	v_mfma_f32_16x16x32_bf16 v[140:143], v[198:201], v[178:181], v[140:143]
	s_waitcnt lgkmcnt(3)
	v_mfma_f32_16x16x32_bf16 v[120:123], v[198:201], v[186:189], v[120:123]
	s_waitcnt lgkmcnt(2)
	v_mfma_f32_16x16x32_bf16 v[116:119], v[198:201], v[190:193], v[116:119]
	s_waitcnt lgkmcnt(1)
	v_mfma_f32_16x16x32_bf16 v[112:115], v[198:201], v[194:197], v[112:115]
	s_and_b32 s16, s5, 1
	s_xor_b32 s33, s16, 1
	v_lshlrev_b32_e32 v250, 1, v160
	v_lshlrev_b32_e32 v251, 1, v173
	v_lshlrev_b32_e32 v252, 1, v174
	v_lshlrev_b32_e32 v253, 1, v175
	s_mul_i32 s33, s33, 0x12000
	s_cmp_eq_u32 s5, 0
	v_add3_u32 v250, s33, v250, v172
	v_add3_u32 v251, s33, v251, v172
	v_add3_u32 v252, s33, v252, v172
	v_add3_u32 v253, s33, v253, v172
	s_cselect_b32 s33, s48, 0x180
	s_add_u32 s52, s0, s33
	s_addc_u32 s53, s1, 0
	s_waitcnt vmcnt(7)
	ds_write_b128 v250, v[124:127]
	ds_read_b128 v[246:249], v182 offset:6912
	v_mfma_f32_16x16x32_bf16 v[108:111], v[202:205], v[178:181], v[108:111]
	v_mfma_f32_16x16x32_bf16 v[104:107], v[202:205], v[186:189], v[104:107]
	v_mfma_f32_16x16x32_bf16 v[100:103], v[202:205], v[190:193], v[100:103]
	v_mfma_f32_16x16x32_bf16 v[96:99], v[202:205], v[194:197], v[96:99]
	s_waitcnt vmcnt(6)
	ds_write_b128 v251, v[128:131]
	ds_read_b128 v[198:201], v182 offset:9216
	s_waitcnt lgkmcnt(4)
	v_mfma_f32_16x16x32_bf16 v[92:95], v[242:245], v[178:181], v[92:95]
	v_mfma_f32_16x16x32_bf16 v[88:91], v[242:245], v[186:189], v[88:91]
	v_mfma_f32_16x16x32_bf16 v[84:87], v[242:245], v[190:193], v[84:87]
	v_mfma_f32_16x16x32_bf16 v[80:83], v[242:245], v[194:197], v[80:83]
	ds_read_b128 v[202:205], v182 offset:11520
	s_waitcnt lgkmcnt(3)
	v_mfma_f32_16x16x32_bf16 v[76:79], v[246:249], v[178:181], v[76:79]
	s_waitcnt vmcnt(5)
	ds_write_b128 v252, v[132:135]
	v_mfma_f32_16x16x32_bf16 v[72:75], v[246:249], v[186:189], v[72:75]
	v_mfma_f32_16x16x32_bf16 v[68:71], v[246:249], v[190:193], v[68:71]
	v_mfma_f32_16x16x32_bf16 v[64:67], v[246:249], v[194:197], v[64:67]
	ds_read_b128 v[242:245], v182 offset:13824
	s_waitcnt lgkmcnt(3)
	v_mfma_f32_16x16x32_bf16 v[60:63], v[198:201], v[178:181], v[60:63]
	s_waitcnt vmcnt(4)
	ds_write_b128 v253, v[136:139]
	v_mfma_f32_16x16x32_bf16 v[56:59], v[198:201], v[186:189], v[56:59]
	v_mfma_f32_16x16x32_bf16 v[52:55], v[198:201], v[190:193], v[52:55]
	v_mfma_f32_16x16x32_bf16 v[48:51], v[198:201], v[194:197], v[48:51]
	ds_read_b128 v[246:249], v182 offset:16128
	s_waitcnt lgkmcnt(4)
	v_mfma_f32_16x16x32_bf16 v[44:47], v[202:205], v[178:181], v[44:47]
	s_waitcnt vmcnt(3)
	ds_write_b128 v250, v[144:147] offset:36864
	v_mfma_f32_16x16x32_bf16 v[40:43], v[202:205], v[186:189], v[40:43]
	v_mfma_f32_16x16x32_bf16 v[36:39], v[202:205], v[190:193], v[36:39]
	v_mfma_f32_16x16x32_bf16 v[32:35], v[202:205], v[194:197], v[32:35]
	ds_read_b128 v[198:201], v182 offset:64
	s_waitcnt lgkmcnt(4)
	v_mfma_f32_16x16x32_bf16 v[28:31], v[242:245], v[178:181], v[28:31]
	s_waitcnt vmcnt(2)
	ds_write_b128 v251, v[148:151] offset:36864
	v_mfma_f32_16x16x32_bf16 v[24:27], v[242:245], v[186:189], v[24:27]
	v_mfma_f32_16x16x32_bf16 v[20:23], v[242:245], v[190:193], v[20:23]
	v_mfma_f32_16x16x32_bf16 v[16:19], v[242:245], v[194:197], v[16:19]
	ds_read_b128 v[202:205], v182 offset:2368
	s_waitcnt lgkmcnt(4)
	v_mfma_f32_16x16x32_bf16 v[8:11], v[246:249], v[178:181], v[8:11]
	ds_read_b128 v[178:181], v183 offset:36928
	s_waitcnt vmcnt(1)
	ds_write_b128 v252, v[152:155] offset:36864
	v_mfma_f32_16x16x32_bf16 v[4:7], v[246:249], v[186:189], v[4:7]
	ds_read_b128 v[186:189], v183 offset:39232
	v_mfma_f32_16x16x32_bf16 v[0:3], v[246:249], v[190:193], v[0:3]
	ds_read_b128 v[190:193], v183 offset:41536
	v_mfma_f32_16x16x32_bf16 v[12:15], v[246:249], v[194:197], v[12:15]
	ds_read_b128 v[194:197], v183 offset:43840
	ds_read_b128 v[242:245], v182 offset:4672
	s_waitcnt lgkmcnt(5)
	v_mfma_f32_16x16x32_bf16 v[140:143], v[198:201], v[178:181], v[140:143]
	s_waitcnt lgkmcnt(3)
	v_mfma_f32_16x16x32_bf16 v[120:123], v[198:201], v[186:189], v[120:123]
	s_waitcnt vmcnt(0)
	ds_write_b128 v253, v[156:159] offset:36864
	s_waitcnt lgkmcnt(3)
	v_mfma_f32_16x16x32_bf16 v[116:119], v[198:201], v[190:193], v[116:119]
	s_waitcnt lgkmcnt(2)
	v_mfma_f32_16x16x32_bf16 v[112:115], v[198:201], v[194:197], v[112:115]
	v_lshl_add_u64 v[124:125], s[52:53], 0, v[162:163]
	v_lshl_add_u64 v[128:129], s[52:53], 0, v[164:165]
	v_lshl_add_u64 v[132:133], s[52:53], 0, v[166:167]
	v_lshl_add_u64 v[136:137], s[52:53], 0, v[168:169]
	s_add_u32 s52, s2, s33
	s_addc_u32 s53, s3, 0
	v_lshl_add_u64 v[144:145], s[52:53], 0, v[162:163]
	v_lshl_add_u64 v[148:149], s[52:53], 0, v[164:165]
	v_lshl_add_u64 v[152:153], s[52:53], 0, v[166:167]
	v_lshl_add_u64 v[156:157], s[52:53], 0, v[168:169]
	global_load_dwordx4 v[124:127], v[124:125], off
	ds_read_b128 v[246:249], v182 offset:6976
	v_mfma_f32_16x16x32_bf16 v[108:111], v[202:205], v[178:181], v[108:111]
	v_mfma_f32_16x16x32_bf16 v[104:107], v[202:205], v[186:189], v[104:107]
	s_nop 0
	global_load_dwordx4 v[128:131], v[128:129], off
	v_mfma_f32_16x16x32_bf16 v[100:103], v[202:205], v[190:193], v[100:103]
	v_mfma_f32_16x16x32_bf16 v[96:99], v[202:205], v[194:197], v[96:99]
	ds_read_b128 v[198:201], v182 offset:9280
	s_waitcnt lgkmcnt(3)
	v_mfma_f32_16x16x32_bf16 v[92:95], v[242:245], v[178:181], v[92:95]
	s_nop 0
	global_load_dwordx4 v[132:135], v[132:133], off
	v_mfma_f32_16x16x32_bf16 v[88:91], v[242:245], v[186:189], v[88:91]
	v_mfma_f32_16x16x32_bf16 v[84:87], v[242:245], v[190:193], v[84:87]
	s_nop 0
	global_load_dwordx4 v[136:139], v[136:137], off
	v_mfma_f32_16x16x32_bf16 v[80:83], v[242:245], v[194:197], v[80:83]
	ds_read_b128 v[202:205], v182 offset:11584
	s_waitcnt lgkmcnt(2)
	v_mfma_f32_16x16x32_bf16 v[76:79], v[246:249], v[178:181], v[76:79]
	v_mfma_f32_16x16x32_bf16 v[72:75], v[246:249], v[186:189], v[72:75]
	s_nop 0
	global_load_dwordx4 v[144:147], v[144:145], off
	v_mfma_f32_16x16x32_bf16 v[68:71], v[246:249], v[190:193], v[68:71]
	v_mfma_f32_16x16x32_bf16 v[64:67], v[246:249], v[194:197], v[64:67]
	s_nop 0
	global_load_dwordx4 v[148:151], v[148:149], off
	ds_read_b128 v[242:245], v182 offset:13888
	s_waitcnt lgkmcnt(2)
	v_mfma_f32_16x16x32_bf16 v[60:63], v[198:201], v[178:181], v[60:63]
	v_mfma_f32_16x16x32_bf16 v[56:59], v[198:201], v[186:189], v[56:59]
	v_mfma_f32_16x16x32_bf16 v[52:55], v[198:201], v[190:193], v[52:55]
	s_nop 0
	global_load_dwordx4 v[152:155], v[152:153], off
	v_mfma_f32_16x16x32_bf16 v[48:51], v[198:201], v[194:197], v[48:51]
	ds_read_b128 v[246:249], v182 offset:16192
	s_waitcnt lgkmcnt(2)
	v_mfma_f32_16x16x32_bf16 v[44:47], v[202:205], v[178:181], v[44:47]
	s_nop 0
	global_load_dwordx4 v[156:159], v[156:157], off
	v_mfma_f32_16x16x32_bf16 v[40:43], v[202:205], v[186:189], v[40:43]
	v_mfma_f32_16x16x32_bf16 v[36:39], v[202:205], v[190:193], v[36:39]
	v_mfma_f32_16x16x32_bf16 v[32:35], v[202:205], v[194:197], v[32:35]
	s_waitcnt lgkmcnt(0)
	s_barrier
; DI f32x4 mfma16(bf16x8 a, bf16x8 b, f32x4 c) { return __builtin_amdgcn_mfma_f32_16x16x32_bf16(a, b, c, 0, 0, 0); }
; template <int MI, int NJ, bool SWAP, class AP, class BP>
; DI void gemm_main(f32x4 (&acc)[MI][NJ], const AP& ap, int a_kstep, const BP& bp, int b_kstep, int nk, bf16_t* smem) {
;     ...
;   for (int kt = 0; kt < nk; ++kt) {
;     const int buf = kt & 1;
;     sstore(buf ^ 1);
;     gload(kt + 2 < nk ? kt + 2 : nk - 1);
;     __builtin_amdgcn_sched_barrier(0);
;     const bf16_t* As = smem + buf * L::STAGE + (wm * 16 * MI + l15) * LDT + quad * 8;
;     const bf16_t* Bs = smem + buf * L::STAGE + L::A_ELEMS + (wn * 16 * NJ + l15) * LDT + quad * 8;
; #pragma unroll
;     for (int ks = 0; ks < 2; ++ks) {
;       if (MI * NJ >= 32 && ks == 1) asm volatile("" ::: "memory");
;       bf16x8 b[NJ];
; #pragma unroll
;       for (int j = 0; j < NJ; ++j) b[j] = *(const bf16x8*)(Bs + j * 16 * LDT + ks * 32);
; #pragma unroll
;       for (int i = 0; i < MI; ++i) {
;         const bf16x8 a = *(const bf16x8*)(As + i * 16 * LDT + ks * 32);
; #pragma unroll
;         for (int j = 0; j < NJ; ++j) acc[i][j] = SWAP ? mfma16(b[j], a, acc[i][j]) : mfma16(a, b[j], acc[i][j]);
	s_add_i32 s5, s5, 1
	s_cmp_lg_u32 s5, 4
	s_cbranch_scc0 .Lgm4_exit
	s_and_b32 s98, s5, 1
	s_mul_i32 s98, s98, 0x12000
	v_add3_u32 v182, s98, v176, v177
	v_add3_u32 v183, s98, v171, v177
	ds_read_b128 v[198:201], v182
	ds_read_b128 v[202:205], v182 offset:2304
	v_mfma_f32_16x16x32_bf16 v[28:31], v[242:245], v[178:181], v[28:31]
	v_mfma_f32_16x16x32_bf16 v[8:11], v[246:249], v[178:181], v[8:11]
	ds_read_b128 v[178:181], v183 offset:36864
	v_mfma_f32_16x16x32_bf16 v[24:27], v[242:245], v[186:189], v[24:27]
	v_mfma_f32_16x16x32_bf16 v[4:7], v[246:249], v[186:189], v[4:7]
	ds_read_b128 v[186:189], v183 offset:39168
	v_mfma_f32_16x16x32_bf16 v[20:23], v[242:245], v[190:193], v[20:23]
	v_mfma_f32_16x16x32_bf16 v[0:3], v[246:249], v[190:193], v[0:3]
	ds_read_b128 v[190:193], v183 offset:41472
	v_mfma_f32_16x16x32_bf16 v[16:19], v[242:245], v[194:197], v[16:19]
	v_mfma_f32_16x16x32_bf16 v[12:15], v[246:249], v[194:197], v[12:15]
	ds_read_b128 v[194:197], v183 offset:43776
	s_branch .Lgm4_main

; DI f32x4 mfma16(bf16x8 a, bf16x8 b, f32x4 c) { return __builtin_amdgcn_mfma_f32_16x16x32_bf16(a, b, c, 0, 0, 0); }
; template <int MI, int NJ, bool SWAP, class AP, class BP>
; DI void gemm_main(f32x4 (&acc)[MI][NJ], const AP& ap, int a_kstep, const BP& bp, int b_kstep, int nk, bf16_t* smem) {
;     ...
;   auto gload = [&](int kt) {
;     const bf16_t* ab = ap.base + (size_t)kt * a_kstep; const bf16_t* bb = bp.base + (size_t)kt * b_kstep;
; #pragma unroll
;     for (int i = 0; i < CA; ++i) ra[i] = *(const u32x4*)(ab + pa[i]);
; #pragma unroll
;     for (int i = 0; i < CB; ++i) rb[i] = *(const u32x4*)(bb + pb[i]);
;   };
;   auto sstore = [&](int buf) {
;     bf16_t* As = smem + buf * L::STAGE; bf16_t* Bs = As + L::A_ELEMS;
; #pragma unroll
;     for (int i = 0; i < CA; ++i) { const int c = tid + NTHR * i; *(u32x4*)(As + (c >> 3) * LDT + (c & 7) * 8) = oka[i] ? ra[i] : (u32x4){0u, 0u, 0u, 0u}; }
; #pragma unroll
;     for (int i = 0; i < CB; ++i) { const int c = tid + NTHR * i; *(u32x4*)(Bs + (c >> 3) * LDT + (c & 7) * 8) = rb[i]; }
;   };
;   gload(0); sstore(0); gload(nk > 1 ? 1 : 0); __syncthreads();
; #pragma unroll 1
;   for (int kt = 0; kt < nk; ++kt) {
;     const int buf = kt & 1;
;     sstore(buf ^ 1);
;     gload(kt + 2 < nk ? kt + 2 : nk - 1);
;     __builtin_amdgcn_sched_barrier(0);
;     const bf16_t* As = smem + buf * L::STAGE + (wm * 16 * MI + l15) * LDT + quad * 8;
;     const bf16_t* Bs = smem + buf * L::STAGE + L::A_ELEMS + (wn * 16 * NJ + l15) * LDT + quad * 8;
; #pragma unroll
;     for (int ks = 0; ks < 2; ++ks) {
;       if (MI * NJ >= 32 && ks == 1) asm volatile("" ::: "memory");
;       bf16x8 b[NJ];
; #pragma unroll
;       for (int j = 0; j < NJ; ++j) b[j] = *(const bf16x8*)(Bs + j * 16 * LDT + ks * 32);
; #pragma unroll
;       for (int i = 0; i < MI; ++i) {
;         const bf16x8 a = *(const bf16x8*)(As + i * 16 * LDT + ks * 32);
; #pragma unroll
;         for (int j = 0; j < NJ; ++j) acc[i][j] = SWAP ? mfma16(b[j], a, acc[i][j]) : mfma16(a, b[j], acc[i][j]);
;       }
;     }
;     __syncthreads();
;   }
.Lgm5_main:
	ds_read_b128 v[242:245], v177 offset:4608
	s_waitcnt lgkmcnt(4)
	v_mfma_f32_16x16x32_bf16 v[156:159], v[178:181], v[194:197], v[156:159]
	s_waitcnt lgkmcnt(3)
	v_mfma_f32_16x16x32_bf16 v[152:155], v[182:185], v[194:197], v[152:155]
	s_waitcnt lgkmcnt(2)
	v_mfma_f32_16x16x32_bf16 v[148:151], v[186:189], v[194:197], v[148:151]
	s_waitcnt lgkmcnt(1)
	v_mfma_f32_16x16x32_bf16 v[128:131], v[190:193], v[194:197], v[128:131]
	s_and_b32 s15, s1, 1
	s_min_u32 s16, s1, 13
	s_xor_b32 s17, s15, 1
	s_lshl_b32 s26, s16, 7
	s_mul_i32 s17, s17, 0x12000
	s_add_u32 s16, s2, s26
	v_add3_u32 v250, s17, v172, v170
	v_add3_u32 v251, s17, v174, v170
	v_add3_u32 v252, s17, v175, v170
	v_add3_u32 v253, s17, v176, v170
	s_addc_u32 s17, s3, 0
	s_waitcnt vmcnt(7)
	ds_write_b128 v250, v[112:115]
	ds_read_b128 v[246:249], v177 offset:6912
	v_mfma_f32_16x16x32_bf16 v[108:111], v[178:181], v[198:201], v[108:111]
	v_mfma_f32_16x16x32_bf16 v[104:107], v[182:185], v[198:201], v[104:107]
	v_mfma_f32_16x16x32_bf16 v[100:103], v[186:189], v[198:201], v[100:103]
	v_mfma_f32_16x16x32_bf16 v[96:99], v[190:193], v[198:201], v[96:99]
	s_waitcnt vmcnt(6)
	ds_write_b128 v251, v[116:119]
	ds_read_b128 v[194:197], v177 offset:9216
	s_waitcnt lgkmcnt(4)
	v_mfma_f32_16x16x32_bf16 v[92:95], v[178:181], v[242:245], v[92:95]
	v_mfma_f32_16x16x32_bf16 v[88:91], v[182:185], v[242:245], v[88:91]
	v_mfma_f32_16x16x32_bf16 v[84:87], v[186:189], v[242:245], v[84:87]
	v_mfma_f32_16x16x32_bf16 v[80:83], v[190:193], v[242:245], v[80:83]
	ds_read_b128 v[198:201], v177 offset:11520
	s_waitcnt lgkmcnt(3)
	v_mfma_f32_16x16x32_bf16 v[76:79], v[178:181], v[246:249], v[76:79]
	s_waitcnt vmcnt(5)
	ds_write_b128 v252, v[120:123]
	v_mfma_f32_16x16x32_bf16 v[72:75], v[182:185], v[246:249], v[72:75]
	v_mfma_f32_16x16x32_bf16 v[68:71], v[186:189], v[246:249], v[68:71]
	v_mfma_f32_16x16x32_bf16 v[64:67], v[190:193], v[246:249], v[64:67]
	ds_read_b128 v[242:245], v177 offset:13824
	s_waitcnt lgkmcnt(3)
	v_mfma_f32_16x16x32_bf16 v[60:63], v[178:181], v[194:197], v[60:63]
	s_waitcnt vmcnt(4)
	ds_write_b128 v253, v[124:127]
	v_mfma_f32_16x16x32_bf16 v[56:59], v[182:185], v[194:197], v[56:59]
	v_mfma_f32_16x16x32_bf16 v[52:55], v[186:189], v[194:197], v[52:55]
	v_mfma_f32_16x16x32_bf16 v[48:51], v[190:193], v[194:197], v[48:51]
	ds_read_b128 v[246:249], v177 offset:16128
	s_waitcnt lgkmcnt(4)
	v_mfma_f32_16x16x32_bf16 v[44:47], v[178:181], v[198:201], v[44:47]
	s_waitcnt vmcnt(3)
	ds_write_b128 v250, v[132:135] offset:36864
	v_mfma_f32_16x16x32_bf16 v[40:43], v[182:185], v[198:201], v[40:43]
	v_mfma_f32_16x16x32_bf16 v[36:39], v[186:189], v[198:201], v[36:39]
	v_mfma_f32_16x16x32_bf16 v[32:35], v[190:193], v[198:201], v[32:35]
	ds_read_b128 v[194:197], v177 offset:64
	s_waitcnt lgkmcnt(4)
	v_mfma_f32_16x16x32_bf16 v[28:31], v[178:181], v[242:245], v[28:31]
	s_waitcnt vmcnt(2)
	ds_write_b128 v251, v[136:139] offset:36864
	v_mfma_f32_16x16x32_bf16 v[24:27], v[182:185], v[242:245], v[24:27]
	v_mfma_f32_16x16x32_bf16 v[20:23], v[186:189], v[242:245], v[20:23]
	v_mfma_f32_16x16x32_bf16 v[16:19], v[190:193], v[242:245], v[16:19]
	ds_read_b128 v[198:201], v177 offset:2368
	s_waitcnt lgkmcnt(4)
	v_mfma_f32_16x16x32_bf16 v[8:11], v[178:181], v[246:249], v[8:11]
	ds_read_b128 v[178:181], v202 offset:36928
	s_waitcnt vmcnt(1)
	ds_write_b128 v252, v[140:143] offset:36864
	v_mfma_f32_16x16x32_bf16 v[4:7], v[182:185], v[246:249], v[4:7]
	ds_read_b128 v[182:185], v202 offset:39232
	v_mfma_f32_16x16x32_bf16 v[0:3], v[186:189], v[246:249], v[0:3]
	ds_read_b128 v[186:189], v202 offset:41536
	v_mfma_f32_16x16x32_bf16 v[12:15], v[190:193], v[246:249], v[12:15]
	ds_read_b128 v[190:193], v202 offset:43840
	ds_read_b128 v[242:245], v177 offset:4672
	s_waitcnt lgkmcnt(5)
	v_mfma_f32_16x16x32_bf16 v[156:159], v[178:181], v[194:197], v[156:159]
	s_waitcnt lgkmcnt(3)
	v_mfma_f32_16x16x32_bf16 v[152:155], v[182:185], v[194:197], v[152:155]
	s_waitcnt vmcnt(0)
	ds_write_b128 v253, v[144:147] offset:36864
	s_waitcnt lgkmcnt(3)
	v_mfma_f32_16x16x32_bf16 v[148:151], v[186:189], v[194:197], v[148:151]
	s_waitcnt lgkmcnt(2)
	v_mfma_f32_16x16x32_bf16 v[128:131], v[190:193], v[194:197], v[128:131]
	v_lshl_add_u64 v[112:113], s[16:17], 0, v[162:163]
	v_lshl_add_u64 v[116:117], s[16:17], 0, v[164:165]
	v_lshl_add_u64 v[120:121], s[16:17], 0, v[166:167]
	v_lshl_add_u64 v[124:125], s[16:17], 0, v[168:169]
	s_add_u32 s16, s12, s26
	s_addc_u32 s17, s13, 0
	v_lshl_add_u64 v[132:133], s[16:17], 0, v[162:163]
	v_lshl_add_u64 v[136:137], s[16:17], 0, v[164:165]
	v_lshl_add_u64 v[140:141], s[16:17], 0, v[166:167]
	v_lshl_add_u64 v[144:145], s[16:17], 0, v[168:169]
	global_load_dwordx4 v[112:115], v[112:113], off offset:256
	ds_read_b128 v[246:249], v177 offset:6976
	v_mfma_f32_16x16x32_bf16 v[108:111], v[178:181], v[198:201], v[108:111]
	v_mfma_f32_16x16x32_bf16 v[104:107], v[182:185], v[198:201], v[104:107]
	s_nop 0
	global_load_dwordx4 v[116:119], v[116:117], off offset:256
	v_mfma_f32_16x16x32_bf16 v[100:103], v[186:189], v[198:201], v[100:103]
	v_mfma_f32_16x16x32_bf16 v[96:99], v[190:193], v[198:201], v[96:99]
	ds_read_b128 v[194:197], v177 offset:9280
	s_waitcnt lgkmcnt(3)
	v_mfma_f32_16x16x32_bf16 v[92:95], v[178:181], v[242:245], v[92:95]
	s_nop 0
	global_load_dwordx4 v[120:123], v[120:121], off offset:256
	v_mfma_f32_16x16x32_bf16 v[88:91], v[182:185], v[242:245], v[88:91]
	v_mfma_f32_16x16x32_bf16 v[84:87], v[186:189], v[242:245], v[84:87]
	s_nop 0
	global_load_dwordx4 v[124:127], v[124:125], off offset:256
	v_mfma_f32_16x16x32_bf16 v[80:83], v[190:193], v[242:245], v[80:83]
	ds_read_b128 v[198:201], v177 offset:11584
	s_waitcnt lgkmcnt(2)
	v_mfma_f32_16x16x32_bf16 v[76:79], v[178:181], v[246:249], v[76:79]
	v_mfma_f32_16x16x32_bf16 v[72:75], v[182:185], v[246:249], v[72:75]
	s_nop 0
	global_load_dwordx4 v[132:135], v[132:133], off offset:256
	v_mfma_f32_16x16x32_bf16 v[68:71], v[186:189], v[246:249], v[68:71]
	v_mfma_f32_16x16x32_bf16 v[64:67], v[190:193], v[246:249], v[64:67]
	s_nop 0
	global_load_dwordx4 v[136:139], v[136:137], off offset:256
	ds_read_b128 v[242:245], v177 offset:13888
	s_waitcnt lgkmcnt(2)
	v_mfma_f32_16x16x32_bf16 v[60:63], v[178:181], v[194:197], v[60:63]
	v_mfma_f32_16x16x32_bf16 v[56:59], v[182:185], v[194:197], v[56:59]
	v_mfma_f32_16x16x32_bf16 v[52:55], v[186:189], v[194:197], v[52:55]
	s_nop 0
	global_load_dwordx4 v[140:143], v[140:141], off offset:256
	v_mfma_f32_16x16x32_bf16 v[48:51], v[190:193], v[194:197], v[48:51]
	ds_read_b128 v[246:249], v177 offset:16192
	s_waitcnt lgkmcnt(2)
	v_mfma_f32_16x16x32_bf16 v[44:47], v[178:181], v[198:201], v[44:47]
	s_nop 0
	global_load_dwordx4 v[144:147], v[144:145], off offset:256
	v_mfma_f32_16x16x32_bf16 v[40:43], v[182:185], v[198:201], v[40:43]
	v_mfma_f32_16x16x32_bf16 v[36:39], v[186:189], v[198:201], v[36:39]
	v_mfma_f32_16x16x32_bf16 v[32:35], v[190:193], v[198:201], v[32:35]
	s_waitcnt lgkmcnt(0)
	s_barrier
; DI f32x4 mfma16(bf16x8 a, bf16x8 b, f32x4 c) { return __builtin_amdgcn_mfma_f32_16x16x32_bf16(a, b, c, 0, 0, 0); }
; template <int MI, int NJ, bool SWAP, class AP, class BP>
; DI void gemm_main(f32x4 (&acc)[MI][NJ], const AP& ap, int a_kstep, const BP& bp, int b_kstep, int nk, bf16_t* smem) {
;     ...
;   for (int kt = 0; kt < nk; ++kt) {
;     const int buf = kt & 1;
;     sstore(buf ^ 1);
;     gload(kt + 2 < nk ? kt + 2 : nk - 1);
;     __builtin_amdgcn_sched_barrier(0);
;     const bf16_t* As = smem + buf * L::STAGE + (wm * 16 * MI + l15) * LDT + quad * 8;
;     const bf16_t* Bs = smem + buf * L::STAGE + L::A_ELEMS + (wn * 16 * NJ + l15) * LDT + quad * 8;
; #pragma unroll
;     for (int ks = 0; ks < 2; ++ks) {
;       if (MI * NJ >= 32 && ks == 1) asm volatile("" ::: "memory");
;       bf16x8 b[NJ];
; #pragma unroll
;       for (int j = 0; j < NJ; ++j) b[j] = *(const bf16x8*)(Bs + j * 16 * LDT + ks * 32);
; #pragma unroll
;       for (int i = 0; i < MI; ++i) {
;         const bf16x8 a = *(const bf16x8*)(As + i * 16 * LDT + ks * 32);
; #pragma unroll
;         for (int j = 0; j < NJ; ++j) acc[i][j] = SWAP ? mfma16(b[j], a, acc[i][j]) : mfma16(a, b[j], acc[i][j]);
	s_add_i32 s1, s1, 1
	s_cmp_lg_u32 s1, 16
	s_cbranch_scc0 .Lgm5_exit
	s_and_b32 s98, s1, 1
	s_mul_i32 s98, s98, 0x12000
	v_add3_u32 v202, s98, v160, v173
	v_add3_u32 v177, s98, v171, v173
	ds_read_b128 v[194:197], v177
	ds_read_b128 v[198:201], v177 offset:2304
	v_mfma_f32_16x16x32_bf16 v[28:31], v[178:181], v[242:245], v[28:31]
	v_mfma_f32_16x16x32_bf16 v[8:11], v[178:181], v[246:249], v[8:11]
	ds_read_b128 v[178:181], v202 offset:36864
	v_mfma_f32_16x16x32_bf16 v[24:27], v[182:185], v[242:245], v[24:27]
	v_mfma_f32_16x16x32_bf16 v[4:7], v[182:185], v[246:249], v[4:7]
	ds_read_b128 v[182:185], v202 offset:39168
	v_mfma_f32_16x16x32_bf16 v[20:23], v[186:189], v[242:245], v[20:23]
	v_mfma_f32_16x16x32_bf16 v[0:3], v[186:189], v[246:249], v[0:3]
	ds_read_b128 v[186:189], v202 offset:41472
	v_mfma_f32_16x16x32_bf16 v[16:19], v[190:193], v[242:245], v[16:19]
	v_mfma_f32_16x16x32_bf16 v[12:15], v[190:193], v[246:249], v[12:15]
	ds_read_b128 v[190:193], v202 offset:43776
	s_branch .Lgm5_main

; DI f32x4 mfma16(bf16x8 a, bf16x8 b, f32x4 c) { return __builtin_amdgcn_mfma_f32_16x16x32_bf16(a, b, c, 0, 0, 0); }
; template <int MI, int NJ, bool SWAP, class AP, class BP>
; DI void gemm_main(f32x4 (&acc)[MI][NJ], const AP& ap, int a_kstep, const BP& bp, int b_kstep, int nk, bf16_t* smem) {
;     ...
;   auto gload = [&](int kt) {
;     const bf16_t* ab = ap.base + (size_t)kt * a_kstep; const bf16_t* bb = bp.base + (size_t)kt * b_kstep;
; #pragma unroll
;     for (int i = 0; i < CA; ++i) ra[i] = *(const u32x4*)(ab + pa[i]);
; #pragma unroll
;     for (int i = 0; i < CB; ++i) rb[i] = *(const u32x4*)(bb + pb[i]);
;   };
;   auto sstore = [&](int buf) {
;     bf16_t* As = smem + buf * L::STAGE; bf16_t* Bs = As + L::A_ELEMS;
; #pragma unroll
;     for (int i = 0; i < CA; ++i) { const int c = tid + NTHR * i; *(u32x4*)(As + (c >> 3) * LDT + (c & 7) * 8) = oka[i] ? ra[i] : (u32x4){0u, 0u, 0u, 0u}; }
; #pragma unroll
;     for (int i = 0; i < CB; ++i) { const int c = tid + NTHR * i; *(u32x4*)(Bs + (c >> 3) * LDT + (c & 7) * 8) = rb[i]; }
;   };
;   gload(0); sstore(0); gload(nk > 1 ? 1 : 0); __syncthreads();
; #pragma unroll 1
;   for (int kt = 0; kt < nk; ++kt) {
;     const int buf = kt & 1;
;     sstore(buf ^ 1);
;     gload(kt + 2 < nk ? kt + 2 : nk - 1);
;     __builtin_amdgcn_sched_barrier(0);
;     const bf16_t* As = smem + buf * L::STAGE + (wm * 16 * MI + l15) * LDT + quad * 8;
;     const bf16_t* Bs = smem + buf * L::STAGE + L::A_ELEMS + (wn * 16 * NJ + l15) * LDT + quad * 8;
; #pragma unroll
;     for (int ks = 0; ks < 2; ++ks) {
;       if (MI * NJ >= 32 && ks == 1) asm volatile("" ::: "memory");
;       bf16x8 b[NJ];
; #pragma unroll
;       for (int j = 0; j < NJ; ++j) b[j] = *(const bf16x8*)(Bs + j * 16 * LDT + ks * 32);
; #pragma unroll
;       for (int i = 0; i < MI; ++i) {
;         const bf16x8 a = *(const bf16x8*)(As + i * 16 * LDT + ks * 32);
; #pragma unroll
;         for (int j = 0; j < NJ; ++j) acc[i][j] = SWAP ? mfma16(b[j], a, acc[i][j]) : mfma16(a, b[j], acc[i][j]);
;       }
;     }
;     __syncthreads();
;   }
.LBB0_1049:
	s_and_b32 s98, s30, 1
	s_mul_i32 s98, s98, 0x12000
	v_add3_u32 v181, s98, v170, v180
	v_add3_u32 v202, s98, v171, v180
	ds_read_b128 v[198:201], v181
	ds_read_b128 v[242:245], v181 offset:2304
	ds_read_b128 v[182:185], v202 offset:36864
	ds_read_b128 v[186:189], v202 offset:39168
	ds_read_b128 v[190:193], v202 offset:41472
	ds_read_b128 v[194:197], v202 offset:43776
.Lgm6_main:
	ds_read_b128 v[246:249], v181 offset:4608
	s_waitcnt lgkmcnt(4)
	v_mfma_f32_16x16x32_bf16 v[156:159], v[182:185], v[198:201], v[156:159]
	s_waitcnt lgkmcnt(3)
	v_mfma_f32_16x16x32_bf16 v[152:155], v[186:189], v[198:201], v[152:155]
	s_waitcnt lgkmcnt(2)
	v_mfma_f32_16x16x32_bf16 v[148:151], v[190:193], v[198:201], v[148:151]
	s_waitcnt lgkmcnt(1)
	v_mfma_f32_16x16x32_bf16 v[144:147], v[194:197], v[198:201], v[144:147]
	s_and_b32 s31, s30, 1
	s_xor_b32 s33, s31, 1
	s_mul_i32 s33, s33, 0x12000
	s_waitcnt vmcnt(7)
	v_cndmask_b32_e32 v139, 0, v139, vcc
	v_cndmask_b32_e32 v138, 0, v138, vcc
	v_cndmask_b32_e32 v137, 0, v137, vcc
	v_cndmask_b32_e32 v136, 0, v136, vcc
	v_add3_u32 v254, s33, v172, v169
	ds_write_b128 v254, v[136:139]
	ds_read_b128 v[250:253], v181 offset:6912
	v_mfma_f32_16x16x32_bf16 v[108:111], v[182:185], v[242:245], v[108:111]
	v_mfma_f32_16x16x32_bf16 v[104:107], v[186:189], v[242:245], v[104:107]
	v_mfma_f32_16x16x32_bf16 v[100:103], v[190:193], v[242:245], v[100:103]
	v_mfma_f32_16x16x32_bf16 v[96:99], v[194:197], v[242:245], v[96:99]
	s_waitcnt vmcnt(6)
	v_cndmask_b32_e64 v127, 0, v127, s[0:1]
	v_cndmask_b32_e64 v126, 0, v126, s[0:1]
	v_cndmask_b32_e64 v125, 0, v125, s[0:1]
	v_cndmask_b32_e64 v124, 0, v124, s[0:1]
	v_add3_u32 v136, s33, v173, v169
	ds_write_b128 v136, v[124:127]
	ds_read_b128 v[198:201], v181 offset:9216
	s_waitcnt lgkmcnt(4)
	v_mfma_f32_16x16x32_bf16 v[92:95], v[182:185], v[246:249], v[92:95]
	v_mfma_f32_16x16x32_bf16 v[88:91], v[186:189], v[246:249], v[88:91]
	v_mfma_f32_16x16x32_bf16 v[84:87], v[190:193], v[246:249], v[84:87]
	v_mfma_f32_16x16x32_bf16 v[80:83], v[194:197], v[246:249], v[80:83]
	ds_read_b128 v[242:245], v181 offset:11520
	s_waitcnt lgkmcnt(3)
	v_mfma_f32_16x16x32_bf16 v[76:79], v[182:185], v[250:253], v[76:79]
	s_waitcnt vmcnt(5)
	v_cndmask_b32_e64 v115, 0, v115, s[2:3]
	v_cndmask_b32_e64 v114, 0, v114, s[2:3]
	v_cndmask_b32_e64 v113, 0, v113, s[2:3]
	v_cndmask_b32_e64 v112, 0, v112, s[2:3]
	v_add3_u32 v124, s33, v174, v169
	ds_write_b128 v124, v[112:115]
	v_mfma_f32_16x16x32_bf16 v[72:75], v[186:189], v[250:253], v[72:75]
	v_mfma_f32_16x16x32_bf16 v[68:71], v[190:193], v[250:253], v[68:71]
	v_mfma_f32_16x16x32_bf16 v[64:67], v[194:197], v[250:253], v[64:67]
	ds_read_b128 v[246:249], v181 offset:13824
	s_waitcnt lgkmcnt(3)
	v_mfma_f32_16x16x32_bf16 v[60:63], v[182:185], v[198:201], v[60:63]
	s_waitcnt vmcnt(4)
	v_cndmask_b32_e64 v112, 0, v116, s[4:5]
	v_add3_u32 v116, s33, v175, v169
	s_min_u32 s33, s30, 13
	s_lshl_b32 s33, s33, 7
	v_cndmask_b32_e64 v115, 0, v119, s[4:5]
	v_cndmask_b32_e64 v114, 0, v118, s[4:5]
	v_cndmask_b32_e64 v113, 0, v117, s[4:5]
	s_add_u32 s34, s12, s33
	ds_write_b128 v116, v[112:115]
	v_mfma_f32_16x16x32_bf16 v[56:59], v[186:189], v[198:201], v[56:59]
	v_mfma_f32_16x16x32_bf16 v[52:55], v[190:193], v[198:201], v[52:55]
	v_mfma_f32_16x16x32_bf16 v[48:51], v[194:197], v[198:201], v[48:51]
	ds_read_b128 v[250:253], v181 offset:16128
	s_waitcnt lgkmcnt(4)
	v_mfma_f32_16x16x32_bf16 v[44:47], v[182:185], v[242:245], v[44:47]
	s_waitcnt vmcnt(3)
	ds_write_b128 v254, v[120:123] offset:36864
	v_mfma_f32_16x16x32_bf16 v[40:43], v[186:189], v[242:245], v[40:43]
	v_mfma_f32_16x16x32_bf16 v[36:39], v[190:193], v[242:245], v[36:39]
	v_mfma_f32_16x16x32_bf16 v[32:35], v[194:197], v[242:245], v[32:35]
	ds_read_b128 v[198:201], v181 offset:64
	s_waitcnt lgkmcnt(4)
	v_mfma_f32_16x16x32_bf16 v[28:31], v[182:185], v[246:249], v[28:31]
	s_waitcnt vmcnt(2)
	ds_write_b128 v136, v[128:131] offset:36864
	v_mfma_f32_16x16x32_bf16 v[24:27], v[186:189], v[246:249], v[24:27]
	v_mfma_f32_16x16x32_bf16 v[20:23], v[190:193], v[246:249], v[20:23]
	v_mfma_f32_16x16x32_bf16 v[16:19], v[194:197], v[246:249], v[16:19]
	ds_read_b128 v[242:245], v181 offset:2368
	s_waitcnt lgkmcnt(4)
	v_mfma_f32_16x16x32_bf16 v[12:15], v[182:185], v[250:253], v[12:15]
	ds_read_b128 v[182:185], v202 offset:36928
	s_waitcnt vmcnt(1)
	ds_write_b128 v124, v[132:135] offset:36864
	v_mfma_f32_16x16x32_bf16 v[8:11], v[186:189], v[250:253], v[8:11]
	ds_read_b128 v[186:189], v202 offset:39232
	v_mfma_f32_16x16x32_bf16 v[4:7], v[190:193], v[250:253], v[4:7]
	ds_read_b128 v[190:193], v202 offset:41536
	v_mfma_f32_16x16x32_bf16 v[0:3], v[194:197], v[250:253], v[0:3]
	ds_read_b128 v[194:197], v202 offset:43840
	ds_read_b128 v[246:249], v181 offset:4672
	s_waitcnt lgkmcnt(5)
	v_mfma_f32_16x16x32_bf16 v[156:159], v[182:185], v[198:201], v[156:159]
	s_waitcnt lgkmcnt(3)
	v_mfma_f32_16x16x32_bf16 v[152:155], v[186:189], v[198:201], v[152:155]
	s_waitcnt vmcnt(0)
	ds_write_b128 v116, v[140:143] offset:36864
	s_waitcnt lgkmcnt(3)
	v_mfma_f32_16x16x32_bf16 v[148:151], v[190:193], v[198:201], v[148:151]
	s_waitcnt lgkmcnt(2)
	v_mfma_f32_16x16x32_bf16 v[144:147], v[194:197], v[198:201], v[144:147]
	s_addc_u32 s35, s13, 0
	global_load_dwordx4 v[136:139], v176, s[34:35] offset:256
	ds_read_b128 v[250:253], v181 offset:6976
	v_mfma_f32_16x16x32_bf16 v[108:111], v[182:185], v[242:245], v[108:111]
	v_mfma_f32_16x16x32_bf16 v[104:107], v[186:189], v[242:245], v[104:107]
	global_load_dwordx4 v[124:127], v177, s[34:35] offset:256
	v_mfma_f32_16x16x32_bf16 v[100:103], v[190:193], v[242:245], v[100:103]
	v_mfma_f32_16x16x32_bf16 v[96:99], v[194:197], v[242:245], v[96:99]
	ds_read_b128 v[198:201], v181 offset:9280
	s_waitcnt lgkmcnt(3)
; DI f32x4 mfma16(bf16x8 a, bf16x8 b, f32x4 c) { return __builtin_amdgcn_mfma_f32_16x16x32_bf16(a, b, c, 0, 0, 0); }
; DI void store4(bf16_t* dst, const f32x4& v, float s) { *(u32x2*)dst = (u32x2){pk2(v[0] * s, v[1] * s), pk2(v[2] * s, v[3] * s)}; }
; template <int MI, int NJ, bool SWAP, class AP, class BP>
; DI void gemm_main(f32x4 (&acc)[MI][NJ], const AP& ap, int a_kstep, const BP& bp, int b_kstep, int nk, bf16_t* smem) {
;     ...
;   for (int kt = 0; kt < nk; ++kt) {
;     const int buf = kt & 1;
;     sstore(buf ^ 1);
;     gload(kt + 2 < nk ? kt + 2 : nk - 1);
;     __builtin_amdgcn_sched_barrier(0);
;     const bf16_t* As = smem + buf * L::STAGE + (wm * 16 * MI + l15) * LDT + quad * 8;
;     const bf16_t* Bs = smem + buf * L::STAGE + L::A_ELEMS + (wn * 16 * NJ + l15) * LDT + quad * 8;
; #pragma unroll
;     for (int ks = 0; ks < 2; ++ks) {
;       if (MI * NJ >= 32 && ks == 1) asm volatile("" ::: "memory");
;       bf16x8 b[NJ];
; #pragma unroll
;       for (int j = 0; j < NJ; ++j) b[j] = *(const bf16x8*)(Bs + j * 16 * LDT + ks * 32);
; #pragma unroll
;       for (int i = 0; i < MI; ++i) {
;         const bf16x8 a = *(const bf16x8*)(As + i * 16 * LDT + ks * 32);
; #pragma unroll
;         for (int j = 0; j < NJ; ++j) acc[i][j] = SWAP ? mfma16(b[j], a, acc[i][j]) : mfma16(a, b[j], acc[i][j]);
;       }
;     }
;     __syncthreads();
;   }
; DI void ffnup_tile(const Params& p, int layer, int b, int mt, int tn, bf16_t* smem) {
;     ...
;   {
;     bf16_t* dstb = (wn < 2 ? U : V) + (wn & 1) * 64 + quad * 4;
; #pragma unroll
;     for (int i = 0; i < 8; ++i) {
;       const int row = wm * 128 + i * 16 + l15, s = s0 + row;
;       const float rs = (s >= 0 && s < S_) ? rstd_from16((const float*)(p.ws + O_SSQ) + ((size_t)b * S_ + s) * 16, 1.f / 1024.f) : 0.f;
; #pragma unroll
;       for (int j = 0; j < 4; ++j) store4(dstb + row * LDU + j * 16, acc[i][j], rs);
	v_mfma_f32_16x16x32_bf16 v[92:95], v[182:185], v[246:249], v[92:95]
	global_load_dwordx4 v[112:115], v178, s[34:35] offset:256
	v_mfma_f32_16x16x32_bf16 v[88:91], v[186:189], v[246:249], v[88:91]
	v_mfma_f32_16x16x32_bf16 v[84:87], v[190:193], v[246:249], v[84:87]
	global_load_dwordx4 v[116:119], v179, s[34:35] offset:256
	v_mfma_f32_16x16x32_bf16 v[80:83], v[194:197], v[246:249], v[80:83]
	ds_read_b128 v[242:245], v181 offset:11584
	s_waitcnt lgkmcnt(2)
	v_mfma_f32_16x16x32_bf16 v[76:79], v[182:185], v[250:253], v[76:79]
	v_mfma_f32_16x16x32_bf16 v[72:75], v[186:189], v[250:253], v[72:75]
	s_add_u32 s34, s14, s33
	s_addc_u32 s35, s15, 0
	v_lshl_add_u64 v[120:121], v[160:161], 1, s[34:35]
	v_lshl_add_u64 v[128:129], v[162:163], 1, s[34:35]
	v_lshl_add_u64 v[132:133], v[164:165], 1, s[34:35]
	v_lshl_add_u64 v[140:141], v[166:167], 1, s[34:35]
	global_load_dwordx4 v[120:123], v[120:121], off offset:256
	v_mfma_f32_16x16x32_bf16 v[68:71], v[190:193], v[250:253], v[68:71]
	v_mfma_f32_16x16x32_bf16 v[64:67], v[194:197], v[250:253], v[64:67]
	s_nop 0
	global_load_dwordx4 v[128:131], v[128:129], off offset:256
	ds_read_b128 v[246:249], v181 offset:13888
	s_waitcnt lgkmcnt(2)
	v_mfma_f32_16x16x32_bf16 v[60:63], v[182:185], v[198:201], v[60:63]
	v_mfma_f32_16x16x32_bf16 v[56:59], v[186:189], v[198:201], v[56:59]
	v_mfma_f32_16x16x32_bf16 v[52:55], v[190:193], v[198:201], v[52:55]
	s_nop 0
	global_load_dwordx4 v[132:135], v[132:133], off offset:256
	v_mfma_f32_16x16x32_bf16 v[48:51], v[194:197], v[198:201], v[48:51]
	ds_read_b128 v[250:253], v181 offset:16192
	s_waitcnt lgkmcnt(2)
	v_mfma_f32_16x16x32_bf16 v[44:47], v[182:185], v[242:245], v[44:47]
	s_nop 0
	global_load_dwordx4 v[140:143], v[140:141], off offset:256
	v_mfma_f32_16x16x32_bf16 v[40:43], v[186:189], v[242:245], v[40:43]
	v_mfma_f32_16x16x32_bf16 v[36:39], v[190:193], v[242:245], v[36:39]
	v_mfma_f32_16x16x32_bf16 v[32:35], v[194:197], v[242:245], v[32:35]
	s_waitcnt lgkmcnt(0)
	s_barrier
	s_add_i32 s30, s30, 1
	s_cmp_lg_u32 s30, 16
	s_cbranch_scc0 .Lgm6_exit
	s_and_b32 s98, s30, 1
	s_mul_i32 s98, s98, 0x12000
	v_add3_u32 v181, s98, v170, v180
	v_add3_u32 v202, s98, v171, v180
	ds_read_b128 v[198:201], v181
	ds_read_b128 v[242:245], v181 offset:2304
	v_mfma_f32_16x16x32_bf16 v[28:31], v[182:185], v[246:249], v[28:31]
	v_mfma_f32_16x16x32_bf16 v[12:15], v[182:185], v[250:253], v[12:15]
	ds_read_b128 v[182:185], v202 offset:36864
	v_mfma_f32_16x16x32_bf16 v[24:27], v[186:189], v[246:249], v[24:27]
	v_mfma_f32_16x16x32_bf16 v[8:11], v[186:189], v[250:253], v[8:11]
	ds_read_b128 v[186:189], v202 offset:39168
	v_mfma_f32_16x16x32_bf16 v[20:23], v[190:193], v[246:249], v[20:23]
	v_mfma_f32_16x16x32_bf16 v[4:7], v[190:193], v[250:253], v[4:7]
	ds_read_b128 v[190:193], v202 offset:41472
	v_mfma_f32_16x16x32_bf16 v[16:19], v[194:197], v[246:249], v[16:19]
	v_mfma_f32_16x16x32_bf16 v[0:3], v[194:197], v[250:253], v[0:3]
	ds_read_b128 v[194:197], v202 offset:43776
	s_branch .Lgm6_main
.Lgm6_exit:
	v_mfma_f32_16x16x32_bf16 v[28:31], v[182:185], v[246:249], v[28:31]
	v_mfma_f32_16x16x32_bf16 v[12:15], v[182:185], v[250:253], v[12:15]
	v_mfma_f32_16x16x32_bf16 v[24:27], v[186:189], v[246:249], v[24:27]
	v_mfma_f32_16x16x32_bf16 v[8:11], v[186:189], v[250:253], v[8:11]
	v_mfma_f32_16x16x32_bf16 v[20:23], v[190:193], v[246:249], v[20:23]
	v_mfma_f32_16x16x32_bf16 v[4:7], v[190:193], v[250:253], v[4:7]
	v_mfma_f32_16x16x32_bf16 v[16:19], v[194:197], v[246:249], v[16:19]
	v_mfma_f32_16x16x32_bf16 v[0:3], v[194:197], v[250:253], v[0:3]
	s_nop 7
	s_waitcnt vmcnt(5)
	v_mov_b32_e32 v115, v220
	s_movk_i32 s0, 0xff80
	v_and_b32_e32 v113, 15, v115
	v_ashrrev_i32_e32 v112, 1, v115
	s_waitcnt vmcnt(4)
	v_and_or_b32 v118, v112, s0, v113
	v_add_u32_e32 v116, s29, v118
	s_lshl_b64 s[2:3], s[10:11], 12
	v_cmp_gt_u32_e32 vcc, s22, v116
	v_mov_b32_e32 v112, 0
	v_mov_b32_e32 v114, 0
	s_and_saveexec_b64 s[0:1], vcc
	s_cbranch_execz .LBB0_1052
	s_waitcnt vmcnt(3)
	v_or_b32_e32 v120, s2, v116
	v_mov_b32_e32 v121, s3
	v_lshlrev_b64 v[120:121], 6, v[120:121]
	s_waitcnt vmcnt(1)
	v_lshl_add_u64 v[132:133], s[8:9], 0, v[120:121]
	global_load_dwordx4 v[120:123], v[132:133], off
	global_load_dwordx4 v[124:127], v[132:133], off offset:16
	global_load_dwordx4 v[128:131], v[132:133], off offset:32
	s_nop 0
	global_load_dwordx4 v[132:135], v[132:133], off offset:48
	s_waitcnt vmcnt(3)
	v_mov_b32_e32 v136, v121
	v_mov_b32_e32 v137, v122
	v_mov_b32_e32 v121, v123
	s_waitcnt vmcnt(2)
	v_mov_b32_e32 v122, v125
	v_mov_b32_e32 v123, v126
	v_mov_b32_e32 v125, v127
	v_pk_add_f32 v[120:121], v[136:137], v[120:121]
	v_pk_add_f32 v[122:123], v[122:123], v[124:125]
	v_pk_add_f32 v[120:121], v[120:121], v[120:121] op_sel:[0,1] op_sel_hi:[1,0]
	v_pk_add_f32 v[122:123], v[122:123], v[122:123] op_sel:[0,1] op_sel_hi:[1,0]
	s_waitcnt vmcnt(1)
	v_add_f32_e32 v126, v128, v129
	v_add_f32_e32 v128, v130, v131
	s_waitcnt vmcnt(0)
	v_mov_b32_e32 v127, v134
	v_mov_b32_e32 v129, v135
	v_mov_b32_e32 v121, v132
	v_mov_b32_e32 v123, v133
	v_pk_add_f32 v[124:125], v[126:127], v[128:129]
	v_pk_add_f32 v[120:121], v[120:121], v[122:123]
	s_nop 0
	v_pk_add_f32 v[120:121], v[120:121], v[124:125]
	s_nop 0
	v_add_f32_e32 v114, v120, v121
	v_fmamk_f32 v114, v114, 0x3a800000, v168
	v_mul_f32_e32 v117, 0x4b800000, v114
	v_cmp_gt_f32_e32 vcc, s24, v114
	s_nop 1
	v_cndmask_b32_e32 v114, v114, v117, vcc
	v_rsq_f32_e32 v114, v114
	s_nop 0
	v_mul_f32_e32 v117, 0x45800000, v114
	v_cndmask_b32_e32 v114, v114, v117, vcc

; DI f32x4 mfma16(bf16x8 a, bf16x8 b, f32x4 c) { return __builtin_amdgcn_mfma_f32_16x16x32_bf16(a, b, c, 0, 0, 0); }
; template <int MI, int NJ, bool SWAP, class AP, class BP>
; DI void gemm_main(f32x4 (&acc)[MI][NJ], const AP& ap, int a_kstep, const BP& bp, int b_kstep, int nk, bf16_t* smem) {
;     ...
;   auto gload = [&](int kt) {
;     const bf16_t* ab = ap.base + (size_t)kt * a_kstep; const bf16_t* bb = bp.base + (size_t)kt * b_kstep;
; #pragma unroll
;     for (int i = 0; i < CA; ++i) ra[i] = *(const u32x4*)(ab + pa[i]);
; #pragma unroll
;     for (int i = 0; i < CB; ++i) rb[i] = *(const u32x4*)(bb + pb[i]);
;   };
;   auto sstore = [&](int buf) {
;     bf16_t* As = smem + buf * L::STAGE; bf16_t* Bs = As + L::A_ELEMS;
; #pragma unroll
;     for (int i = 0; i < CA; ++i) { const int c = tid + NTHR * i; *(u32x4*)(As + (c >> 3) * LDT + (c & 7) * 8) = oka[i] ? ra[i] : (u32x4){0u, 0u, 0u, 0u}; }
; #pragma unroll
;     for (int i = 0; i < CB; ++i) { const int c = tid + NTHR * i; *(u32x4*)(Bs + (c >> 3) * LDT + (c & 7) * 8) = rb[i]; }
;   };
;   gload(0); sstore(0); gload(nk > 1 ? 1 : 0); __syncthreads();
; #pragma unroll 1
;   for (int kt = 0; kt < nk; ++kt) {
;     const int buf = kt & 1;
;     sstore(buf ^ 1);
;     gload(kt + 2 < nk ? kt + 2 : nk - 1);
;     __builtin_amdgcn_sched_barrier(0);
;     const bf16_t* As = smem + buf * L::STAGE + (wm * 16 * MI + l15) * LDT + quad * 8;
;     const bf16_t* Bs = smem + buf * L::STAGE + L::A_ELEMS + (wn * 16 * NJ + l15) * LDT + quad * 8;
; #pragma unroll
;     for (int ks = 0; ks < 2; ++ks) {
;       if (MI * NJ >= 32 && ks == 1) asm volatile("" ::: "memory");
;       bf16x8 b[NJ];
; #pragma unroll
;       for (int j = 0; j < NJ; ++j) b[j] = *(const bf16x8*)(Bs + j * 16 * LDT + ks * 32);
; #pragma unroll
;       for (int i = 0; i < MI; ++i) {
;         const bf16x8 a = *(const bf16x8*)(As + i * 16 * LDT + ks * 32);
; #pragma unroll
;         for (int j = 0; j < NJ; ++j) acc[i][j] = SWAP ? mfma16(b[j], a, acc[i][j]) : mfma16(a, b[j], acc[i][j]);
;       }
;     }
;     __syncthreads();
;   }
.Lgm7_main:
	ds_read_b128 v[242:245], v177 offset:4608
	s_waitcnt lgkmcnt(4)
	v_mfma_f32_16x16x32_bf16 v[156:159], v[178:181], v[194:197], v[156:159]
	s_waitcnt lgkmcnt(3)
	v_mfma_f32_16x16x32_bf16 v[152:155], v[182:185], v[194:197], v[152:155]
	s_waitcnt lgkmcnt(2)
	v_mfma_f32_16x16x32_bf16 v[148:151], v[186:189], v[194:197], v[148:151]
	s_waitcnt lgkmcnt(1)
	v_mfma_f32_16x16x32_bf16 v[144:147], v[190:193], v[194:197], v[144:147]
	s_and_b32 s24, s21, 1
	s_min_u32 s22, s21, 41
	s_xor_b32 s23, s24, 1
	s_lshl_b32 s25, s22, 7
	s_mul_i32 s23, s23, 0x12000
	s_add_u32 s22, s6, s25
	v_add3_u32 v250, s23, v172, v170
	v_add3_u32 v251, s23, v173, v170
	v_add3_u32 v252, s23, v174, v170
	v_add3_u32 v253, s23, v175, v170
	s_addc_u32 s23, s7, 0
	s_waitcnt vmcnt(7)
	ds_write_b128 v250, v[112:115]
	ds_read_b128 v[246:249], v177 offset:6912
	v_mfma_f32_16x16x32_bf16 v[108:111], v[178:181], v[198:201], v[108:111]
	v_mfma_f32_16x16x32_bf16 v[104:107], v[182:185], v[198:201], v[104:107]
	v_mfma_f32_16x16x32_bf16 v[100:103], v[186:189], v[198:201], v[100:103]
	v_mfma_f32_16x16x32_bf16 v[96:99], v[190:193], v[198:201], v[96:99]
	s_waitcnt vmcnt(6)
	ds_write_b128 v251, v[116:119]
	ds_read_b128 v[194:197], v177 offset:9216
	s_waitcnt lgkmcnt(4)
	v_mfma_f32_16x16x32_bf16 v[92:95], v[178:181], v[242:245], v[92:95]
	v_mfma_f32_16x16x32_bf16 v[88:91], v[182:185], v[242:245], v[88:91]
	v_mfma_f32_16x16x32_bf16 v[84:87], v[186:189], v[242:245], v[84:87]
	v_mfma_f32_16x16x32_bf16 v[80:83], v[190:193], v[242:245], v[80:83]
	ds_read_b128 v[198:201], v177 offset:11520
	s_waitcnt lgkmcnt(3)
	v_mfma_f32_16x16x32_bf16 v[76:79], v[178:181], v[246:249], v[76:79]
	s_waitcnt vmcnt(5)
	ds_write_b128 v252, v[120:123]
	v_mfma_f32_16x16x32_bf16 v[72:75], v[182:185], v[246:249], v[72:75]
	v_mfma_f32_16x16x32_bf16 v[68:71], v[186:189], v[246:249], v[68:71]
	v_mfma_f32_16x16x32_bf16 v[64:67], v[190:193], v[246:249], v[64:67]
	ds_read_b128 v[242:245], v177 offset:13824
	s_waitcnt lgkmcnt(3)
	v_mfma_f32_16x16x32_bf16 v[60:63], v[178:181], v[194:197], v[60:63]
	s_waitcnt vmcnt(4)
	ds_write_b128 v253, v[124:127]
	v_mfma_f32_16x16x32_bf16 v[56:59], v[182:185], v[194:197], v[56:59]
	v_mfma_f32_16x16x32_bf16 v[52:55], v[186:189], v[194:197], v[52:55]
	v_mfma_f32_16x16x32_bf16 v[48:51], v[190:193], v[194:197], v[48:51]
	ds_read_b128 v[246:249], v177 offset:16128
	s_waitcnt lgkmcnt(4)
	v_mfma_f32_16x16x32_bf16 v[44:47], v[178:181], v[198:201], v[44:47]
	s_waitcnt vmcnt(3)
	ds_write_b128 v250, v[128:131] offset:36864
	v_mfma_f32_16x16x32_bf16 v[40:43], v[182:185], v[198:201], v[40:43]
	v_mfma_f32_16x16x32_bf16 v[36:39], v[186:189], v[198:201], v[36:39]
	v_mfma_f32_16x16x32_bf16 v[32:35], v[190:193], v[198:201], v[32:35]
	ds_read_b128 v[194:197], v177 offset:64
	s_waitcnt lgkmcnt(4)
	v_mfma_f32_16x16x32_bf16 v[28:31], v[178:181], v[242:245], v[28:31]
	s_waitcnt vmcnt(2)
	ds_write_b128 v251, v[132:135] offset:36864
	v_mfma_f32_16x16x32_bf16 v[24:27], v[182:185], v[242:245], v[24:27]
	v_mfma_f32_16x16x32_bf16 v[20:23], v[186:189], v[242:245], v[20:23]
	v_mfma_f32_16x16x32_bf16 v[16:19], v[190:193], v[242:245], v[16:19]
	ds_read_b128 v[198:201], v177 offset:2368
	s_waitcnt lgkmcnt(4)
	v_mfma_f32_16x16x32_bf16 v[8:11], v[178:181], v[246:249], v[8:11]
	ds_read_b128 v[178:181], v202 offset:36928
	s_waitcnt vmcnt(1)
	ds_write_b128 v252, v[136:139] offset:36864
	v_mfma_f32_16x16x32_bf16 v[4:7], v[182:185], v[246:249], v[4:7]
	ds_read_b128 v[182:185], v202 offset:39232
	v_mfma_f32_16x16x32_bf16 v[0:3], v[186:189], v[246:249], v[0:3]
	ds_read_b128 v[186:189], v202 offset:41536
	v_mfma_f32_16x16x32_bf16 v[12:15], v[190:193], v[246:249], v[12:15]
	ds_read_b128 v[190:193], v202 offset:43840
	ds_read_b128 v[242:245], v177 offset:4672
	s_waitcnt lgkmcnt(5)
	v_mfma_f32_16x16x32_bf16 v[156:159], v[178:181], v[194:197], v[156:159]
	s_waitcnt lgkmcnt(3)
	v_mfma_f32_16x16x32_bf16 v[152:155], v[182:185], v[194:197], v[152:155]
	s_waitcnt vmcnt(0)
	ds_write_b128 v253, v[140:143] offset:36864
	s_waitcnt lgkmcnt(3)
	v_mfma_f32_16x16x32_bf16 v[148:151], v[186:189], v[194:197], v[148:151]
	s_waitcnt lgkmcnt(2)
	v_mfma_f32_16x16x32_bf16 v[144:147], v[190:193], v[194:197], v[144:147]
	v_lshl_add_u64 v[112:113], s[22:23], 0, v[162:163]
	v_lshl_add_u64 v[116:117], s[22:23], 0, v[164:165]
	v_lshl_add_u64 v[120:121], s[22:23], 0, v[166:167]
	v_lshl_add_u64 v[124:125], s[22:23], 0, v[168:169]
	s_add_u32 s22, s8, s25
	s_addc_u32 s23, s9, 0
	v_lshl_add_u64 v[128:129], s[22:23], 0, v[162:163]
	v_lshl_add_u64 v[132:133], s[22:23], 0, v[164:165]
	v_lshl_add_u64 v[136:137], s[22:23], 0, v[166:167]
	v_lshl_add_u64 v[140:141], s[22:23], 0, v[168:169]
	global_load_dwordx4 v[112:115], v[112:113], off offset:256
	ds_read_b128 v[246:249], v177 offset:6976
	v_mfma_f32_16x16x32_bf16 v[108:111], v[178:181], v[198:201], v[108:111]
	v_mfma_f32_16x16x32_bf16 v[104:107], v[182:185], v[198:201], v[104:107]
	s_nop 0
	global_load_dwordx4 v[116:119], v[116:117], off offset:256
	v_mfma_f32_16x16x32_bf16 v[100:103], v[186:189], v[198:201], v[100:103]
	v_mfma_f32_16x16x32_bf16 v[96:99], v[190:193], v[198:201], v[96:99]
	ds_read_b128 v[194:197], v177 offset:9280
	s_waitcnt lgkmcnt(3)
	v_mfma_f32_16x16x32_bf16 v[92:95], v[178:181], v[242:245], v[92:95]
	s_nop 0
	global_load_dwordx4 v[120:123], v[120:121], off offset:256
	v_mfma_f32_16x16x32_bf16 v[88:91], v[182:185], v[242:245], v[88:91]
	v_mfma_f32_16x16x32_bf16 v[84:87], v[186:189], v[242:245], v[84:87]
	s_nop 0
	global_load_dwordx4 v[124:127], v[124:125], off offset:256
	v_mfma_f32_16x16x32_bf16 v[80:83], v[190:193], v[242:245], v[80:83]
	ds_read_b128 v[198:201], v177 offset:11584
	s_waitcnt lgkmcnt(2)
	v_mfma_f32_16x16x32_bf16 v[76:79], v[178:181], v[246:249], v[76:79]
	v_mfma_f32_16x16x32_bf16 v[72:75], v[182:185], v[246:249], v[72:75]
	s_nop 0
	global_load_dwordx4 v[128:131], v[128:129], off offset:256
	v_mfma_f32_16x16x32_bf16 v[68:71], v[186:189], v[246:249], v[68:71]
	v_mfma_f32_16x16x32_bf16 v[64:67], v[190:193], v[246:249], v[64:67]
	s_nop 0
	global_load_dwordx4 v[132:135], v[132:133], off offset:256
	ds_read_b128 v[242:245], v177 offset:13888
	s_waitcnt lgkmcnt(2)
	v_mfma_f32_16x16x32_bf16 v[60:63], v[178:181], v[194:197], v[60:63]
	v_mfma_f32_16x16x32_bf16 v[56:59], v[182:185], v[194:197], v[56:59]
	v_mfma_f32_16x16x32_bf16 v[52:55], v[186:189], v[194:197], v[52:55]
	s_nop 0
	global_load_dwordx4 v[136:139], v[136:137], off offset:256
	v_mfma_f32_16x16x32_bf16 v[48:51], v[190:193], v[194:197], v[48:51]
	ds_read_b128 v[246:249], v177 offset:16192
	s_waitcnt lgkmcnt(2)
	v_mfma_f32_16x16x32_bf16 v[44:47], v[178:181], v[198:201], v[44:47]
	s_nop 0
	global_load_dwordx4 v[140:143], v[140:141], off offset:256
	v_mfma_f32_16x16x32_bf16 v[40:43], v[182:185], v[198:201], v[40:43]
	v_mfma_f32_16x16x32_bf16 v[36:39], v[186:189], v[198:201], v[36:39]
	v_mfma_f32_16x16x32_bf16 v[32:35], v[190:193], v[198:201], v[32:35]
	s_waitcnt lgkmcnt(0)
	s_barrier
; DI f32x4 mfma16(bf16x8 a, bf16x8 b, f32x4 c) { return __builtin_amdgcn_mfma_f32_16x16x32_bf16(a, b, c, 0, 0, 0); }
; template <int MI, int NJ, bool SWAP, class AP, class BP>
; DI void gemm_main(f32x4 (&acc)[MI][NJ], const AP& ap, int a_kstep, const BP& bp, int b_kstep, int nk, bf16_t* smem) {
;     ...
;   for (int kt = 0; kt < nk; ++kt) {
;     const int buf = kt & 1;
;     sstore(buf ^ 1);
;     gload(kt + 2 < nk ? kt + 2 : nk - 1);
;     __builtin_amdgcn_sched_barrier(0);
;     const bf16_t* As = smem + buf * L::STAGE + (wm * 16 * MI + l15) * LDT + quad * 8;
;     const bf16_t* Bs = smem + buf * L::STAGE + L::A_ELEMS + (wn * 16 * NJ + l15) * LDT + quad * 8;
; #pragma unroll
;     for (int ks = 0; ks < 2; ++ks) {
;       if (MI * NJ >= 32 && ks == 1) asm volatile("" ::: "memory");
;       bf16x8 b[NJ];
; #pragma unroll
;       for (int j = 0; j < NJ; ++j) b[j] = *(const bf16x8*)(Bs + j * 16 * LDT + ks * 32);
; #pragma unroll
;       for (int i = 0; i < MI; ++i) {
;         const bf16x8 a = *(const bf16x8*)(As + i * 16 * LDT + ks * 32);
; #pragma unroll
;         for (int j = 0; j < NJ; ++j) acc[i][j] = SWAP ? mfma16(b[j], a, acc[i][j]) : mfma16(a, b[j], acc[i][j]);
	s_add_i32 s21, s21, 1
	s_cmp_lg_u32 s21, 44
	s_cbranch_scc0 .Lgm7_exit
	s_and_b32 s98, s21, 1
	s_mul_i32 s98, s98, 0x12000
	v_add3_u32 v202, s98, v160, v176
	v_add3_u32 v177, s98, v171, v176
	ds_read_b128 v[194:197], v177
	ds_read_b128 v[198:201], v177 offset:2304
	v_mfma_f32_16x16x32_bf16 v[28:31], v[178:181], v[242:245], v[28:31]
	v_mfma_f32_16x16x32_bf16 v[8:11], v[178:181], v[246:249], v[8:11]
	ds_read_b128 v[178:181], v202 offset:36864
	v_mfma_f32_16x16x32_bf16 v[24:27], v[182:185], v[242:245], v[24:27]
	v_mfma_f32_16x16x32_bf16 v[4:7], v[182:185], v[246:249], v[4:7]
	ds_read_b128 v[182:185], v202 offset:39168
	v_mfma_f32_16x16x32_bf16 v[20:23], v[186:189], v[242:245], v[20:23]
	v_mfma_f32_16x16x32_bf16 v[0:3], v[186:189], v[246:249], v[0:3]
	ds_read_b128 v[186:189], v202 offset:41472
	v_mfma_f32_16x16x32_bf16 v[16:19], v[190:193], v[242:245], v[16:19]
	v_mfma_f32_16x16x32_bf16 v[12:15], v[190:193], v[246:249], v[12:15]
	ds_read_b128 v[190:193], v202 offset:43776
	s_branch .Lgm7_main

; DI f32x4 mfma16(bf16x8 a, bf16x8 b, f32x4 c) { return __builtin_amdgcn_mfma_f32_16x16x32_bf16(a, b, c, 0, 0, 0); }
; template <int MI, int NJ, bool SWAP, class AP, class BP>
; DI void gemm_main(f32x4 (&acc)[MI][NJ], const AP& ap, int a_kstep, const BP& bp, int b_kstep, int nk, bf16_t* smem) {
;     ...
;   auto gload = [&](int kt) {
;     const bf16_t* ab = ap.base + (size_t)kt * a_kstep; const bf16_t* bb = bp.base + (size_t)kt * b_kstep;
; #pragma unroll
;     for (int i = 0; i < CA; ++i) ra[i] = *(const u32x4*)(ab + pa[i]);
; #pragma unroll
;     for (int i = 0; i < CB; ++i) rb[i] = *(const u32x4*)(bb + pb[i]);
;   };
;   auto sstore = [&](int buf) {
;     bf16_t* As = smem + buf * L::STAGE; bf16_t* Bs = As + L::A_ELEMS;
; #pragma unroll
;     for (int i = 0; i < CA; ++i) { const int c = tid + NTHR * i; *(u32x4*)(As + (c >> 3) * LDT + (c & 7) * 8) = oka[i] ? ra[i] : (u32x4){0u, 0u, 0u, 0u}; }
; #pragma unroll
;     for (int i = 0; i < CB; ++i) { const int c = tid + NTHR * i; *(u32x4*)(Bs + (c >> 3) * LDT + (c & 7) * 8) = rb[i]; }
;   };
;   gload(0); sstore(0); gload(nk > 1 ? 1 : 0); __syncthreads();
; #pragma unroll 1
;   for (int kt = 0; kt < nk; ++kt) {
;     const int buf = kt & 1;
;     sstore(buf ^ 1);
;     gload(kt + 2 < nk ? kt + 2 : nk - 1);
;     __builtin_amdgcn_sched_barrier(0);
;     const bf16_t* As = smem + buf * L::STAGE + (wm * 16 * MI + l15) * LDT + quad * 8;
;     const bf16_t* Bs = smem + buf * L::STAGE + L::A_ELEMS + (wn * 16 * NJ + l15) * LDT + quad * 8;
; #pragma unroll
;     for (int ks = 0; ks < 2; ++ks) {
;       if (MI * NJ >= 32 && ks == 1) asm volatile("" ::: "memory");
;       bf16x8 b[NJ];
; #pragma unroll
;       for (int j = 0; j < NJ; ++j) b[j] = *(const bf16x8*)(Bs + j * 16 * LDT + ks * 32);
; #pragma unroll
;       for (int i = 0; i < MI; ++i) {
;         const bf16x8 a = *(const bf16x8*)(As + i * 16 * LDT + ks * 32);
; #pragma unroll
;         for (int j = 0; j < NJ; ++j) acc[i][j] = SWAP ? mfma16(b[j], a, acc[i][j]) : mfma16(a, b[j], acc[i][j]);
;       }
;     }
;     __syncthreads();
;   }
.LBB0_1208:
	s_and_b32 s98, s4, 1
	s_mul_i32 s98, s98, 0x12000
	v_add3_u32 v210, s98, v184, v186
	v_add3_u32 v211, s98, v160, v186
	ds_read_b128 v[206:209], v210
	ds_read_b128 v[242:245], v210 offset:2304
	ds_read_b128 v[190:193], v211 offset:36864
	ds_read_b128 v[194:197], v211 offset:39168
	ds_read_b128 v[198:201], v211 offset:41472
	ds_read_b128 v[202:205], v211 offset:43776
.Lgm8_main:
	ds_read_b128 v[246:249], v210 offset:4608
	s_waitcnt lgkmcnt(4)
	v_mfma_f32_16x16x32_bf16 v[124:127], v[190:193], v[206:209], v[124:127]
	s_waitcnt lgkmcnt(3)
	v_mfma_f32_16x16x32_bf16 v[120:123], v[194:197], v[206:209], v[120:123]
	s_waitcnt lgkmcnt(2)
	v_mfma_f32_16x16x32_bf16 v[116:119], v[198:201], v[206:209], v[116:119]
	s_waitcnt lgkmcnt(1)
	v_mfma_f32_16x16x32_bf16 v[112:115], v[202:205], v[206:209], v[112:115]
	s_and_b32 s5, s4, 1
	s_xor_b32 s23, s5, 1
	s_mul_i32 s23, s23, 0x12000
	v_add3_u32 v254, s23, v185, v183
	s_waitcnt vmcnt(7)
	ds_write_b128 v254, v[128:131]
	ds_read_b128 v[250:253], v210 offset:6912
	v_mfma_f32_16x16x32_bf16 v[108:111], v[190:193], v[242:245], v[108:111]
	v_mfma_f32_16x16x32_bf16 v[104:107], v[194:197], v[242:245], v[104:107]
	v_mfma_f32_16x16x32_bf16 v[100:103], v[198:201], v[242:245], v[100:103]
	v_mfma_f32_16x16x32_bf16 v[96:99], v[202:205], v[242:245], v[96:99]
	v_add3_u32 v128, s23, v187, v183
	v_add3_u32 v129, s23, v188, v183
	v_add3_u32 v130, s23, v189, v183
	s_min_u32 s23, s4, 13
	s_lshl_b32 s23, s23, 7
	s_add_u32 s26, s0, s23
	s_addc_u32 s27, s1, 0
	s_waitcnt vmcnt(6)
	ds_write_b128 v128, v[132:135]
	ds_read_b128 v[206:209], v210 offset:9216
	s_waitcnt lgkmcnt(4)
	v_mfma_f32_16x16x32_bf16 v[92:95], v[190:193], v[246:249], v[92:95]
	v_mfma_f32_16x16x32_bf16 v[88:91], v[194:197], v[246:249], v[88:91]
	v_mfma_f32_16x16x32_bf16 v[84:87], v[198:201], v[246:249], v[84:87]
	v_mfma_f32_16x16x32_bf16 v[80:83], v[202:205], v[246:249], v[80:83]
	ds_read_b128 v[242:245], v210 offset:11520
	s_waitcnt lgkmcnt(3)
	v_mfma_f32_16x16x32_bf16 v[76:79], v[190:193], v[250:253], v[76:79]
	s_waitcnt vmcnt(5)
	ds_write_b128 v129, v[136:139]
	v_mfma_f32_16x16x32_bf16 v[72:75], v[194:197], v[250:253], v[72:75]
	v_mfma_f32_16x16x32_bf16 v[68:71], v[198:201], v[250:253], v[68:71]
	v_mfma_f32_16x16x32_bf16 v[64:67], v[202:205], v[250:253], v[64:67]
	ds_read_b128 v[246:249], v210 offset:13824
	s_waitcnt lgkmcnt(3)
	v_mfma_f32_16x16x32_bf16 v[60:63], v[190:193], v[206:209], v[60:63]
	s_waitcnt vmcnt(4)
	ds_write_b128 v130, v[140:143]
	v_mfma_f32_16x16x32_bf16 v[56:59], v[194:197], v[206:209], v[56:59]
	v_mfma_f32_16x16x32_bf16 v[52:55], v[198:201], v[206:209], v[52:55]
	v_mfma_f32_16x16x32_bf16 v[48:51], v[202:205], v[206:209], v[48:51]
	ds_read_b128 v[250:253], v210 offset:16128
	s_waitcnt lgkmcnt(4)
	v_mfma_f32_16x16x32_bf16 v[44:47], v[190:193], v[242:245], v[44:47]
	s_waitcnt vmcnt(3)
	ds_write_b128 v254, v[144:147] offset:36864
	v_mfma_f32_16x16x32_bf16 v[40:43], v[194:197], v[242:245], v[40:43]
	v_mfma_f32_16x16x32_bf16 v[36:39], v[198:201], v[242:245], v[36:39]
	v_mfma_f32_16x16x32_bf16 v[32:35], v[202:205], v[242:245], v[32:35]
	ds_read_b128 v[206:209], v210 offset:64
	s_waitcnt lgkmcnt(4)
	v_mfma_f32_16x16x32_bf16 v[28:31], v[190:193], v[246:249], v[28:31]
	s_waitcnt vmcnt(2)
	ds_write_b128 v128, v[148:151] offset:36864
	v_mfma_f32_16x16x32_bf16 v[24:27], v[194:197], v[246:249], v[24:27]
	v_mfma_f32_16x16x32_bf16 v[20:23], v[198:201], v[246:249], v[20:23]
	v_mfma_f32_16x16x32_bf16 v[16:19], v[202:205], v[246:249], v[16:19]
	ds_read_b128 v[242:245], v210 offset:2368
	s_waitcnt lgkmcnt(4)
	v_mfma_f32_16x16x32_bf16 v[12:15], v[190:193], v[250:253], v[12:15]
	ds_read_b128 v[190:193], v211 offset:36928
	s_waitcnt vmcnt(1)
	ds_write_b128 v129, v[152:155] offset:36864
	v_mfma_f32_16x16x32_bf16 v[8:11], v[194:197], v[250:253], v[8:11]
	ds_read_b128 v[194:197], v211 offset:39232
	v_mfma_f32_16x16x32_bf16 v[4:7], v[198:201], v[250:253], v[4:7]
	ds_read_b128 v[198:201], v211 offset:41536
	v_mfma_f32_16x16x32_bf16 v[0:3], v[202:205], v[250:253], v[0:3]
	ds_read_b128 v[202:205], v211 offset:43840
	ds_read_b128 v[246:249], v210 offset:4672
	s_waitcnt lgkmcnt(5)
	v_mfma_f32_16x16x32_bf16 v[124:127], v[190:193], v[206:209], v[124:127]
	s_waitcnt lgkmcnt(3)
	v_mfma_f32_16x16x32_bf16 v[120:123], v[194:197], v[206:209], v[120:123]
	s_waitcnt vmcnt(0)
	ds_write_b128 v130, v[156:159] offset:36864
	s_waitcnt lgkmcnt(3)
	v_mfma_f32_16x16x32_bf16 v[116:119], v[198:201], v[206:209], v[116:119]
	s_waitcnt lgkmcnt(2)
	v_mfma_f32_16x16x32_bf16 v[112:115], v[202:205], v[206:209], v[112:115]
	v_lshl_add_u64 v[128:129], s[26:27], 0, v[162:163]
	v_lshl_add_u64 v[132:133], s[26:27], 0, v[164:165]
	v_lshl_add_u64 v[136:137], s[26:27], 0, v[166:167]
	v_lshl_add_u64 v[140:141], s[26:27], 0, v[168:169]
	s_add_u32 s26, s2, s23
	s_addc_u32 s27, s3, 0
	v_lshl_add_u64 v[144:145], s[26:27], 0, v[162:163]
	v_lshl_add_u64 v[148:149], s[26:27], 0, v[164:165]
	v_lshl_add_u64 v[152:153], s[26:27], 0, v[166:167]
	v_lshl_add_u64 v[156:157], s[26:27], 0, v[168:169]
	global_load_dwordx4 v[128:131], v[128:129], off offset:256
	ds_read_b128 v[250:253], v210 offset:6976
	v_mfma_f32_16x16x32_bf16 v[108:111], v[190:193], v[242:245], v[108:111]
	v_mfma_f32_16x16x32_bf16 v[104:107], v[194:197], v[242:245], v[104:107]
	s_nop 0
	global_load_dwordx4 v[132:135], v[132:133], off offset:256
	v_mfma_f32_16x16x32_bf16 v[100:103], v[198:201], v[242:245], v[100:103]
	v_mfma_f32_16x16x32_bf16 v[96:99], v[202:205], v[242:245], v[96:99]
	ds_read_b128 v[206:209], v210 offset:9280
	s_waitcnt lgkmcnt(3)
; DI float sigmoidf_(float x) { return 1.f / (1.f + __expf(-x)); }
; template <int MI, int NJ, bool SWAP, class AP, class BP>
; DI void gemm_main(f32x4 (&acc)[MI][NJ], const AP& ap, int a_kstep, const BP& bp, int b_kstep, int nk, bf16_t* smem) {
;     ...
;     for (int ks = 0; ks < 2; ++ks) {
;       if (MI * NJ >= 32 && ks == 1) asm volatile("" ::: "memory");
;       bf16x8 b[NJ];
; #pragma unroll
;       for (int j = 0; j < NJ; ++j) b[j] = *(const bf16x8*)(Bs + j * 16 * LDT + ks * 32);
; #pragma unroll
;       for (int i = 0; i < MI; ++i) {
;         const bf16x8 a = *(const bf16x8*)(As + i * 16 * LDT + ks * 32);
; #pragma unroll
;         for (int j = 0; j < NJ; ++j) acc[i][j] = SWAP ? mfma16(b[j], a, acc[i][j]) : mfma16(a, b[j], acc[i][j]);
;       }
;     }
;     __syncthreads();
;   }
; template <bool SWAP> DI void inproj_tile(const Params& p, int layer, int tm, int tn, bf16_t* smem) {
;     ...
;     const int slab = tn * 4 + wn;
;     if (slab == 54) {
; #pragma unroll
;       for (int i = 0; i < 8; ++i) {
;         const int t = trow0 + i * 16 + l15; const float rs = rstd_from16(ssq + (size_t)t * 16, 1.f / 1024.f);
;         float* gt = (float*)(p.ws + O_GATES) + (size_t)t * 24; float* lf = (float*)(p.ws + O_LOGF) + (size_t)t * 8;
; #pragma unroll
;         for (int r = 0; r < 4; ++r) gt[quad * 4 + r] = sigmoidf_(acc[i][0][r] * rs);
;         if (quad < 2) {
; #pragma unroll
;           for (int r = 0; r < 4; ++r) gt[16 + quad * 4 + r] = sigmoidf_(acc[i][1][r] * rs);
;         } else {
; #pragma unroll
;           for (int r = 0; r < 4; ++r) { const int h = (quad - 2) * 4 + r; const float xx = acc[i][1][r] * rs + p.b_forget[layer * 8 + h]; lf[h] = fminf(xx, 0.f) - log1pf(__expf(-fabsf(xx))); }
;         }
;         const float* rp = (const float*)(p.ws + O_ROPE16) + (size_t)t * 32 + quad * 8; float o1[4], o2[4];
; #pragma unroll
;         for (int r = 0; r < 4; ++r) { const float cs = rp[2 * r], sn = rp[2 * r + 1], x1 = acc[i][2][r] * rs, x2 = acc[i][3][r] * rs; o1[r] = x1 * cs - x2 * sn; o2[r] = x2 * cs + x1 * sn; }
;         bf16_t* kp = (bf16_t*)(p.ws + O_MLAKPE) + (size_t)t * 32 + quad * 4;
;         *(u32x2*)kp = (u32x2){pk2(o1[0], o1[1]), pk2(o1[2], o1[3])}; *(u32x2*)(kp + 16) = (u32x2){pk2(o2[0], o2[1]), pk2(o2[2], o2[3])};
;       }
;     } else if (slab != 55) {
;       bf16_t* dbuf; int dld, dcol, kind = 0; float qs = 1.f; int cslot = 0;
	v_mfma_f32_16x16x32_bf16 v[92:95], v[190:193], v[246:249], v[92:95]
	s_nop 0
	global_load_dwordx4 v[136:139], v[136:137], off offset:256
	v_mfma_f32_16x16x32_bf16 v[88:91], v[194:197], v[246:249], v[88:91]
	v_mfma_f32_16x16x32_bf16 v[84:87], v[198:201], v[246:249], v[84:87]
	s_nop 0
	global_load_dwordx4 v[140:143], v[140:141], off offset:256
	v_mfma_f32_16x16x32_bf16 v[80:83], v[202:205], v[246:249], v[80:83]
	ds_read_b128 v[242:245], v210 offset:11584
	s_waitcnt lgkmcnt(2)
	v_mfma_f32_16x16x32_bf16 v[76:79], v[190:193], v[250:253], v[76:79]
	v_mfma_f32_16x16x32_bf16 v[72:75], v[194:197], v[250:253], v[72:75]
	s_nop 0
	global_load_dwordx4 v[144:147], v[144:145], off offset:256
	v_mfma_f32_16x16x32_bf16 v[68:71], v[198:201], v[250:253], v[68:71]
	v_mfma_f32_16x16x32_bf16 v[64:67], v[202:205], v[250:253], v[64:67]
	s_nop 0
	global_load_dwordx4 v[148:151], v[148:149], off offset:256
	ds_read_b128 v[246:249], v210 offset:13888
	s_waitcnt lgkmcnt(2)
	v_mfma_f32_16x16x32_bf16 v[60:63], v[190:193], v[206:209], v[60:63]
	v_mfma_f32_16x16x32_bf16 v[56:59], v[194:197], v[206:209], v[56:59]
	v_mfma_f32_16x16x32_bf16 v[52:55], v[198:201], v[206:209], v[52:55]
	s_nop 0
	global_load_dwordx4 v[152:155], v[152:153], off offset:256
	v_mfma_f32_16x16x32_bf16 v[48:51], v[202:205], v[206:209], v[48:51]
	ds_read_b128 v[250:253], v210 offset:16192
	s_waitcnt lgkmcnt(2)
	v_mfma_f32_16x16x32_bf16 v[44:47], v[190:193], v[242:245], v[44:47]
	s_nop 0
	global_load_dwordx4 v[156:159], v[156:157], off offset:256
	v_mfma_f32_16x16x32_bf16 v[40:43], v[194:197], v[242:245], v[40:43]
	v_mfma_f32_16x16x32_bf16 v[36:39], v[198:201], v[242:245], v[36:39]
	v_mfma_f32_16x16x32_bf16 v[32:35], v[202:205], v[242:245], v[32:35]
	s_waitcnt lgkmcnt(0)
	s_barrier
	s_add_i32 s4, s4, 1
	s_cmp_lg_u32 s4, 16
	s_cbranch_scc0 .Lgm8_exit
	s_and_b32 s98, s4, 1
	s_mul_i32 s98, s98, 0x12000
	v_add3_u32 v210, s98, v184, v186
	v_add3_u32 v211, s98, v160, v186
	ds_read_b128 v[206:209], v210
	ds_read_b128 v[242:245], v210 offset:2304
	v_mfma_f32_16x16x32_bf16 v[28:31], v[190:193], v[246:249], v[28:31]
	v_mfma_f32_16x16x32_bf16 v[12:15], v[190:193], v[250:253], v[12:15]
	ds_read_b128 v[190:193], v211 offset:36864
	v_mfma_f32_16x16x32_bf16 v[24:27], v[194:197], v[246:249], v[24:27]
	v_mfma_f32_16x16x32_bf16 v[8:11], v[194:197], v[250:253], v[8:11]
	ds_read_b128 v[194:197], v211 offset:39168
	v_mfma_f32_16x16x32_bf16 v[20:23], v[198:201], v[246:249], v[20:23]
	v_mfma_f32_16x16x32_bf16 v[4:7], v[198:201], v[250:253], v[4:7]
	ds_read_b128 v[198:201], v211 offset:41472
	v_mfma_f32_16x16x32_bf16 v[16:19], v[202:205], v[246:249], v[16:19]
	v_mfma_f32_16x16x32_bf16 v[0:3], v[202:205], v[250:253], v[0:3]
	ds_read_b128 v[202:205], v211 offset:43776
	s_branch .Lgm8_main
.Lgm8_exit:
	v_mfma_f32_16x16x32_bf16 v[28:31], v[190:193], v[246:249], v[28:31]
	v_mfma_f32_16x16x32_bf16 v[12:15], v[190:193], v[250:253], v[12:15]
	v_mfma_f32_16x16x32_bf16 v[24:27], v[194:197], v[246:249], v[24:27]
	v_mfma_f32_16x16x32_bf16 v[8:11], v[194:197], v[250:253], v[8:11]
	v_mfma_f32_16x16x32_bf16 v[20:23], v[198:201], v[246:249], v[20:23]
	v_mfma_f32_16x16x32_bf16 v[4:7], v[198:201], v[250:253], v[4:7]
	v_mfma_f32_16x16x32_bf16 v[16:19], v[202:205], v[246:249], v[16:19]
	v_mfma_f32_16x16x32_bf16 v[0:3], v[202:205], v[250:253], v[0:3]
	s_nop 7
	s_waitcnt vmcnt(7)
	v_mov_b32_e32 v128, v220
	v_mov_b32_e32 v131, v220
	s_lshl_b32 s25, s22, 2
	s_waitcnt vmcnt(6)
	v_ashrrev_i32_e32 v133, 6, v131
	s_waitcnt vmcnt(5)
	v_and_or_b32 v136, v133, 3, s25
	v_cmp_lt_i32_e32 vcc, 54, v136
	s_mov_b64 s[4:5], 0
	s_mov_b64 s[0:1], 0
	s_and_saveexec_b64 s[2:3], vcc
	s_xor_b64 s[2:3], exec, s[2:3]
	v_cmp_ne_u32_e32 vcc, 55, v136
	s_and_b64 s[0:1], vcc, exec
	s_andn2_saveexec_b64 s[2:3], s[2:3]
	v_cmp_ne_u32_e32 vcc, 54, v136
	s_andn2_b64 s[0:1], s[0:1], exec
	s_and_b64 s[4:5], vcc, exec
	s_or_b64 s[0:1], s[0:1], s[4:5]
	s_mov_b64 s[4:5], exec
	s_or_b64 exec, exec, s[2:3]
	s_waitcnt vmcnt(3)
	v_and_b32_e32 v145, 63, v128
	v_and_b32_e32 v146, 15, v128
	v_bfe_u32 v144, v128, 4, 2
	v_ashrrev_i32_e32 v128, 1, v131
	v_and_b32_e32 v128, 0xffffff80, v128
	v_lshl_add_u32 v147, s24, 8, v128
	s_and_saveexec_b64 s[26:27], s[0:1]
	s_cbranch_execz .LBB0_1294
	v_cmp_lt_i32_e32 vcc, 7, v136
	s_and_saveexec_b64 s[0:1], vcc
	s_xor_b64 s[0:1], exec, s[0:1]
	s_cbranch_execz .LBB0_1235
	s_cmp_gt_u32 s25, 11
	s_mov_b64 s[30:31], -1
	s_cbranch_scc0 .LBB0_1232
	s_cmp_gt_u32 s25, 15
	s_mov_b64 s[2:3], -1
	s_cbranch_scc0 .LBB0_1230
	s_cmp_gt_u32 s25, 27
	s_cbranch_scc0 .LBB0_1227
	s_mov_b64 s[28:29], -1
	s_cmp_gt_u32 s25, 35
	s_cbranch_scc0 .LBB0_1224
	v_cmp_lt_u32_e32 vcc, 49, v136
	s_and_saveexec_b64 s[2:3], vcc
	s_xor_b64 s[2:3], exec, s[2:3]
	v_lshl_add_u32 v130, v136, 6, v172
	v_subrev_u32_e32 v132, 42, v136
	s_or_saveexec_b64 s[2:3], s[2:3]
	v_mov_b64_e32 v[128:129], 0x100
	v_mov_b64_e32 v[134:135], s[12:13]
	s_xor_b64 exec, exec, s[2:3]
	s_cbranch_execz .LBB0_1223
	v_readlane_b32 s30, v240, 23
	v_subrev_u32_e32 v132, 44, v136
	v_readlane_b32 s31, v240, 24
	v_lshlrev_b32_e32 v130, 6, v132
	v_mov_b64_e32 v[128:129], 0x180
	v_mov_b64_e32 v[134:135], s[30:31]

; DI f32x4 mfma16(bf16x8 a, bf16x8 b, f32x4 c) { return __builtin_amdgcn_mfma_f32_16x16x32_bf16(a, b, c, 0, 0, 0); }
; template <int MI, int NJ, bool SWAP, class AP, class BP>
; DI void gemm_main(f32x4 (&acc)[MI][NJ], const AP& ap, int a_kstep, const BP& bp, int b_kstep, int nk, bf16_t* smem) {
;     ...
;   auto gload = [&](int kt) {
;     const bf16_t* ab = ap.base + (size_t)kt * a_kstep; const bf16_t* bb = bp.base + (size_t)kt * b_kstep;
; #pragma unroll
;     for (int i = 0; i < CA; ++i) ra[i] = *(const u32x4*)(ab + pa[i]);
; #pragma unroll
;     for (int i = 0; i < CB; ++i) rb[i] = *(const u32x4*)(bb + pb[i]);
;   };
;   auto sstore = [&](int buf) {
;     bf16_t* As = smem + buf * L::STAGE; bf16_t* Bs = As + L::A_ELEMS;
; #pragma unroll
;     for (int i = 0; i < CA; ++i) { const int c = tid + NTHR * i; *(u32x4*)(As + (c >> 3) * LDT + (c & 7) * 8) = oka[i] ? ra[i] : (u32x4){0u, 0u, 0u, 0u}; }
; #pragma unroll
;     for (int i = 0; i < CB; ++i) { const int c = tid + NTHR * i; *(u32x4*)(Bs + (c >> 3) * LDT + (c & 7) * 8) = rb[i]; }
;   };
;   gload(0); sstore(0); gload(nk > 1 ? 1 : 0); __syncthreads();
; #pragma unroll 1
;   for (int kt = 0; kt < nk; ++kt) {
;     const int buf = kt & 1;
;     sstore(buf ^ 1);
;     gload(kt + 2 < nk ? kt + 2 : nk - 1);
;     __builtin_amdgcn_sched_barrier(0);
;     const bf16_t* As = smem + buf * L::STAGE + (wm * 16 * MI + l15) * LDT + quad * 8;
;     const bf16_t* Bs = smem + buf * L::STAGE + L::A_ELEMS + (wn * 16 * NJ + l15) * LDT + quad * 8;
; #pragma unroll
;     for (int ks = 0; ks < 2; ++ks) {
;       if (MI * NJ >= 32 && ks == 1) asm volatile("" ::: "memory");
;       bf16x8 b[NJ];
; #pragma unroll
;       for (int j = 0; j < NJ; ++j) b[j] = *(const bf16x8*)(Bs + j * 16 * LDT + ks * 32);
; #pragma unroll
;       for (int i = 0; i < MI; ++i) {
;         const bf16x8 a = *(const bf16x8*)(As + i * 16 * LDT + ks * 32);
; #pragma unroll
;         for (int j = 0; j < NJ; ++j) acc[i][j] = SWAP ? mfma16(b[j], a, acc[i][j]) : mfma16(a, b[j], acc[i][j]);
;       }
;     }
;     __syncthreads();
;   }
.LBB0_1331:
	s_and_b32 s98, s4, 1
	s_mul_i32 s98, s98, 0x12000
	v_add3_u32 v210, s98, v188, v189
	v_add3_u32 v211, s98, v183, v189
	ds_read_b128 v[206:209], v210
	ds_read_b128 v[242:245], v210 offset:2304
	ds_read_b128 v[190:193], v211 offset:36864
	ds_read_b128 v[194:197], v211 offset:39168
	ds_read_b128 v[198:201], v211 offset:41472
	ds_read_b128 v[202:205], v211 offset:43776
.Lgm9_main:
	ds_read_b128 v[246:249], v210 offset:4608
	s_waitcnt lgkmcnt(4)
	v_mfma_f32_16x16x32_bf16 v[124:127], v[206:209], v[190:193], v[124:127]
	s_waitcnt lgkmcnt(3)
	v_mfma_f32_16x16x32_bf16 v[120:123], v[206:209], v[194:197], v[120:123]
	s_waitcnt lgkmcnt(2)
	v_mfma_f32_16x16x32_bf16 v[116:119], v[206:209], v[198:201], v[116:119]
	s_waitcnt lgkmcnt(1)
	v_mfma_f32_16x16x32_bf16 v[112:115], v[206:209], v[202:205], v[112:115]
	s_and_b32 s5, s4, 1
	s_xor_b32 s23, s5, 1
	s_mul_i32 s23, s23, 0x12000
	v_lshlrev_b32_e32 v254, 1, v160
	v_add3_u32 v254, s23, v254, v184
	s_waitcnt vmcnt(7)
	ds_write_b128 v254, v[140:143]
	ds_read_b128 v[250:253], v210 offset:6912
	v_mfma_f32_16x16x32_bf16 v[108:111], v[242:245], v[190:193], v[108:111]
	v_mfma_f32_16x16x32_bf16 v[104:107], v[242:245], v[194:197], v[104:107]
	v_mfma_f32_16x16x32_bf16 v[100:103], v[242:245], v[198:201], v[100:103]
	v_mfma_f32_16x16x32_bf16 v[96:99], v[242:245], v[202:205], v[96:99]
	v_lshlrev_b32_e32 v140, 1, v185
	v_add3_u32 v140, s23, v140, v184
	s_waitcnt vmcnt(6)
	ds_write_b128 v140, v[136:139]
	ds_read_b128 v[206:209], v210 offset:9216
	s_waitcnt lgkmcnt(4)
	v_mfma_f32_16x16x32_bf16 v[92:95], v[246:249], v[190:193], v[92:95]
	v_mfma_f32_16x16x32_bf16 v[88:91], v[246:249], v[194:197], v[88:91]
	v_mfma_f32_16x16x32_bf16 v[84:87], v[246:249], v[198:201], v[84:87]
	v_mfma_f32_16x16x32_bf16 v[80:83], v[246:249], v[202:205], v[80:83]
	ds_read_b128 v[242:245], v210 offset:11520
	s_waitcnt lgkmcnt(3)
	v_mfma_f32_16x16x32_bf16 v[76:79], v[250:253], v[190:193], v[76:79]
	v_lshlrev_b32_e32 v136, 1, v186
	v_add3_u32 v136, s23, v136, v184
	s_waitcnt vmcnt(5)
	ds_write_b128 v136, v[132:135]
	v_mfma_f32_16x16x32_bf16 v[72:75], v[250:253], v[194:197], v[72:75]
	v_mfma_f32_16x16x32_bf16 v[68:71], v[250:253], v[198:201], v[68:71]
	v_mfma_f32_16x16x32_bf16 v[64:67], v[250:253], v[202:205], v[64:67]
	ds_read_b128 v[246:249], v210 offset:13824
	s_waitcnt lgkmcnt(3)
	v_mfma_f32_16x16x32_bf16 v[60:63], v[206:209], v[190:193], v[60:63]
	v_lshlrev_b32_e32 v132, 1, v187
	v_add3_u32 v132, s23, v132, v184
	s_min_u32 s23, s4, 13
	s_lshl_b32 s23, s23, 7
	s_add_u32 s26, s0, s23
	s_addc_u32 s27, s1, 0
	s_waitcnt vmcnt(4)
	ds_write_b128 v132, v[128:131]
	v_mfma_f32_16x16x32_bf16 v[56:59], v[206:209], v[194:197], v[56:59]
	v_mfma_f32_16x16x32_bf16 v[52:55], v[206:209], v[198:201], v[52:55]
	v_mfma_f32_16x16x32_bf16 v[48:51], v[206:209], v[202:205], v[48:51]
	ds_read_b128 v[250:253], v210 offset:16128
	s_waitcnt lgkmcnt(4)
	v_mfma_f32_16x16x32_bf16 v[44:47], v[242:245], v[190:193], v[44:47]
	s_waitcnt vmcnt(3)
	ds_write_b128 v254, v[144:147] offset:36864
	v_mfma_f32_16x16x32_bf16 v[40:43], v[242:245], v[194:197], v[40:43]
	v_mfma_f32_16x16x32_bf16 v[36:39], v[242:245], v[198:201], v[36:39]
	v_mfma_f32_16x16x32_bf16 v[32:35], v[242:245], v[202:205], v[32:35]
	ds_read_b128 v[206:209], v210 offset:64
	s_waitcnt lgkmcnt(4)
	v_mfma_f32_16x16x32_bf16 v[28:31], v[246:249], v[190:193], v[28:31]
	s_waitcnt vmcnt(2)
	ds_write_b128 v140, v[148:151] offset:36864
	v_mfma_f32_16x16x32_bf16 v[24:27], v[246:249], v[194:197], v[24:27]
	v_mfma_f32_16x16x32_bf16 v[20:23], v[246:249], v[198:201], v[20:23]
	v_mfma_f32_16x16x32_bf16 v[16:19], v[246:249], v[202:205], v[16:19]
	ds_read_b128 v[242:245], v210 offset:2368
	s_waitcnt lgkmcnt(4)
	v_mfma_f32_16x16x32_bf16 v[12:15], v[250:253], v[190:193], v[12:15]
	ds_read_b128 v[190:193], v211 offset:36928
	s_waitcnt vmcnt(1)
	ds_write_b128 v136, v[152:155] offset:36864
	v_mfma_f32_16x16x32_bf16 v[8:11], v[250:253], v[194:197], v[8:11]
	ds_read_b128 v[194:197], v211 offset:39232
	v_mfma_f32_16x16x32_bf16 v[4:7], v[250:253], v[198:201], v[4:7]
	ds_read_b128 v[198:201], v211 offset:41536
	v_mfma_f32_16x16x32_bf16 v[0:3], v[250:253], v[202:205], v[0:3]
	ds_read_b128 v[202:205], v211 offset:43840
	ds_read_b128 v[246:249], v210 offset:4672
	s_waitcnt lgkmcnt(5)
	v_mfma_f32_16x16x32_bf16 v[124:127], v[206:209], v[190:193], v[124:127]
	s_waitcnt lgkmcnt(3)
	v_mfma_f32_16x16x32_bf16 v[120:123], v[206:209], v[194:197], v[120:123]
	s_waitcnt vmcnt(0)
	ds_write_b128 v132, v[156:159] offset:36864
	s_waitcnt lgkmcnt(3)
	v_mfma_f32_16x16x32_bf16 v[116:119], v[206:209], v[198:201], v[116:119]
	s_waitcnt lgkmcnt(2)
; DI f32x4 mfma16(bf16x8 a, bf16x8 b, f32x4 c) { return __builtin_amdgcn_mfma_f32_16x16x32_bf16(a, b, c, 0, 0, 0); }
; template <int MI, int NJ, bool SWAP, class AP, class BP>
; DI void gemm_main(f32x4 (&acc)[MI][NJ], const AP& ap, int a_kstep, const BP& bp, int b_kstep, int nk, bf16_t* smem) {
;     ...
;     for (int ks = 0; ks < 2; ++ks) {
;       if (MI * NJ >= 32 && ks == 1) asm volatile("" ::: "memory");
;       bf16x8 b[NJ];
; #pragma unroll
;       for (int j = 0; j < NJ; ++j) b[j] = *(const bf16x8*)(Bs + j * 16 * LDT + ks * 32);
; #pragma unroll
;       for (int i = 0; i < MI; ++i) {
;         const bf16x8 a = *(const bf16x8*)(As + i * 16 * LDT + ks * 32);
; #pragma unroll
;         for (int j = 0; j < NJ; ++j) acc[i][j] = SWAP ? mfma16(b[j], a, acc[i][j]) : mfma16(a, b[j], acc[i][j]);
;       }
;     }
;     __syncthreads();
;   }
; template <bool SWAP> DI void inproj_tile(const Params& p, int layer, int tm, int tn, bf16_t* smem) {
;     ...
;   if constexpr (!SWAP) {
;     bf16_t* dst; int hh, hd;
;     if (tn == 4) { dst = (bf16_t*)(p.ws + (wn < 2 ? O_VSLCT : O_VWINT)); hh = 2; hd = wn & 1; } else { dst = (bf16_t*)(p.ws + O_FOXVT); hh = 8; hd = (tn - 9) * 4 + wn; }
;     constexpr int VLD = 136;
; #pragma unroll
;     for (int i = 0; i < 8; ++i) {
;       const int t0 = trow0 + i * 16 + quad * 4;
	v_mfma_f32_16x16x32_bf16 v[112:115], v[206:209], v[202:205], v[112:115]
	v_lshl_add_u64 v[128:129], s[26:27], 0, v[162:163]
	global_load_dwordx4 v[140:143], v[128:129], off offset:256
	ds_read_b128 v[250:253], v210 offset:6976
	v_mfma_f32_16x16x32_bf16 v[108:111], v[242:245], v[190:193], v[108:111]
	v_mfma_f32_16x16x32_bf16 v[104:107], v[242:245], v[194:197], v[104:107]
	v_lshl_add_u64 v[128:129], s[26:27], 0, v[164:165]
	global_load_dwordx4 v[136:139], v[128:129], off offset:256
	v_mfma_f32_16x16x32_bf16 v[100:103], v[242:245], v[198:201], v[100:103]
	v_mfma_f32_16x16x32_bf16 v[96:99], v[242:245], v[202:205], v[96:99]
	ds_read_b128 v[206:209], v210 offset:9280
	s_waitcnt lgkmcnt(3)
	v_mfma_f32_16x16x32_bf16 v[92:95], v[246:249], v[190:193], v[92:95]
	v_lshl_add_u64 v[128:129], s[26:27], 0, v[166:167]
	global_load_dwordx4 v[132:135], v[128:129], off offset:256
	v_mfma_f32_16x16x32_bf16 v[88:91], v[246:249], v[194:197], v[88:91]
	v_mfma_f32_16x16x32_bf16 v[84:87], v[246:249], v[198:201], v[84:87]
	v_lshl_add_u64 v[128:129], s[26:27], 0, v[168:169]
	s_add_u32 s26, s2, s23
	s_addc_u32 s27, s3, 0
	v_lshl_add_u64 v[144:145], s[26:27], 0, v[162:163]
	v_lshl_add_u64 v[148:149], s[26:27], 0, v[164:165]
	v_lshl_add_u64 v[152:153], s[26:27], 0, v[166:167]
	v_lshl_add_u64 v[156:157], s[26:27], 0, v[168:169]
	global_load_dwordx4 v[128:131], v[128:129], off offset:256
	v_mfma_f32_16x16x32_bf16 v[80:83], v[246:249], v[202:205], v[80:83]
	ds_read_b128 v[242:245], v210 offset:11584
	s_waitcnt lgkmcnt(2)
	v_mfma_f32_16x16x32_bf16 v[76:79], v[250:253], v[190:193], v[76:79]
	v_mfma_f32_16x16x32_bf16 v[72:75], v[250:253], v[194:197], v[72:75]
	s_nop 0
	global_load_dwordx4 v[144:147], v[144:145], off offset:256
	v_mfma_f32_16x16x32_bf16 v[68:71], v[250:253], v[198:201], v[68:71]
	v_mfma_f32_16x16x32_bf16 v[64:67], v[250:253], v[202:205], v[64:67]
	s_nop 0
	global_load_dwordx4 v[148:151], v[148:149], off offset:256
	ds_read_b128 v[246:249], v210 offset:13888
	s_waitcnt lgkmcnt(2)
	v_mfma_f32_16x16x32_bf16 v[60:63], v[206:209], v[190:193], v[60:63]
	v_mfma_f32_16x16x32_bf16 v[56:59], v[206:209], v[194:197], v[56:59]
	v_mfma_f32_16x16x32_bf16 v[52:55], v[206:209], v[198:201], v[52:55]
	s_nop 0
	global_load_dwordx4 v[152:155], v[152:153], off offset:256
	v_mfma_f32_16x16x32_bf16 v[48:51], v[206:209], v[202:205], v[48:51]
	ds_read_b128 v[250:253], v210 offset:16192
	s_waitcnt lgkmcnt(2)
	v_mfma_f32_16x16x32_bf16 v[44:47], v[242:245], v[190:193], v[44:47]
	s_nop 0
	global_load_dwordx4 v[156:159], v[156:157], off offset:256
	v_mfma_f32_16x16x32_bf16 v[40:43], v[242:245], v[194:197], v[40:43]
	v_mfma_f32_16x16x32_bf16 v[36:39], v[242:245], v[198:201], v[36:39]
	v_mfma_f32_16x16x32_bf16 v[32:35], v[242:245], v[202:205], v[32:35]
	s_waitcnt lgkmcnt(0)
	s_barrier
	s_add_i32 s4, s4, 1
	s_cmp_lg_u32 s4, 16
	s_cbranch_scc0 .Lgm9_exit
	s_and_b32 s98, s4, 1
	s_mul_i32 s98, s98, 0x12000
	v_add3_u32 v210, s98, v188, v189
	v_add3_u32 v211, s98, v183, v189
	ds_read_b128 v[206:209], v210
	ds_read_b128 v[242:245], v210 offset:2304
	v_mfma_f32_16x16x32_bf16 v[28:31], v[246:249], v[190:193], v[28:31]
	v_mfma_f32_16x16x32_bf16 v[12:15], v[250:253], v[190:193], v[12:15]
	ds_read_b128 v[190:193], v211 offset:36864
	v_mfma_f32_16x16x32_bf16 v[24:27], v[246:249], v[194:197], v[24:27]
	v_mfma_f32_16x16x32_bf16 v[8:11], v[250:253], v[194:197], v[8:11]
	ds_read_b128 v[194:197], v211 offset:39168
	v_mfma_f32_16x16x32_bf16 v[20:23], v[246:249], v[198:201], v[20:23]
	v_mfma_f32_16x16x32_bf16 v[4:7], v[250:253], v[198:201], v[4:7]
	ds_read_b128 v[198:201], v211 offset:41472
	v_mfma_f32_16x16x32_bf16 v[16:19], v[246:249], v[202:205], v[16:19]
	v_mfma_f32_16x16x32_bf16 v[0:3], v[250:253], v[202:205], v[0:3]
	ds_read_b128 v[202:205], v211 offset:43776
	s_branch .Lgm9_main
.Lgm9_exit:
	v_mfma_f32_16x16x32_bf16 v[28:31], v[246:249], v[190:193], v[28:31]
	v_mfma_f32_16x16x32_bf16 v[12:15], v[250:253], v[190:193], v[12:15]
	v_mfma_f32_16x16x32_bf16 v[24:27], v[246:249], v[194:197], v[24:27]
	v_mfma_f32_16x16x32_bf16 v[8:11], v[250:253], v[194:197], v[8:11]
	v_mfma_f32_16x16x32_bf16 v[20:23], v[246:249], v[198:201], v[20:23]
	v_mfma_f32_16x16x32_bf16 v[4:7], v[250:253], v[198:201], v[4:7]
	v_mfma_f32_16x16x32_bf16 v[16:19], v[246:249], v[202:205], v[16:19]
	v_mfma_f32_16x16x32_bf16 v[0:3], v[250:253], v[202:205], v[0:3]
	s_nop 7
	v_mov_b32_e32 v162, v220
	s_waitcnt vmcnt(4)
	v_mov_b32_e32 v129, v220
	s_and_b32 s0, s51, 0xfff8
	v_ashrrev_i32_e32 v128, 6, v129
	v_and_b32_e32 v130, 3, v128
	s_cmp_lg_u32 s0, 32
	s_mov_b64 s[0:1], -1
	s_cbranch_scc0 .LBB0_1334
	s_lshl_b32 s0, s22, 2
	s_sub_i32 s0, s0, 36
	v_or_b32_e32 v163, s0, v130
	s_mov_b64 s[0:1], 0

; DI f32x4 mfma16(bf16x8 a, bf16x8 b, f32x4 c) { return __builtin_amdgcn_mfma_f32_16x16x32_bf16(a, b, c, 0, 0, 0); }
; template <int MI, int NJ, bool SWAP, class AP, class BP>
; DI void gemm_main(f32x4 (&acc)[MI][NJ], const AP& ap, int a_kstep, const BP& bp, int b_kstep, int nk, bf16_t* smem) {
;     ...
;   for (int kt = 0; kt < nk; ++kt) {
;     const int buf = kt & 1;
;     sstore(buf ^ 1);
;     gload(kt + 2 < nk ? kt + 2 : nk - 1);
;     __builtin_amdgcn_sched_barrier(0);
;     const bf16_t* As = smem + buf * L::STAGE + (wm * 16 * MI + l15) * LDT + quad * 8;
;     const bf16_t* Bs = smem + buf * L::STAGE + L::A_ELEMS + (wn * 16 * NJ + l15) * LDT + quad * 8;
; #pragma unroll
;     for (int ks = 0; ks < 2; ++ks) {
;       if (MI * NJ >= 32 && ks == 1) asm volatile("" ::: "memory");
;       bf16x8 b[NJ];
; #pragma unroll
;       for (int j = 0; j < NJ; ++j) b[j] = *(const bf16x8*)(Bs + j * 16 * LDT + ks * 32);
; #pragma unroll
;       for (int i = 0; i < MI; ++i) {
;         const bf16x8 a = *(const bf16x8*)(As + i * 16 * LDT + ks * 32);
; #pragma unroll
;         for (int j = 0; j < NJ; ++j) acc[i][j] = SWAP ? mfma16(b[j], a, acc[i][j]) : mfma16(a, b[j], acc[i][j]);
;       }
;     }
.LBB0_1410:
	s_and_b32 s98, s8, 1
	s_mul_i32 s98, s98, 0x12000
	v_add3_u32 v198, s98, v172, v177
	v_add3_u32 v199, s98, v160, v177
	ds_read_b128 v[194:197], v198
	ds_read_b128 v[242:245], v198 offset:2304
	ds_read_b128 v[178:181], v199 offset:36864
	ds_read_b128 v[182:185], v199 offset:39168
	ds_read_b128 v[186:189], v199 offset:41472
	ds_read_b128 v[190:193], v199 offset:43776
.Lgm10_main:
	ds_read_b128 v[246:249], v198 offset:4608
	s_waitcnt lgkmcnt(4)
	v_mfma_f32_16x16x32_bf16 v[156:159], v[178:181], v[194:197], v[156:159]
	s_waitcnt lgkmcnt(3)
	v_mfma_f32_16x16x32_bf16 v[152:155], v[182:185], v[194:197], v[152:155]
	s_waitcnt lgkmcnt(2)
	v_mfma_f32_16x16x32_bf16 v[148:151], v[186:189], v[194:197], v[148:151]
	s_waitcnt lgkmcnt(1)
	v_mfma_f32_16x16x32_bf16 v[144:147], v[190:193], v[194:197], v[144:147]
	s_and_b32 s33, s8, 1
	s_xor_b32 s37, s33, 1
	s_mul_i32 s37, s37, 0x12000
	v_add3_u32 v254, s37, v173, v171
	s_waitcnt vmcnt(7)
	ds_write_b128 v254, v[112:115]
	ds_read_b128 v[250:253], v198 offset:6912
	v_mfma_f32_16x16x32_bf16 v[108:111], v[178:181], v[242:245], v[108:111]
	v_mfma_f32_16x16x32_bf16 v[104:107], v[182:185], v[242:245], v[104:107]
	v_mfma_f32_16x16x32_bf16 v[100:103], v[186:189], v[242:245], v[100:103]
	v_mfma_f32_16x16x32_bf16 v[96:99], v[190:193], v[242:245], v[96:99]
	v_add3_u32 v112, s37, v174, v171
	v_add3_u32 v113, s37, v175, v171
	v_add3_u32 v114, s37, v176, v171
	s_min_u32 s37, s8, 3
	s_lshl_b32 s37, s37, 7
	s_add_u32 s38, s0, s37
	s_addc_u32 s39, s1, 0
	s_waitcnt vmcnt(5)
	ds_write_b128 v112, v[116:119]
	ds_read_b128 v[194:197], v198 offset:9216
	s_waitcnt lgkmcnt(4)
	v_mfma_f32_16x16x32_bf16 v[92:95], v[178:181], v[246:249], v[92:95]
	v_mfma_f32_16x16x32_bf16 v[88:91], v[182:185], v[246:249], v[88:91]
	v_mfma_f32_16x16x32_bf16 v[84:87], v[186:189], v[246:249], v[84:87]
	v_mfma_f32_16x16x32_bf16 v[80:83], v[190:193], v[246:249], v[80:83]
	ds_read_b128 v[242:245], v198 offset:11520
	s_waitcnt lgkmcnt(3)
	v_mfma_f32_16x16x32_bf16 v[76:79], v[178:181], v[250:253], v[76:79]
	s_waitcnt vmcnt(4)
	ds_write_b128 v113, v[120:123]
	v_mfma_f32_16x16x32_bf16 v[72:75], v[182:185], v[250:253], v[72:75]
	v_mfma_f32_16x16x32_bf16 v[68:71], v[186:189], v[250:253], v[68:71]
	v_mfma_f32_16x16x32_bf16 v[64:67], v[190:193], v[250:253], v[64:67]
	ds_read_b128 v[246:249], v198 offset:13824
	s_waitcnt lgkmcnt(3)
	v_mfma_f32_16x16x32_bf16 v[60:63], v[178:181], v[194:197], v[60:63]
	s_waitcnt vmcnt(3)
	ds_write_b128 v114, v[124:127]
	v_mfma_f32_16x16x32_bf16 v[56:59], v[182:185], v[194:197], v[56:59]
	v_mfma_f32_16x16x32_bf16 v[52:55], v[186:189], v[194:197], v[52:55]
	v_mfma_f32_16x16x32_bf16 v[48:51], v[190:193], v[194:197], v[48:51]
	ds_read_b128 v[250:253], v198 offset:16128
	s_waitcnt lgkmcnt(4)
	v_mfma_f32_16x16x32_bf16 v[44:47], v[178:181], v[242:245], v[44:47]
	ds_write_b128 v254, v[128:131] offset:36864
	v_mfma_f32_16x16x32_bf16 v[40:43], v[182:185], v[242:245], v[40:43]
	v_mfma_f32_16x16x32_bf16 v[36:39], v[186:189], v[242:245], v[36:39]
	v_mfma_f32_16x16x32_bf16 v[32:35], v[190:193], v[242:245], v[32:35]
	ds_read_b128 v[194:197], v198 offset:64
	s_waitcnt lgkmcnt(4)
	v_mfma_f32_16x16x32_bf16 v[28:31], v[178:181], v[246:249], v[28:31]
	s_waitcnt vmcnt(2)
	ds_write_b128 v112, v[132:135] offset:36864
	v_mfma_f32_16x16x32_bf16 v[24:27], v[182:185], v[246:249], v[24:27]
	v_mfma_f32_16x16x32_bf16 v[20:23], v[186:189], v[246:249], v[20:23]
	v_mfma_f32_16x16x32_bf16 v[16:19], v[190:193], v[246:249], v[16:19]
	ds_read_b128 v[242:245], v198 offset:2368
	s_waitcnt lgkmcnt(4)
	v_mfma_f32_16x16x32_bf16 v[12:15], v[178:181], v[250:253], v[12:15]
	ds_read_b128 v[178:181], v199 offset:36928
	s_waitcnt vmcnt(1)
	ds_write_b128 v113, v[136:139] offset:36864
	v_mfma_f32_16x16x32_bf16 v[8:11], v[182:185], v[250:253], v[8:11]
	ds_read_b128 v[182:185], v199 offset:39232
	v_mfma_f32_16x16x32_bf16 v[4:7], v[186:189], v[250:253], v[4:7]
	ds_read_b128 v[186:189], v199 offset:41536
	v_mfma_f32_16x16x32_bf16 v[0:3], v[190:193], v[250:253], v[0:3]
	ds_read_b128 v[190:193], v199 offset:43840
	ds_read_b128 v[246:249], v198 offset:4672
	s_waitcnt lgkmcnt(5)
	v_mfma_f32_16x16x32_bf16 v[156:159], v[178:181], v[194:197], v[156:159]
	s_waitcnt lgkmcnt(3)
	v_mfma_f32_16x16x32_bf16 v[152:155], v[182:185], v[194:197], v[152:155]
	s_waitcnt vmcnt(0)
	ds_write_b128 v114, v[140:143] offset:36864
	s_waitcnt lgkmcnt(3)
	v_mfma_f32_16x16x32_bf16 v[148:151], v[186:189], v[194:197], v[148:151]
	s_waitcnt lgkmcnt(2)
	v_mfma_f32_16x16x32_bf16 v[144:147], v[190:193], v[194:197], v[144:147]
	v_lshl_add_u64 v[112:113], s[38:39], 0, v[162:163]
	v_lshl_add_u64 v[116:117], s[38:39], 0, v[164:165]
	v_lshl_add_u64 v[120:121], s[38:39], 0, v[166:167]
	v_lshl_add_u64 v[124:125], s[38:39], 0, v[168:169]
	s_add_u32 s38, s2, s37
	s_addc_u32 s39, s3, 0
	v_lshl_add_u64 v[128:129], s[38:39], 0, v[162:163]
	v_lshl_add_u64 v[132:133], s[38:39], 0, v[164:165]
	v_lshl_add_u64 v[136:137], s[38:39], 0, v[166:167]
	v_lshl_add_u64 v[140:141], s[38:39], 0, v[168:169]
	global_load_dwordx4 v[112:115], v[112:113], off offset:256
	ds_read_b128 v[250:253], v198 offset:6976
	v_mfma_f32_16x16x32_bf16 v[108:111], v[178:181], v[242:245], v[108:111]
	v_mfma_f32_16x16x32_bf16 v[104:107], v[182:185], v[242:245], v[104:107]
	s_nop 0
	global_load_dwordx4 v[116:119], v[116:117], off offset:256
	v_mfma_f32_16x16x32_bf16 v[100:103], v[186:189], v[242:245], v[100:103]
	v_mfma_f32_16x16x32_bf16 v[96:99], v[190:193], v[242:245], v[96:99]
	ds_read_b128 v[194:197], v198 offset:9280
	s_waitcnt lgkmcnt(3)
; DI f32x4 mfma16(bf16x8 a, bf16x8 b, f32x4 c) { return __builtin_amdgcn_mfma_f32_16x16x32_bf16(a, b, c, 0, 0, 0); }
; template <int MI, int NJ, bool SWAP, class AP, class BP>
; DI void gemm_main(f32x4 (&acc)[MI][NJ], const AP& ap, int a_kstep, const BP& bp, int b_kstep, int nk, bf16_t* smem) {
;     ...
;   for (int kt = 0; kt < nk; ++kt) {
;     const int buf = kt & 1;
;     sstore(buf ^ 1);
;     gload(kt + 2 < nk ? kt + 2 : nk - 1);
;     __builtin_amdgcn_sched_barrier(0);
;     const bf16_t* As = smem + buf * L::STAGE + (wm * 16 * MI + l15) * LDT + quad * 8;
;     const bf16_t* Bs = smem + buf * L::STAGE + L::A_ELEMS + (wn * 16 * NJ + l15) * LDT + quad * 8;
; #pragma unroll
;     for (int ks = 0; ks < 2; ++ks) {
;       if (MI * NJ >= 32 && ks == 1) asm volatile("" ::: "memory");
;       bf16x8 b[NJ];
; #pragma unroll
;       for (int j = 0; j < NJ; ++j) b[j] = *(const bf16x8*)(Bs + j * 16 * LDT + ks * 32);
; #pragma unroll
;       for (int i = 0; i < MI; ++i) {
;         const bf16x8 a = *(const bf16x8*)(As + i * 16 * LDT + ks * 32);
; #pragma unroll
;         for (int j = 0; j < NJ; ++j) acc[i][j] = SWAP ? mfma16(b[j], a, acc[i][j]) : mfma16(a, b[j], acc[i][j]);
;       }
;     }
;     __syncthreads();
;   }
	v_mfma_f32_16x16x32_bf16 v[92:95], v[178:181], v[246:249], v[92:95]
	s_nop 0
	global_load_dwordx4 v[120:123], v[120:121], off offset:256
	v_mfma_f32_16x16x32_bf16 v[88:91], v[182:185], v[246:249], v[88:91]
	v_mfma_f32_16x16x32_bf16 v[84:87], v[186:189], v[246:249], v[84:87]
	s_nop 0
	global_load_dwordx4 v[124:127], v[124:125], off offset:256
	v_mfma_f32_16x16x32_bf16 v[80:83], v[190:193], v[246:249], v[80:83]
	ds_read_b128 v[242:245], v198 offset:11584
	s_waitcnt lgkmcnt(2)
	v_mfma_f32_16x16x32_bf16 v[76:79], v[178:181], v[250:253], v[76:79]
	v_mfma_f32_16x16x32_bf16 v[72:75], v[182:185], v[250:253], v[72:75]
	s_nop 0
	global_load_dwordx4 v[128:131], v[128:129], off offset:256
	v_mfma_f32_16x16x32_bf16 v[68:71], v[186:189], v[250:253], v[68:71]
	v_mfma_f32_16x16x32_bf16 v[64:67], v[190:193], v[250:253], v[64:67]
	s_nop 0
	global_load_dwordx4 v[132:135], v[132:133], off offset:256
	ds_read_b128 v[246:249], v198 offset:13888
	s_waitcnt lgkmcnt(2)
	v_mfma_f32_16x16x32_bf16 v[60:63], v[178:181], v[194:197], v[60:63]
	v_mfma_f32_16x16x32_bf16 v[56:59], v[182:185], v[194:197], v[56:59]
	v_mfma_f32_16x16x32_bf16 v[52:55], v[186:189], v[194:197], v[52:55]
	s_nop 0
	global_load_dwordx4 v[136:139], v[136:137], off offset:256
	v_mfma_f32_16x16x32_bf16 v[48:51], v[190:193], v[194:197], v[48:51]
	ds_read_b128 v[250:253], v198 offset:16192
	s_waitcnt lgkmcnt(2)
	v_mfma_f32_16x16x32_bf16 v[44:47], v[178:181], v[242:245], v[44:47]
	s_nop 0
	global_load_dwordx4 v[140:143], v[140:141], off offset:256
	v_mfma_f32_16x16x32_bf16 v[40:43], v[182:185], v[242:245], v[40:43]
	v_mfma_f32_16x16x32_bf16 v[36:39], v[186:189], v[242:245], v[36:39]
	v_mfma_f32_16x16x32_bf16 v[32:35], v[190:193], v[242:245], v[32:35]
	s_waitcnt lgkmcnt(0)
	s_barrier
	s_add_i32 s8, s8, 1
	s_cmp_lg_u32 s8, 6
	s_cbranch_scc0 .Lgm10_exit
	s_and_b32 s98, s8, 1
	s_mul_i32 s98, s98, 0x12000
	v_add3_u32 v198, s98, v172, v177
	v_add3_u32 v199, s98, v160, v177
	ds_read_b128 v[194:197], v198
	ds_read_b128 v[242:245], v198 offset:2304
	v_mfma_f32_16x16x32_bf16 v[28:31], v[178:181], v[246:249], v[28:31]
	v_mfma_f32_16x16x32_bf16 v[12:15], v[178:181], v[250:253], v[12:15]
	ds_read_b128 v[178:181], v199 offset:36864
	v_mfma_f32_16x16x32_bf16 v[24:27], v[182:185], v[246:249], v[24:27]
	v_mfma_f32_16x16x32_bf16 v[8:11], v[182:185], v[250:253], v[8:11]
	ds_read_b128 v[182:185], v199 offset:39168
	v_mfma_f32_16x16x32_bf16 v[20:23], v[186:189], v[246:249], v[20:23]
	v_mfma_f32_16x16x32_bf16 v[4:7], v[186:189], v[250:253], v[4:7]
	ds_read_b128 v[186:189], v199 offset:41472
	v_mfma_f32_16x16x32_bf16 v[16:19], v[190:193], v[246:249], v[16:19]
	v_mfma_f32_16x16x32_bf16 v[0:3], v[190:193], v[250:253], v[0:3]
	ds_read_b128 v[190:193], v199 offset:43776
	s_branch .Lgm10_main
; template <int KIND> DI void mlaup_tile(const Params& p, int layer, int tm, int tn, bf16_t* smem) {
;     ...
;     const int n0 = tn * 256 + wn * 64, ph = n0 % 96;
; #pragma unroll
;     for (int i = 0; i < 8; ++i) {
;       asm volatile("" ::: "memory");
;       const int row = i * 16 + l15, t = trow0 + row; const float* c = cssq + (size_t)t * 16;
;       const float rs = rsqrtf((c[0] + c[1] + c[2] + c[3] + c[4] + c[5]) * (1.f / 384.f) + EPS_) * QS96_;
;       f32x4 v0 = acc[i][0] * rs, v1 = acc[i][1] * rs, v2 = acc[i][2] * rs, v3 = acc[i][3] * rs;
;       if (ph != 0) {
;         const float* rp = (const float*)(p.ws + O_ROPE16) + (size_t)t * 32 + quad * 8;
;         const f32x4 x1 = ph == 64 ? v0 : v2, x2 = ph == 64 ? v1 : v3; f32x4 o1, o2;
; #pragma unroll
;         for (int r = 0; r < 4; ++r) { const float cs = rp[2 * r], sn = rp[2 * r + 1]; o1[r] = x1[r] * cs - x2[r] * sn; o2[r] = x2[r] * cs + x1[r] * sn; }
;         if (ph == 64) { v0 = o1; v1 = o2; } else { v2 = o1; v3 = o2; }
;       }
.Lgm10_exit:
	v_mfma_f32_16x16x32_bf16 v[28:31], v[178:181], v[246:249], v[28:31]
	v_mfma_f32_16x16x32_bf16 v[12:15], v[178:181], v[250:253], v[12:15]
	v_mfma_f32_16x16x32_bf16 v[24:27], v[182:185], v[246:249], v[24:27]
	v_mfma_f32_16x16x32_bf16 v[8:11], v[182:185], v[250:253], v[8:11]
	v_mfma_f32_16x16x32_bf16 v[20:23], v[186:189], v[246:249], v[20:23]
	v_mfma_f32_16x16x32_bf16 v[4:7], v[186:189], v[250:253], v[4:7]
	v_mfma_f32_16x16x32_bf16 v[16:19], v[190:193], v[246:249], v[16:19]
	v_mfma_f32_16x16x32_bf16 v[0:3], v[190:193], v[250:253], v[0:3]
	s_nop 7
	s_waitcnt vmcnt(2)
	v_mov_b32_e32 v132, v220
	v_mov_b32_e32 v135, v220
	s_mov_b32 s0, 0x2aaaaaab
	v_ashrrev_i32_e32 v112, 1, v135
	v_and_b32_e32 v112, 0xffffff80, v112
	v_and_b32_e32 v133, 15, v132
	v_lshl_add_u32 v113, s16, 8, v112
	v_or_b32_e32 v130, v113, v133
	v_ashrrev_i32_e32 v131, 31, v130
	v_lshlrev_b64 v[114:115], 6, v[130:131]
	v_lshl_add_u64 v[118:119], s[4:5], 0, v[114:115]
	global_load_dwordx4 v[114:117], v[118:119], off
	s_nop 0
	global_load_dwordx2 v[118:119], v[118:119], off offset:16
	v_and_b32_e32 v112, 0xc0, v135
	v_lshl_or_b32 v112, s36, 8, v112
	v_mul_hi_i32 v120, v112, s0
	v_lshrrev_b32_e32 v121, 31, v120
	v_lshrrev_b32_e32 v120, 4, v120
	v_add_u32_e32 v120, v120, v121
	v_mul_lo_u32 v120, v120, s28
	v_bfe_u32 v134, v132, 4, 2
	s_waitcnt vmcnt(3)
	v_lshlrev_b32_e32 v136, 3, v134
	v_lshlrev_b32_e32 v160, 2, v136
	s_waitcnt vmcnt(1)
	v_add_f32_e32 v114, v114, v115
	v_add_f32_e32 v114, v114, v116
	v_add_f32_e32 v114, v114, v117
	s_waitcnt vmcnt(0)
	v_add_f32_e32 v114, v114, v118
	v_add_f32_e32 v114, v114, v119
	v_fmamk_f32 v114, v114, 0x3b2aaaab, v170
	v_mul_f32_e32 v115, 0x4b800000, v114
	v_cmp_gt_f32_e64 s[2:3], s29, v114
	s_nop 1
	v_cndmask_b32_e64 v114, v114, v115, s[2:3]
	v_rsq_f32_e32 v114, v114
	v_sub_u32_e32 v115, v112, v120
	v_cmp_ne_u32_e64 s[0:1], 0, v115
	v_cmp_eq_u32_e32 vcc, 64, v115
	v_mul_f32_e32 v115, 0x45800000, v114
	v_cndmask_b32_e64 v114, v114, v115, s[2:3]
	v_mul_f32_e32 v128, 0x3e16c740, v114
	v_pk_mul_f32 v[114:115], v[158:159], v[128:129] op_sel_hi:[1,0]
	v_pk_mul_f32 v[116:117], v[156:157], v[128:129] op_sel_hi:[1,0]
	v_pk_mul_f32 v[118:119], v[154:155], v[128:129] op_sel_hi:[1,0]
	v_pk_mul_f32 v[120:121], v[152:153], v[128:129] op_sel_hi:[1,0]
	v_pk_mul_f32 v[122:123], v[150:151], v[128:129] op_sel_hi:[1,0]
	v_pk_mul_f32 v[124:125], v[148:149], v[128:129] op_sel_hi:[1,0]
	v_pk_mul_f32 v[126:127], v[146:147], v[128:129] op_sel_hi:[1,0]
	v_pk_mul_f32 v[128:129], v[144:145], v[128:129] op_sel_hi:[1,0]
	s_and_saveexec_b64 s[2:3], s[0:1]
	s_cbranch_execz .LBB0_1413
	v_lshlrev_b64 v[130:131], 7, v[130:131]
	v_lshl_add_u64 v[130:131], s[6:7], 0, v[130:131]
	v_lshl_add_u64 v[130:131], v[130:131], 0, v[160:161]
	global_load_dwordx4 v[138:141], v[130:131], off offset:16
	global_load_dwordx4 v[142:145], v[130:131], off
	v_cndmask_b32_e32 v149, v125, v117, vcc
	v_cndmask_b32_e32 v148, v124, v116, vcc
	v_cndmask_b32_e32 v153, v129, v121, vcc
	v_cndmask_b32_e32 v152, v128, v120, vcc
	v_cndmask_b32_e32 v147, v123, v115, vcc
	v_cndmask_b32_e32 v146, v122, v114, vcc
	v_cndmask_b32_e32 v151, v127, v119, vcc
	v_cndmask_b32_e32 v150, v126, v118, vcc
	s_waitcnt vmcnt(0)
	v_mov_b32_e32 v131, v144
	v_mov_b32_e32 v144, v143
	v_mov_b32_e32 v130, v142
	v_pk_mul_f32 v[142:143], v[148:149], v[144:145]
	v_pk_mul_f32 v[144:145], v[152:153], v[144:145]
	v_pk_fma_f32 v[142:143], v[152:153], v[130:131], v[142:143]
	v_pk_fma_f32 v[130:131], v[148:149], v[130:131], v[144:145] neg_lo:[0,0,1] neg_hi:[0,0,1]
	v_mov_b32_e32 v145, v140
	v_mov_b32_e32 v140, v139
	v_mov_b32_e32 v144, v138
	v_pk_mul_f32 v[138:139], v[146:147], v[140:141]
	v_pk_mul_f32 v[140:141], v[150:151], v[140:141]
	v_pk_fma_f32 v[138:139], v[150:151], v[144:145], v[138:139]
	v_pk_fma_f32 v[140:141], v[146:147], v[144:145], v[140:141] neg_lo:[0,0,1] neg_hi:[0,0,1]
	v_cndmask_b32_e32 v117, v117, v131, vcc
	v_cndmask_b32_e32 v115, v115, v141, vcc
	v_cndmask_b32_e32 v114, v114, v140, vcc
	v_cndmask_b32_e32 v116, v116, v130, vcc
	v_cndmask_b32_e32 v119, v119, v139, vcc
	v_cndmask_b32_e32 v118, v118, v138, vcc
	v_cndmask_b32_e32 v121, v121, v143, vcc
	v_cndmask_b32_e32 v120, v120, v142, vcc
	v_cndmask_b32_e32 v123, v141, v123, vcc
	v_cndmask_b32_e32 v122, v140, v122, vcc
	v_cndmask_b32_e32 v125, v131, v125, vcc
	v_cndmask_b32_e32 v124, v130, v124, vcc
	v_cndmask_b32_e32 v127, v139, v127, vcc
	v_cndmask_b32_e32 v126, v138, v126, vcc
	v_cndmask_b32_e32 v129, v143, v129, vcc
	v_cndmask_b32_e32 v128, v142, v128, vcc

; DI f32x4 mfma16(bf16x8 a, bf16x8 b, f32x4 c) { return __builtin_amdgcn_mfma_f32_16x16x32_bf16(a, b, c, 0, 0, 0); }
; template <int MI, int NJ, bool SWAP, class AP, class BP>
; DI void gemm_main(f32x4 (&acc)[MI][NJ], const AP& ap, int a_kstep, const BP& bp, int b_kstep, int nk, bf16_t* smem) {
;     ...
;   for (int kt = 0; kt < nk; ++kt) {
;     const int buf = kt & 1;
;     sstore(buf ^ 1);
;     gload(kt + 2 < nk ? kt + 2 : nk - 1);
;     __builtin_amdgcn_sched_barrier(0);
;     const bf16_t* As = smem + buf * L::STAGE + (wm * 16 * MI + l15) * LDT + quad * 8;
;     const bf16_t* Bs = smem + buf * L::STAGE + L::A_ELEMS + (wn * 16 * NJ + l15) * LDT + quad * 8;
; #pragma unroll
;     for (int ks = 0; ks < 2; ++ks) {
;       if (MI * NJ >= 32 && ks == 1) asm volatile("" ::: "memory");
;       bf16x8 b[NJ];
; #pragma unroll
;       for (int j = 0; j < NJ; ++j) b[j] = *(const bf16x8*)(Bs + j * 16 * LDT + ks * 32);
; #pragma unroll
;       for (int i = 0; i < MI; ++i) {
;         const bf16x8 a = *(const bf16x8*)(As + i * 16 * LDT + ks * 32);
; #pragma unroll
;         for (int j = 0; j < NJ; ++j) acc[i][j] = SWAP ? mfma16(b[j], a, acc[i][j]) : mfma16(a, b[j], acc[i][j]);
;       }
;     }
.LBB0_1430:
	s_and_b32 s98, s33, 1
	s_mul_i32 s98, s98, 0x12000
	v_add3_u32 v198, s98, v176, v177
	v_add3_u32 v199, s98, v171, v177
	ds_read_b128 v[194:197], v198
	ds_read_b128 v[242:245], v198 offset:2304
	ds_read_b128 v[178:181], v199 offset:36864
	ds_read_b128 v[182:185], v199 offset:39168
	ds_read_b128 v[186:189], v199 offset:41472
	ds_read_b128 v[190:193], v199 offset:43776
.Lgm11_main:
	ds_read_b128 v[246:249], v198 offset:4608
	s_waitcnt lgkmcnt(4)
	v_mfma_f32_16x16x32_bf16 v[156:159], v[178:181], v[194:197], v[156:159]
	s_waitcnt lgkmcnt(3)
	v_mfma_f32_16x16x32_bf16 v[152:155], v[182:185], v[194:197], v[152:155]
	s_waitcnt lgkmcnt(2)
	v_mfma_f32_16x16x32_bf16 v[148:151], v[186:189], v[194:197], v[148:151]
	s_waitcnt lgkmcnt(1)
	v_mfma_f32_16x16x32_bf16 v[144:147], v[190:193], v[194:197], v[144:147]
	s_and_b32 s37, s33, 1
	s_xor_b32 s38, s37, 1
	s_mul_i32 s38, s38, 0x12000
	v_lshlrev_b32_e32 v254, 1, v160
	v_add3_u32 v254, s38, v254, v172
	s_waitcnt vmcnt(7)
	ds_write_b128 v254, v[124:127]
	ds_read_b128 v[250:253], v198 offset:6912
	v_mfma_f32_16x16x32_bf16 v[108:111], v[178:181], v[242:245], v[108:111]
	v_mfma_f32_16x16x32_bf16 v[104:107], v[182:185], v[242:245], v[104:107]
	v_mfma_f32_16x16x32_bf16 v[100:103], v[186:189], v[242:245], v[100:103]
	v_mfma_f32_16x16x32_bf16 v[96:99], v[190:193], v[242:245], v[96:99]
	v_lshlrev_b32_e32 v124, 1, v173
	v_add3_u32 v124, s38, v124, v172
	s_waitcnt vmcnt(6)
	ds_write_b128 v124, v[120:123]
	ds_read_b128 v[194:197], v198 offset:9216
	s_waitcnt lgkmcnt(4)
	v_mfma_f32_16x16x32_bf16 v[92:95], v[178:181], v[246:249], v[92:95]
	v_mfma_f32_16x16x32_bf16 v[88:91], v[182:185], v[246:249], v[88:91]
	v_mfma_f32_16x16x32_bf16 v[84:87], v[186:189], v[246:249], v[84:87]
	v_mfma_f32_16x16x32_bf16 v[80:83], v[190:193], v[246:249], v[80:83]
	ds_read_b128 v[242:245], v198 offset:11520
	s_waitcnt lgkmcnt(3)
	v_mfma_f32_16x16x32_bf16 v[76:79], v[178:181], v[250:253], v[76:79]
	v_lshlrev_b32_e32 v120, 1, v174
	v_add3_u32 v120, s38, v120, v172
	s_cmp_eq_u32 s33, 0
	s_waitcnt vmcnt(5)
	ds_write_b128 v120, v[116:119]
	v_mfma_f32_16x16x32_bf16 v[72:75], v[182:185], v[250:253], v[72:75]
	v_mfma_f32_16x16x32_bf16 v[68:71], v[186:189], v[250:253], v[68:71]
	v_mfma_f32_16x16x32_bf16 v[64:67], v[190:193], v[250:253], v[64:67]
	ds_read_b128 v[246:249], v198 offset:13824
	s_waitcnt lgkmcnt(3)
	v_mfma_f32_16x16x32_bf16 v[60:63], v[178:181], v[194:197], v[60:63]
	v_lshlrev_b32_e32 v116, 1, v175
	s_cselect_b32 s40, s31, 0x180
	v_add3_u32 v116, s38, v116, v172
	s_add_u32 s38, s0, s40
	s_addc_u32 s39, s1, 0
	s_waitcnt vmcnt(4)
	ds_write_b128 v116, v[112:115]
	v_mfma_f32_16x16x32_bf16 v[56:59], v[182:185], v[194:197], v[56:59]
	v_mfma_f32_16x16x32_bf16 v[52:55], v[186:189], v[194:197], v[52:55]
	v_mfma_f32_16x16x32_bf16 v[48:51], v[190:193], v[194:197], v[48:51]
	ds_read_b128 v[250:253], v198 offset:16128
	s_waitcnt lgkmcnt(4)
	v_mfma_f32_16x16x32_bf16 v[44:47], v[178:181], v[242:245], v[44:47]
	s_waitcnt vmcnt(3)
	ds_write_b128 v254, v[128:131] offset:36864
	v_mfma_f32_16x16x32_bf16 v[40:43], v[182:185], v[242:245], v[40:43]
	v_mfma_f32_16x16x32_bf16 v[36:39], v[186:189], v[242:245], v[36:39]
	v_mfma_f32_16x16x32_bf16 v[32:35], v[190:193], v[242:245], v[32:35]
	ds_read_b128 v[194:197], v198 offset:64
	s_waitcnt lgkmcnt(4)
	v_mfma_f32_16x16x32_bf16 v[28:31], v[178:181], v[246:249], v[28:31]
	s_waitcnt vmcnt(2)
	ds_write_b128 v124, v[132:135] offset:36864
	v_mfma_f32_16x16x32_bf16 v[24:27], v[182:185], v[246:249], v[24:27]
	v_mfma_f32_16x16x32_bf16 v[20:23], v[186:189], v[246:249], v[20:23]
	v_mfma_f32_16x16x32_bf16 v[16:19], v[190:193], v[246:249], v[16:19]
	ds_read_b128 v[242:245], v198 offset:2368
	s_waitcnt lgkmcnt(4)
	v_mfma_f32_16x16x32_bf16 v[12:15], v[178:181], v[250:253], v[12:15]
	ds_read_b128 v[178:181], v199 offset:36928
	s_waitcnt vmcnt(1)
	ds_write_b128 v120, v[136:139] offset:36864
	v_mfma_f32_16x16x32_bf16 v[8:11], v[182:185], v[250:253], v[8:11]
	ds_read_b128 v[182:185], v199 offset:39232
	v_mfma_f32_16x16x32_bf16 v[4:7], v[186:189], v[250:253], v[4:7]
	ds_read_b128 v[186:189], v199 offset:41536
	v_mfma_f32_16x16x32_bf16 v[0:3], v[190:193], v[250:253], v[0:3]
	ds_read_b128 v[190:193], v199 offset:43840
	ds_read_b128 v[246:249], v198 offset:4672
	s_waitcnt lgkmcnt(5)
	v_mfma_f32_16x16x32_bf16 v[156:159], v[178:181], v[194:197], v[156:159]
	s_waitcnt lgkmcnt(3)
	v_mfma_f32_16x16x32_bf16 v[152:155], v[182:185], v[194:197], v[152:155]
	s_waitcnt vmcnt(0)
	ds_write_b128 v116, v[140:143] offset:36864
	s_waitcnt lgkmcnt(3)
	v_mfma_f32_16x16x32_bf16 v[148:151], v[186:189], v[194:197], v[148:151]
	s_waitcnt lgkmcnt(2)
	v_mfma_f32_16x16x32_bf16 v[144:147], v[190:193], v[194:197], v[144:147]
	v_lshl_add_u64 v[112:113], s[38:39], 0, v[162:163]
	global_load_dwordx4 v[124:127], v[112:113], off
	ds_read_b128 v[250:253], v198 offset:6976
	v_mfma_f32_16x16x32_bf16 v[108:111], v[178:181], v[242:245], v[108:111]
	v_mfma_f32_16x16x32_bf16 v[104:107], v[182:185], v[242:245], v[104:107]
	v_lshl_add_u64 v[112:113], s[38:39], 0, v[164:165]
	global_load_dwordx4 v[120:123], v[112:113], off
	v_mfma_f32_16x16x32_bf16 v[100:103], v[186:189], v[242:245], v[100:103]
	v_mfma_f32_16x16x32_bf16 v[96:99], v[190:193], v[242:245], v[96:99]
	ds_read_b128 v[194:197], v198 offset:9280
	s_waitcnt lgkmcnt(3)
; DI f32x4 mfma16(bf16x8 a, bf16x8 b, f32x4 c) { return __builtin_amdgcn_mfma_f32_16x16x32_bf16(a, b, c, 0, 0, 0); }
; DI void stage4(bf16_t* stg, int row, int col, const f32x4& v, float s) { *(u32x2*)(stg + row * STG_LD + col) = (u32x2){pk2(v[0] * s, v[1] * s), pk2(v[2] * s, v[3] * s)}; }
; template <int MI, int NJ, bool SWAP, class AP, class BP>
; DI void gemm_main(f32x4 (&acc)[MI][NJ], const AP& ap, int a_kstep, const BP& bp, int b_kstep, int nk, bf16_t* smem) {
;     ...
;   for (int kt = 0; kt < nk; ++kt) {
;     const int buf = kt & 1;
;     sstore(buf ^ 1);
;     gload(kt + 2 < nk ? kt + 2 : nk - 1);
;     __builtin_amdgcn_sched_barrier(0);
;     const bf16_t* As = smem + buf * L::STAGE + (wm * 16 * MI + l15) * LDT + quad * 8;
;     const bf16_t* Bs = smem + buf * L::STAGE + L::A_ELEMS + (wn * 16 * NJ + l15) * LDT + quad * 8;
; #pragma unroll
;     for (int ks = 0; ks < 2; ++ks) {
;       if (MI * NJ >= 32 && ks == 1) asm volatile("" ::: "memory");
;       bf16x8 b[NJ];
; #pragma unroll
;       for (int j = 0; j < NJ; ++j) b[j] = *(const bf16x8*)(Bs + j * 16 * LDT + ks * 32);
; #pragma unroll
;       for (int i = 0; i < MI; ++i) {
;         const bf16x8 a = *(const bf16x8*)(As + i * 16 * LDT + ks * 32);
; #pragma unroll
;         for (int j = 0; j < NJ; ++j) acc[i][j] = SWAP ? mfma16(b[j], a, acc[i][j]) : mfma16(a, b[j], acc[i][j]);
;       }
;     }
;     __syncthreads();
;   }
; template <int KIND> DI void mlaup_tile(const Params& p, int layer, int tm, int tn, bf16_t* smem) {
;     ...
; #pragma unroll
;     for (int i = 0; i < 8; ++i) {
;       asm volatile("" ::: "memory");
;       const int row = i * 16 + l15, t = trow0 + row; const float* c = cssq + (size_t)t * 16;
;       const float rs = rsqrtf((c[8] + c[9] + c[10] + c[11]) * (1.f / 256.f) + EPS_);
; #pragma unroll
;       for (int j = 0; j < 4; ++j) stage4(stg, row, j * 16 + quad * 4, acc[i][j], rs);
;     }
	v_mfma_f32_16x16x32_bf16 v[92:95], v[178:181], v[246:249], v[92:95]
	v_lshl_add_u64 v[112:113], s[38:39], 0, v[166:167]
	global_load_dwordx4 v[116:119], v[112:113], off
	v_mfma_f32_16x16x32_bf16 v[88:91], v[182:185], v[246:249], v[88:91]
	v_mfma_f32_16x16x32_bf16 v[84:87], v[186:189], v[246:249], v[84:87]
	v_lshl_add_u64 v[112:113], s[38:39], 0, v[168:169]
	s_add_u32 s38, s2, s40
	s_addc_u32 s39, s3, 0
	v_lshl_add_u64 v[128:129], s[38:39], 0, v[162:163]
	v_lshl_add_u64 v[132:133], s[38:39], 0, v[164:165]
	v_lshl_add_u64 v[136:137], s[38:39], 0, v[166:167]
	v_lshl_add_u64 v[140:141], s[38:39], 0, v[168:169]
	global_load_dwordx4 v[112:115], v[112:113], off
	v_mfma_f32_16x16x32_bf16 v[80:83], v[190:193], v[246:249], v[80:83]
	ds_read_b128 v[242:245], v198 offset:11584
	s_waitcnt lgkmcnt(2)
	v_mfma_f32_16x16x32_bf16 v[76:79], v[178:181], v[250:253], v[76:79]
	v_mfma_f32_16x16x32_bf16 v[72:75], v[182:185], v[250:253], v[72:75]
	s_nop 0
	global_load_dwordx4 v[128:131], v[128:129], off
	v_mfma_f32_16x16x32_bf16 v[68:71], v[186:189], v[250:253], v[68:71]
	v_mfma_f32_16x16x32_bf16 v[64:67], v[190:193], v[250:253], v[64:67]
	s_nop 0
	global_load_dwordx4 v[132:135], v[132:133], off
	ds_read_b128 v[246:249], v198 offset:13888
	s_waitcnt lgkmcnt(2)
	v_mfma_f32_16x16x32_bf16 v[60:63], v[178:181], v[194:197], v[60:63]
	v_mfma_f32_16x16x32_bf16 v[56:59], v[182:185], v[194:197], v[56:59]
	v_mfma_f32_16x16x32_bf16 v[52:55], v[186:189], v[194:197], v[52:55]
	s_nop 0
	global_load_dwordx4 v[136:139], v[136:137], off
	v_mfma_f32_16x16x32_bf16 v[48:51], v[190:193], v[194:197], v[48:51]
	ds_read_b128 v[250:253], v198 offset:16192
	s_waitcnt lgkmcnt(2)
	v_mfma_f32_16x16x32_bf16 v[44:47], v[178:181], v[242:245], v[44:47]
	s_nop 0
	global_load_dwordx4 v[140:143], v[140:141], off
	v_mfma_f32_16x16x32_bf16 v[40:43], v[182:185], v[242:245], v[40:43]
	v_mfma_f32_16x16x32_bf16 v[36:39], v[186:189], v[242:245], v[36:39]
	v_mfma_f32_16x16x32_bf16 v[32:35], v[190:193], v[242:245], v[32:35]
	s_waitcnt lgkmcnt(0)
	s_barrier
	s_add_i32 s33, s33, 1
	s_cmp_lg_u32 s33, 4
	s_cbranch_scc0 .Lgm11_exit
	s_and_b32 s98, s33, 1
	s_mul_i32 s98, s98, 0x12000
	v_add3_u32 v198, s98, v176, v177
	v_add3_u32 v199, s98, v171, v177
	ds_read_b128 v[194:197], v198
	ds_read_b128 v[242:245], v198 offset:2304
	v_mfma_f32_16x16x32_bf16 v[28:31], v[178:181], v[246:249], v[28:31]
	v_mfma_f32_16x16x32_bf16 v[12:15], v[178:181], v[250:253], v[12:15]
	ds_read_b128 v[178:181], v199 offset:36864
	v_mfma_f32_16x16x32_bf16 v[24:27], v[182:185], v[246:249], v[24:27]
	v_mfma_f32_16x16x32_bf16 v[8:11], v[182:185], v[250:253], v[8:11]
	ds_read_b128 v[182:185], v199 offset:39168
	v_mfma_f32_16x16x32_bf16 v[20:23], v[186:189], v[246:249], v[20:23]
	v_mfma_f32_16x16x32_bf16 v[4:7], v[186:189], v[250:253], v[4:7]
	ds_read_b128 v[186:189], v199 offset:41472
	v_mfma_f32_16x16x32_bf16 v[16:19], v[190:193], v[246:249], v[16:19]
	v_mfma_f32_16x16x32_bf16 v[0:3], v[190:193], v[250:253], v[0:3]
	ds_read_b128 v[190:193], v199 offset:43776
	s_branch .Lgm11_main
.Lgm11_exit:
	v_mfma_f32_16x16x32_bf16 v[28:31], v[178:181], v[246:249], v[28:31]
	v_mfma_f32_16x16x32_bf16 v[12:15], v[178:181], v[250:253], v[12:15]
	v_mfma_f32_16x16x32_bf16 v[24:27], v[182:185], v[246:249], v[24:27]
	v_mfma_f32_16x16x32_bf16 v[8:11], v[182:185], v[250:253], v[8:11]
	v_mfma_f32_16x16x32_bf16 v[20:23], v[186:189], v[246:249], v[20:23]
	v_mfma_f32_16x16x32_bf16 v[4:7], v[186:189], v[250:253], v[4:7]
	v_mfma_f32_16x16x32_bf16 v[16:19], v[190:193], v[246:249], v[16:19]
	v_mfma_f32_16x16x32_bf16 v[0:3], v[190:193], v[250:253], v[0:3]
	s_nop 7
	s_waitcnt vmcnt(4)
	v_mov_b32_e32 v113, v220
	v_mov_b32_e32 v116, v220
	v_readlane_b32 s0, v237, 29
	v_ashrrev_i32_e32 v112, 1, v116
	v_and_b32_e32 v112, 0xffffff80, v112
	v_and_b32_e32 v117, 15, v113
	v_lshl_add_u32 v112, s16, 8, v112
	v_or_b32_e32 v114, v112, v117
	v_ashrrev_i32_e32 v115, 31, v114
	v_lshlrev_b64 v[118:119], 6, v[114:115]
	v_lshl_add_u64 v[118:119], s[4:5], 0, v[118:119]
	global_load_dwordx4 v[118:121], v[118:119], off offset:32
	v_lshrrev_b32_e32 v115, 6, v116
	v_lshrrev_b32_e32 v122, 1, v113
	v_mul_lo_u32 v115, v115, s30
	v_and_or_b32 v122, v122, 24, v115
	v_mad_u32_u24 v117, v117, s27, v122
	v_or_b32_e32 v122, 16, v114
	v_ashrrev_i32_e32 v123, 31, v122
	v_readlane_b32 s1, v237, 30
	s_lshl_b32 s8, s8, 9
	v_readlane_b32 s37, v240, 6
	s_waitcnt vmcnt(0)
	v_add_f32_e32 v118, v118, v119
	v_add_f32_e32 v118, v118, v120
	v_add_f32_e32 v118, v118, v121
	v_fmamk_f32 v118, v118, 0x3b800000, v170
	v_mul_f32_e32 v119, 0x4b800000, v118
	v_cmp_gt_f32_e32 vcc, s29, v118
	s_nop 1
	v_cndmask_b32_e32 v118, v118, v119, vcc
	v_rsq_f32_e32 v120, v118
	v_lshlrev_b64 v[118:119], 6, v[122:123]
	v_lshl_add_u64 v[118:119], s[4:5], 0, v[118:119]
	v_mul_f32_e32 v121, 0x45800000, v120
	v_cndmask_b32_e32 v120, v120, v121, vcc
	v_pk_mul_f32 v[122:123], v[156:157], v[120:121] op_sel_hi:[1,0]
	v_pk_mul_f32 v[124:125], v[158:159], v[120:121] op_sel_hi:[1,0]
	v_pk_mul_f32 v[126:127], v[152:153], v[120:121] op_sel_hi:[1,0]
	v_pk_mul_f32 v[128:129], v[154:155], v[120:121] op_sel_hi:[1,0]
	v_pk_mul_f32 v[130:131], v[148:149], v[120:121] op_sel_hi:[1,0]
	v_pk_mul_f32 v[132:133], v[150:151], v[120:121] op_sel_hi:[1,0]
	v_pk_mul_f32 v[134:135], v[144:145], v[120:121] op_sel_hi:[1,0]
	v_pk_mul_f32 v[120:121], v[146:147], v[120:121] op_sel_hi:[1,0]
	v_cvt_pk_bf16_f32 v122, v122, v123
	v_cvt_pk_bf16_f32 v123, v124, v125
	v_cvt_pk_bf16_f32 v124, v126, v127
	v_cvt_pk_bf16_f32 v125, v128, v129
	v_cvt_pk_bf16_f32 v126, v130, v131
	v_cvt_pk_bf16_f32 v127, v132, v133
	v_cvt_pk_bf16_f32 v128, v134, v135
	v_cvt_pk_bf16_f32 v129, v120, v121
	ds_write2_b64 v117, v[122:123], v[124:125] offset1:4
	ds_write2_b64 v117, v[126:127], v[128:129] offset0:8 offset1:12
	global_load_dwordx4 v[118:121], v[118:119], off offset:32
	v_or_b32_e32 v122, 32, v114
	v_add_u32_e32 v124, 0x800, v117
	v_ashrrev_i32_e32 v123, 31, v122
	s_waitcnt vmcnt(0)
; DI void stage4(bf16_t* stg, int row, int col, const f32x4& v, float s) { *(u32x2*)(stg + row * STG_LD + col) = (u32x2){pk2(v[0] * s, v[1] * s), pk2(v[2] * s, v[3] * s)}; }
; template <int KIND> DI void mlaup_tile(const Params& p, int layer, int tm, int tn, bf16_t* smem) {
;     ...
; #pragma unroll
;     for (int i = 0; i < 8; ++i) {
;       asm volatile("" ::: "memory");
;       const int row = i * 16 + l15, t = trow0 + row; const float* c = cssq + (size_t)t * 16;
;       const float rs = rsqrtf((c[8] + c[9] + c[10] + c[11]) * (1.f / 256.f) + EPS_);
; #pragma unroll
;       for (int j = 0; j < 4; ++j) stage4(stg, row, j * 16 + quad * 4, acc[i][j], rs);
;     }
	v_add_f32_e32 v118, v118, v119
	v_add_f32_e32 v118, v118, v120
	v_add_f32_e32 v118, v118, v121
	v_fmamk_f32 v118, v118, 0x3b800000, v170
	v_mul_f32_e32 v119, 0x4b800000, v118
	v_cmp_gt_f32_e32 vcc, s29, v118
	s_nop 1
	v_cndmask_b32_e32 v118, v118, v119, vcc
	v_rsq_f32_e32 v120, v118
	v_lshlrev_b64 v[118:119], 6, v[122:123]
	v_lshl_add_u64 v[118:119], s[4:5], 0, v[118:119]
	v_mul_f32_e32 v121, 0x45800000, v120
	v_cndmask_b32_e32 v120, v120, v121, vcc
	v_pk_mul_f32 v[108:109], v[108:109], v[120:121] op_sel_hi:[1,0]
	v_pk_mul_f32 v[110:111], v[110:111], v[120:121] op_sel_hi:[1,0]
	v_pk_mul_f32 v[104:105], v[104:105], v[120:121] op_sel_hi:[1,0]
	v_pk_mul_f32 v[106:107], v[106:107], v[120:121] op_sel_hi:[1,0]
	v_pk_mul_f32 v[100:101], v[100:101], v[120:121] op_sel_hi:[1,0]
	v_pk_mul_f32 v[102:103], v[102:103], v[120:121] op_sel_hi:[1,0]
	v_pk_mul_f32 v[96:97], v[96:97], v[120:121] op_sel_hi:[1,0]
	v_pk_mul_f32 v[98:99], v[98:99], v[120:121] op_sel_hi:[1,0]
	v_cvt_pk_bf16_f32 v108, v108, v109
	v_cvt_pk_bf16_f32 v109, v110, v111
	v_cvt_pk_bf16_f32 v104, v104, v105
	v_cvt_pk_bf16_f32 v105, v106, v107
	v_cvt_pk_bf16_f32 v100, v100, v101
	v_cvt_pk_bf16_f32 v101, v102, v103
	v_cvt_pk_bf16_f32 v96, v96, v97
	v_cvt_pk_bf16_f32 v97, v98, v99
	ds_write2_b64 v124, v[108:109], v[104:105] offset0:32 offset1:36
	ds_write2_b64 v124, v[100:101], v[96:97] offset0:40 offset1:44
	global_load_dwordx4 v[96:99], v[118:119], off offset:32
	v_or_b32_e32 v100, 48, v114
	v_add_u32_e32 v102, 0x1000, v117
	v_ashrrev_i32_e32 v101, 31, v100
	s_waitcnt vmcnt(0)
	v_add_f32_e32 v96, v96, v97
	v_add_f32_e32 v96, v96, v98
	v_add_f32_e32 v96, v96, v99
	v_fmamk_f32 v96, v96, 0x3b800000, v170
	v_mul_f32_e32 v97, 0x4b800000, v96
	v_cmp_gt_f32_e32 vcc, s29, v96
	s_nop 1
	v_cndmask_b32_e32 v96, v96, v97, vcc
	v_rsq_f32_e32 v98, v96
	v_lshlrev_b64 v[96:97], 6, v[100:101]
	v_lshl_add_u64 v[96:97], s[4:5], 0, v[96:97]
	v_mul_f32_e32 v99, 0x45800000, v98
	v_cndmask_b32_e32 v98, v98, v99, vcc
	v_pk_mul_f32 v[92:93], v[92:93], v[98:99] op_sel_hi:[1,0]
	v_pk_mul_f32 v[94:95], v[94:95], v[98:99] op_sel_hi:[1,0]
	v_pk_mul_f32 v[88:89], v[88:89], v[98:99] op_sel_hi:[1,0]
	v_pk_mul_f32 v[90:91], v[90:91], v[98:99] op_sel_hi:[1,0]
	v_pk_mul_f32 v[84:85], v[84:85], v[98:99] op_sel_hi:[1,0]
	v_pk_mul_f32 v[86:87], v[86:87], v[98:99] op_sel_hi:[1,0]
	v_pk_mul_f32 v[80:81], v[80:81], v[98:99] op_sel_hi:[1,0]
	v_pk_mul_f32 v[82:83], v[82:83], v[98:99] op_sel_hi:[1,0]
	v_cvt_pk_bf16_f32 v92, v92, v93
	v_cvt_pk_bf16_f32 v93, v94, v95
	v_cvt_pk_bf16_f32 v88, v88, v89
	v_cvt_pk_bf16_f32 v89, v90, v91
	v_cvt_pk_bf16_f32 v84, v84, v85
	v_cvt_pk_bf16_f32 v85, v86, v87
	v_cvt_pk_bf16_f32 v80, v80, v81
	v_cvt_pk_bf16_f32 v81, v82, v83
	ds_write2_b64 v102, v[92:93], v[88:89] offset0:64 offset1:68
	ds_write2_b64 v102, v[84:85], v[80:81] offset0:72 offset1:76
	global_load_dwordx4 v[80:83], v[96:97], off offset:32
	v_or_b32_e32 v84, 64, v114
	v_add_u32_e32 v86, 0x1800, v117
	v_ashrrev_i32_e32 v85, 31, v84
	s_waitcnt vmcnt(0)
	v_add_f32_e32 v80, v80, v81
	v_add_f32_e32 v80, v80, v82
	v_add_f32_e32 v80, v80, v83
	v_fmamk_f32 v80, v80, 0x3b800000, v170
	v_mul_f32_e32 v81, 0x4b800000, v80
	v_cmp_gt_f32_e32 vcc, s29, v80
	s_nop 1
	v_cndmask_b32_e32 v80, v80, v81, vcc
	v_rsq_f32_e32 v82, v80
	v_lshlrev_b64 v[80:81], 6, v[84:85]
	v_lshl_add_u64 v[80:81], s[4:5], 0, v[80:81]
	v_mul_f32_e32 v83, 0x45800000, v82
	v_cndmask_b32_e32 v82, v82, v83, vcc
	v_pk_mul_f32 v[76:77], v[76:77], v[82:83] op_sel_hi:[1,0]
	v_pk_mul_f32 v[78:79], v[78:79], v[82:83] op_sel_hi:[1,0]
	v_pk_mul_f32 v[72:73], v[72:73], v[82:83] op_sel_hi:[1,0]
	v_pk_mul_f32 v[74:75], v[74:75], v[82:83] op_sel_hi:[1,0]
	v_pk_mul_f32 v[68:69], v[68:69], v[82:83] op_sel_hi:[1,0]
	v_pk_mul_f32 v[70:71], v[70:71], v[82:83] op_sel_hi:[1,0]
	v_pk_mul_f32 v[64:65], v[64:65], v[82:83] op_sel_hi:[1,0]
	v_pk_mul_f32 v[66:67], v[66:67], v[82:83] op_sel_hi:[1,0]
	v_cvt_pk_bf16_f32 v76, v76, v77
	v_cvt_pk_bf16_f32 v77, v78, v79
	v_cvt_pk_bf16_f32 v72, v72, v73
	v_cvt_pk_bf16_f32 v73, v74, v75
	v_cvt_pk_bf16_f32 v68, v68, v69
	v_cvt_pk_bf16_f32 v69, v70, v71
	v_cvt_pk_bf16_f32 v64, v64, v65
	v_cvt_pk_bf16_f32 v65, v66, v67
	ds_write2_b64 v86, v[76:77], v[72:73] offset0:96 offset1:100
	ds_write2_b64 v86, v[68:69], v[64:65] offset0:104 offset1:108
	global_load_dwordx4 v[64:67], v[80:81], off offset:32
	v_or_b32_e32 v68, 0x50, v114
	v_add_u32_e32 v70, 0x2000, v117
	v_ashrrev_i32_e32 v69, 31, v68
	s_waitcnt vmcnt(0)
	v_add_f32_e32 v64, v64, v65
	v_add_f32_e32 v64, v64, v66
	v_add_f32_e32 v64, v64, v67
	v_fmamk_f32 v64, v64, 0x3b800000, v170
	v_mul_f32_e32 v65, 0x4b800000, v64
	v_cmp_gt_f32_e32 vcc, s29, v64
	s_nop 1
	v_cndmask_b32_e32 v64, v64, v65, vcc
	v_rsq_f32_e32 v66, v64
	v_lshlrev_b64 v[64:65], 6, v[68:69]
	v_lshl_add_u64 v[64:65], s[4:5], 0, v[64:65]
	v_mul_f32_e32 v67, 0x45800000, v66
	v_cndmask_b32_e32 v66, v66, v67, vcc
	v_pk_mul_f32 v[60:61], v[60:61], v[66:67] op_sel_hi:[1,0]
	v_pk_mul_f32 v[62:63], v[62:63], v[66:67] op_sel_hi:[1,0]
	v_pk_mul_f32 v[56:57], v[56:57], v[66:67] op_sel_hi:[1,0]
	v_pk_mul_f32 v[58:59], v[58:59], v[66:67] op_sel_hi:[1,0]
	v_pk_mul_f32 v[52:53], v[52:53], v[66:67] op_sel_hi:[1,0]
	v_pk_mul_f32 v[54:55], v[54:55], v[66:67] op_sel_hi:[1,0]
	v_pk_mul_f32 v[48:49], v[48:49], v[66:67] op_sel_hi:[1,0]
	v_pk_mul_f32 v[50:51], v[50:51], v[66:67] op_sel_hi:[1,0]
	v_cvt_pk_bf16_f32 v60, v60, v61
	v_cvt_pk_bf16_f32 v61, v62, v63
	v_cvt_pk_bf16_f32 v56, v56, v57
	v_cvt_pk_bf16_f32 v57, v58, v59
	v_cvt_pk_bf16_f32 v52, v52, v53
	v_cvt_pk_bf16_f32 v53, v54, v55
	v_cvt_pk_bf16_f32 v48, v48, v49
	v_cvt_pk_bf16_f32 v49, v50, v51
	ds_write2_b64 v70, v[60:61], v[56:57] offset0:128 offset1:132
	ds_write2_b64 v70, v[52:53], v[48:49] offset0:136 offset1:140
	global_load_dwordx4 v[48:51], v[64:65], off offset:32
	v_or_b32_e32 v52, 0x60, v114
	v_add_u32_e32 v54, 0x2800, v117
	v_ashrrev_i32_e32 v53, 31, v52
	s_waitcnt vmcnt(0)
; DI void stage4(bf16_t* stg, int row, int col, const f32x4& v, float s) { *(u32x2*)(stg + row * STG_LD + col) = (u32x2){pk2(v[0] * s, v[1] * s), pk2(v[2] * s, v[3] * s)}; }
; template <int KIND> DI void mlaup_tile(const Params& p, int layer, int tm, int tn, bf16_t* smem) {
;     ...
; #pragma unroll
;     for (int i = 0; i < 8; ++i) {
;       asm volatile("" ::: "memory");
;       const int row = i * 16 + l15, t = trow0 + row; const float* c = cssq + (size_t)t * 16;
;       const float rs = rsqrtf((c[8] + c[9] + c[10] + c[11]) * (1.f / 256.f) + EPS_);
; #pragma unroll
;       for (int j = 0; j < 4; ++j) stage4(stg, row, j * 16 + quad * 4, acc[i][j], rs);
;     }
;     stage_out<128, 64, STG_LD>(stg, (bf16_t*)(p.ws + O_MLAKN) + (size_t)trow0 * 512 + (tn - 3) * 256 + wn * 64, (size_t)512, lane);
	v_add_f32_e32 v48, v48, v49
	v_add_f32_e32 v48, v48, v50
	v_add_f32_e32 v48, v48, v51
	v_fmamk_f32 v48, v48, 0x3b800000, v170
	v_mul_f32_e32 v49, 0x4b800000, v48
	v_cmp_gt_f32_e32 vcc, s29, v48
	s_nop 1
	v_cndmask_b32_e32 v48, v48, v49, vcc
	v_rsq_f32_e32 v50, v48
	v_lshlrev_b64 v[48:49], 6, v[52:53]
	v_lshl_add_u64 v[48:49], s[4:5], 0, v[48:49]
	v_mul_f32_e32 v51, 0x45800000, v50
	v_cndmask_b32_e32 v50, v50, v51, vcc
	v_pk_mul_f32 v[44:45], v[44:45], v[50:51] op_sel_hi:[1,0]
	v_pk_mul_f32 v[46:47], v[46:47], v[50:51] op_sel_hi:[1,0]
	v_pk_mul_f32 v[40:41], v[40:41], v[50:51] op_sel_hi:[1,0]
	v_pk_mul_f32 v[42:43], v[42:43], v[50:51] op_sel_hi:[1,0]
	v_pk_mul_f32 v[36:37], v[36:37], v[50:51] op_sel_hi:[1,0]
	v_pk_mul_f32 v[38:39], v[38:39], v[50:51] op_sel_hi:[1,0]
	v_pk_mul_f32 v[32:33], v[32:33], v[50:51] op_sel_hi:[1,0]
	v_pk_mul_f32 v[34:35], v[34:35], v[50:51] op_sel_hi:[1,0]
	v_cvt_pk_bf16_f32 v44, v44, v45
	v_cvt_pk_bf16_f32 v45, v46, v47
	v_cvt_pk_bf16_f32 v40, v40, v41
	v_cvt_pk_bf16_f32 v41, v42, v43
	v_cvt_pk_bf16_f32 v36, v36, v37
	v_cvt_pk_bf16_f32 v37, v38, v39
	v_cvt_pk_bf16_f32 v32, v32, v33
	v_cvt_pk_bf16_f32 v33, v34, v35
	ds_write2_b64 v54, v[44:45], v[40:41] offset0:160 offset1:164
	ds_write2_b64 v54, v[36:37], v[32:33] offset0:168 offset1:172
	global_load_dwordx4 v[32:35], v[48:49], off offset:32
	v_or_b32_e32 v36, 0x70, v114
	v_add_u32_e32 v38, 0x3000, v117
	v_ashrrev_i32_e32 v37, 31, v36
	v_add_u32_e32 v50, 0x3800, v117
	v_mov_b32_e32 v39, v161
	v_mov_b32_e32 v41, v161
	v_mov_b32_e32 v43, v161
	v_mov_b32_e32 v45, v161
	v_mov_b32_e32 v47, v161
	s_waitcnt vmcnt(0)
	v_add_f32_e32 v32, v32, v33
	v_add_f32_e32 v32, v32, v34
	v_add_f32_e32 v32, v32, v35
	v_fmamk_f32 v32, v32, 0x3b800000, v170
	v_mul_f32_e32 v33, 0x4b800000, v32
	v_cmp_gt_f32_e32 vcc, s29, v32
	s_nop 1
	v_cndmask_b32_e32 v32, v32, v33, vcc
	v_rsq_f32_e32 v34, v32
	v_lshlrev_b64 v[32:33], 6, v[36:37]
	v_lshl_add_u64 v[32:33], s[4:5], 0, v[32:33]
	v_mov_b32_e32 v37, v161
	v_mul_f32_e32 v35, 0x45800000, v34
	v_cndmask_b32_e32 v34, v34, v35, vcc
	v_pk_mul_f32 v[28:29], v[28:29], v[34:35] op_sel_hi:[1,0]
	v_pk_mul_f32 v[30:31], v[30:31], v[34:35] op_sel_hi:[1,0]
	v_pk_mul_f32 v[24:25], v[24:25], v[34:35] op_sel_hi:[1,0]
	v_pk_mul_f32 v[26:27], v[26:27], v[34:35] op_sel_hi:[1,0]
	v_pk_mul_f32 v[20:21], v[20:21], v[34:35] op_sel_hi:[1,0]
	v_pk_mul_f32 v[22:23], v[22:23], v[34:35] op_sel_hi:[1,0]
	v_pk_mul_f32 v[16:17], v[16:17], v[34:35] op_sel_hi:[1,0]
	v_pk_mul_f32 v[18:19], v[18:19], v[34:35] op_sel_hi:[1,0]
	v_cvt_pk_bf16_f32 v28, v28, v29
	v_cvt_pk_bf16_f32 v29, v30, v31
	v_cvt_pk_bf16_f32 v24, v24, v25
	v_cvt_pk_bf16_f32 v25, v26, v27
	v_cvt_pk_bf16_f32 v20, v20, v21
	v_cvt_pk_bf16_f32 v21, v22, v23
	v_cvt_pk_bf16_f32 v16, v16, v17
	v_cvt_pk_bf16_f32 v17, v18, v19
	ds_write2_b64 v38, v[28:29], v[24:25] offset0:192 offset1:196
	ds_write2_b64 v38, v[20:21], v[16:17] offset0:200 offset1:204
	global_load_dwordx4 v[16:19], v[32:33], off offset:32
	v_lshlrev_b32_e32 v22, 4, v113
	v_bfe_u32 v24, v113, 3, 3
	v_ashrrev_i32_e32 v113, 31, v112
	v_lshlrev_b64 v[48:49], 10, v[112:113]
	v_and_b32_e32 v20, 0xc0, v116
	v_lshl_add_u64 v[48:49], s[0:1], 0, v[48:49]
	v_lshlrev_b32_e32 v160, 1, v20
	v_lshl_add_u64 v[48:49], v[48:49], 0, s[8:9]
	v_lshl_add_u64 v[48:49], v[48:49], 0, v[160:161]
	v_and_b32_e32 v160, 0x70, v22
	v_or_b32_e32 v20, v115, v160
	v_lshl_add_u64 v[48:49], v[48:49], 0, v[160:161]
	v_lshlrev_b32_e32 v160, 10, v24
	v_mov_b32_e32 v21, v161
	v_mov_b32_e32 v23, v161
	v_mov_b32_e32 v25, v161
	v_mov_b32_e32 v27, v161
	v_mov_b32_e32 v29, v161
	v_mov_b32_e32 v31, v161
	v_mov_b32_e32 v33, v161
	v_mov_b32_e32 v35, v161
	v_mad_u32_u24 v60, v24, s27, v20
	v_lshl_add_u64 v[64:65], v[48:49], 0, v[160:161]
	v_or_b32_e32 v20, 0x2000, v160
	v_or_b32_e32 v22, 0x4000, v160
	v_or_b32_e32 v24, 0x6000, v160
	v_or_b32_e32 v26, 0x8000, v160
	v_or_b32_e32 v28, 0xa000, v160
	v_or_b32_e32 v30, 0xc000, v160
	v_or_b32_e32 v32, 0xe000, v160
	v_or_b32_e32 v34, 0x10000, v160
	v_or_b32_e32 v36, 0x12000, v160
	v_or_b32_e32 v38, 0x14000, v160
	v_or_b32_e32 v40, 0x16000, v160
	v_or_b32_e32 v42, 0x18000, v160
	v_or_b32_e32 v44, 0x1a000, v160
	v_or_b32_e32 v46, 0x1c000, v160
	v_or_b32_e32 v160, 0x1e000, v160
	v_lshl_add_u64 v[66:67], v[48:49], 0, v[20:21]
	v_lshl_add_u64 v[68:69], v[48:49], 0, v[22:23]
	v_lshl_add_u64 v[70:71], v[48:49], 0, v[24:25]
	v_lshl_add_u64 v[72:73], v[48:49], 0, v[26:27]
	v_lshl_add_u64 v[74:75], v[48:49], 0, v[28:29]
	v_lshl_add_u64 v[76:77], v[48:49], 0, v[30:31]
	v_lshl_add_u64 v[78:79], v[48:49], 0, v[32:33]
	v_lshl_add_u64 v[80:81], v[48:49], 0, v[34:35]
	v_lshl_add_u64 v[82:83], v[48:49], 0, v[36:37]
	v_lshl_add_u64 v[84:85], v[48:49], 0, v[38:39]
	v_lshl_add_u64 v[86:87], v[48:49], 0, v[40:41]
	v_lshl_add_u64 v[88:89], v[48:49], 0, v[42:43]
	v_lshl_add_u64 v[90:91], v[48:49], 0, v[44:45]
	v_lshl_add_u64 v[92:93], v[48:49], 0, v[46:47]
	v_lshl_add_u64 v[94:95], v[48:49], 0, v[160:161]
	s_waitcnt vmcnt(0)
; DI void stage4(bf16_t* stg, int row, int col, const f32x4& v, float s) { *(u32x2*)(stg + row * STG_LD + col) = (u32x2){pk2(v[0] * s, v[1] * s), pk2(v[2] * s, v[3] * s)}; }
; template <int ROWS, int COLS, int LD> DI void stage_out(const bf16_t* stg, bf16_t* dst, size_t ld, int lane) {
;   asm volatile("s_waitcnt lgkmcnt(0)" ::: "memory");
;   constexpr int CPR = COLS / 8, IT = ROWS * CPR / 64;
; #pragma unroll
;   for (int it = 0; it < IT; ++it) {
;     const int idx = it * 64 + lane, r = idx / CPR, c = idx % CPR;
;     __builtin_nontemporal_store(*(const u32x4*)(stg + r * LD + c * 8), (u32x4*)(dst + (size_t)r * ld + c * 8));
;   }
; template <int KIND> DI void mlaup_tile(const Params& p, int layer, int tm, int tn, bf16_t* smem) {
;     ...
;     for (int i = 0; i < 8; ++i) {
;       asm volatile("" ::: "memory");
;       const int row = i * 16 + l15, t = trow0 + row; const float* c = cssq + (size_t)t * 16;
;       const float rs = rsqrtf((c[8] + c[9] + c[10] + c[11]) * (1.f / 256.f) + EPS_);
; #pragma unroll
;       for (int j = 0; j < 4; ++j) stage4(stg, row, j * 16 + quad * 4, acc[i][j], rs);
;     }
;     stage_out<128, 64, STG_LD>(stg, (bf16_t*)(p.ws + O_MLAKN) + (size_t)trow0 * 512 + (tn - 3) * 256 + wn * 64, (size_t)512, lane);
	v_add_f32_e32 v16, v16, v17
	v_add_f32_e32 v16, v16, v18
	v_add_f32_e32 v16, v16, v19
	v_fmamk_f32 v16, v16, 0x3b800000, v170
	v_mul_f32_e32 v17, 0x4b800000, v16
	v_cmp_gt_f32_e32 vcc, s29, v16
	s_nop 1
	v_cndmask_b32_e32 v16, v16, v17, vcc
	v_rsq_f32_e32 v16, v16
	s_nop 0
	v_mul_f32_e32 v17, 0x45800000, v16
	v_cndmask_b32_e32 v16, v16, v17, vcc
	v_pk_mul_f32 v[12:13], v[12:13], v[16:17] op_sel_hi:[1,0]
	v_pk_mul_f32 v[14:15], v[14:15], v[16:17] op_sel_hi:[1,0]
	v_pk_mul_f32 v[8:9], v[8:9], v[16:17] op_sel_hi:[1,0]
	v_pk_mul_f32 v[10:11], v[10:11], v[16:17] op_sel_hi:[1,0]
	v_pk_mul_f32 v[4:5], v[4:5], v[16:17] op_sel_hi:[1,0]
	v_pk_mul_f32 v[6:7], v[6:7], v[16:17] op_sel_hi:[1,0]
	v_pk_mul_f32 v[0:1], v[0:1], v[16:17] op_sel_hi:[1,0]
	v_pk_mul_f32 v[2:3], v[2:3], v[16:17] op_sel_hi:[1,0]
	v_cvt_pk_bf16_f32 v12, v12, v13
	v_cvt_pk_bf16_f32 v13, v14, v15
	v_cvt_pk_bf16_f32 v8, v8, v9
	v_cvt_pk_bf16_f32 v9, v10, v11
	v_cvt_pk_bf16_f32 v4, v4, v5
	v_cvt_pk_bf16_f32 v5, v6, v7
	v_cvt_pk_bf16_f32 v0, v0, v1
	v_cvt_pk_bf16_f32 v1, v2, v3
	ds_write2_b64 v50, v[12:13], v[8:9] offset0:224 offset1:228
	ds_write2_b64 v50, v[4:5], v[0:1] offset0:232 offset1:236
	s_waitcnt lgkmcnt(0)
	ds_read_b128 v[0:3], v60
	ds_read_b128 v[4:7], v60 offset:1152
	ds_read_b128 v[8:11], v60 offset:2304
	ds_read_b128 v[12:15], v60 offset:3456
	ds_read_b128 v[16:19], v60 offset:4608
	ds_read_b128 v[20:23], v60 offset:5760
	ds_read_b128 v[24:27], v60 offset:6912
	ds_read_b128 v[28:31], v60 offset:8064
	ds_read_b128 v[32:35], v60 offset:9216
	ds_read_b128 v[36:39], v60 offset:10368
	ds_read_b128 v[40:43], v60 offset:11520
	ds_read_b128 v[44:47], v60 offset:12672
	ds_read_b128 v[48:51], v60 offset:13824
	ds_read_b128 v[52:55], v60 offset:14976
	ds_read_b128 v[56:59], v60 offset:16128
	ds_read_b128 v[60:63], v60 offset:17280
	s_waitcnt lgkmcnt(14)
	global_store_dwordx4 v[64:65], v[0:3], off nt
	global_store_dwordx4 v[66:67], v[4:7], off nt
	s_waitcnt lgkmcnt(13)
	global_store_dwordx4 v[68:69], v[8:11], off nt
	s_waitcnt lgkmcnt(12)
	global_store_dwordx4 v[70:71], v[12:15], off nt
	s_waitcnt lgkmcnt(11)
	global_store_dwordx4 v[72:73], v[16:19], off nt
	s_waitcnt lgkmcnt(10)
	global_store_dwordx4 v[74:75], v[20:23], off nt
	s_waitcnt lgkmcnt(9)
	global_store_dwordx4 v[76:77], v[24:27], off nt
	s_waitcnt lgkmcnt(8)
	global_store_dwordx4 v[78:79], v[28:31], off nt
	s_waitcnt lgkmcnt(7)
	global_store_dwordx4 v[80:81], v[32:35], off nt
	s_waitcnt lgkmcnt(6)
	global_store_dwordx4 v[82:83], v[36:39], off nt
	s_waitcnt lgkmcnt(5)
	global_store_dwordx4 v[84:85], v[40:43], off nt
	s_waitcnt lgkmcnt(4)
	global_store_dwordx4 v[86:87], v[44:47], off nt
	s_waitcnt lgkmcnt(3)
	global_store_dwordx4 v[88:89], v[48:51], off nt
	s_waitcnt lgkmcnt(2)
	global_store_dwordx4 v[90:91], v[52:55], off nt
	s_waitcnt lgkmcnt(1)
	global_store_dwordx4 v[92:93], v[56:59], off nt
	s_waitcnt lgkmcnt(0)
	global_store_dwordx4 v[94:95], v[60:63], off nt
	s_barrier

; DI f32x4 mfma16(bf16x8 a, bf16x8 b, f32x4 c) { return __builtin_amdgcn_mfma_f32_16x16x32_bf16(a, b, c, 0, 0, 0); }
; template <int MI, int NJ, bool SWAP, class AP, class BP>
; DI void gemm_main(f32x4 (&acc)[MI][NJ], const AP& ap, int a_kstep, const BP& bp, int b_kstep, int nk, bf16_t* smem) {
;     ...
;   for (int kt = 0; kt < nk; ++kt) {
;     const int buf = kt & 1;
;     sstore(buf ^ 1);
;     gload(kt + 2 < nk ? kt + 2 : nk - 1);
;     __builtin_amdgcn_sched_barrier(0);
;     const bf16_t* As = smem + buf * L::STAGE + (wm * 16 * MI + l15) * LDT + quad * 8;
;     const bf16_t* Bs = smem + buf * L::STAGE + L::A_ELEMS + (wn * 16 * NJ + l15) * LDT + quad * 8;
; #pragma unroll
;     for (int ks = 0; ks < 2; ++ks) {
;       if (MI * NJ >= 32 && ks == 1) asm volatile("" ::: "memory");
;       bf16x8 b[NJ];
; #pragma unroll
;       for (int j = 0; j < NJ; ++j) b[j] = *(const bf16x8*)(Bs + j * 16 * LDT + ks * 32);
; #pragma unroll
;       for (int i = 0; i < MI; ++i) {
;         const bf16x8 a = *(const bf16x8*)(As + i * 16 * LDT + ks * 32);
; #pragma unroll
;         for (int j = 0; j < NJ; ++j) acc[i][j] = SWAP ? mfma16(b[j], a, acc[i][j]) : mfma16(a, b[j], acc[i][j]);
;       }
;     }
.LBB0_1434:
	s_and_b32 s98, s8, 1
	s_mul_i32 s98, s98, 0x12000
	v_add3_u32 v198, s98, v176, v177
	v_add3_u32 v199, s98, v171, v177
	ds_read_b128 v[194:197], v198
	ds_read_b128 v[242:245], v198 offset:2304
	ds_read_b128 v[178:181], v199 offset:36864
	ds_read_b128 v[182:185], v199 offset:39168
	ds_read_b128 v[186:189], v199 offset:41472
	ds_read_b128 v[190:193], v199 offset:43776
.Lgm12_main:
	ds_read_b128 v[246:249], v198 offset:4608
	s_waitcnt lgkmcnt(4)
	v_mfma_f32_16x16x32_bf16 v[124:127], v[194:197], v[178:181], v[124:127]
	s_waitcnt lgkmcnt(3)
	v_mfma_f32_16x16x32_bf16 v[120:123], v[194:197], v[182:185], v[120:123]
	s_waitcnt lgkmcnt(2)
	v_mfma_f32_16x16x32_bf16 v[116:119], v[194:197], v[186:189], v[116:119]
	s_waitcnt lgkmcnt(1)
	v_mfma_f32_16x16x32_bf16 v[112:115], v[194:197], v[190:193], v[112:115]
	s_and_b32 s17, s8, 1
	s_xor_b32 s33, s17, 1
	s_mul_i32 s33, s33, 0x12000
	v_lshlrev_b32_e32 v254, 1, v160
	v_add3_u32 v254, s33, v254, v172
	s_waitcnt vmcnt(7)
	ds_write_b128 v254, v[140:143]
	ds_read_b128 v[250:253], v198 offset:6912
	v_mfma_f32_16x16x32_bf16 v[108:111], v[242:245], v[178:181], v[108:111]
	v_mfma_f32_16x16x32_bf16 v[104:107], v[242:245], v[182:185], v[104:107]
	v_mfma_f32_16x16x32_bf16 v[100:103], v[242:245], v[186:189], v[100:103]
	v_mfma_f32_16x16x32_bf16 v[96:99], v[242:245], v[190:193], v[96:99]
	v_lshlrev_b32_e32 v140, 1, v173
	v_add3_u32 v140, s33, v140, v172
	s_waitcnt vmcnt(6)
	ds_write_b128 v140, v[136:139]
	ds_read_b128 v[194:197], v198 offset:9216
	s_waitcnt lgkmcnt(4)
	v_mfma_f32_16x16x32_bf16 v[92:95], v[246:249], v[178:181], v[92:95]
	v_mfma_f32_16x16x32_bf16 v[88:91], v[246:249], v[182:185], v[88:91]
	v_mfma_f32_16x16x32_bf16 v[84:87], v[246:249], v[186:189], v[84:87]
	v_mfma_f32_16x16x32_bf16 v[80:83], v[246:249], v[190:193], v[80:83]
	ds_read_b128 v[242:245], v198 offset:11520
	s_waitcnt lgkmcnt(3)
	v_mfma_f32_16x16x32_bf16 v[76:79], v[250:253], v[178:181], v[76:79]
	v_lshlrev_b32_e32 v136, 1, v174
	v_add3_u32 v136, s33, v136, v172
	s_waitcnt vmcnt(5)
	ds_write_b128 v136, v[132:135]
	v_mfma_f32_16x16x32_bf16 v[72:75], v[250:253], v[182:185], v[72:75]
	v_mfma_f32_16x16x32_bf16 v[68:71], v[250:253], v[186:189], v[68:71]
	v_mfma_f32_16x16x32_bf16 v[64:67], v[250:253], v[190:193], v[64:67]
	ds_read_b128 v[246:249], v198 offset:13824
	s_waitcnt lgkmcnt(3)
	v_mfma_f32_16x16x32_bf16 v[60:63], v[194:197], v[178:181], v[60:63]
	v_lshlrev_b32_e32 v132, 1, v175
	s_cmp_eq_u32 s8, 0
	v_add3_u32 v132, s33, v132, v172
	s_cselect_b32 s33, s31, 0x180
	s_add_u32 s38, s0, s33
	s_addc_u32 s39, s1, 0
	s_waitcnt vmcnt(4)
	ds_write_b128 v132, v[128:131]
	v_mfma_f32_16x16x32_bf16 v[56:59], v[194:197], v[182:185], v[56:59]
	v_mfma_f32_16x16x32_bf16 v[52:55], v[194:197], v[186:189], v[52:55]
	v_mfma_f32_16x16x32_bf16 v[48:51], v[194:197], v[190:193], v[48:51]
	ds_read_b128 v[250:253], v198 offset:16128
	s_waitcnt lgkmcnt(4)
	v_mfma_f32_16x16x32_bf16 v[44:47], v[242:245], v[178:181], v[44:47]
	s_waitcnt vmcnt(3)
	ds_write_b128 v254, v[144:147] offset:36864
	v_mfma_f32_16x16x32_bf16 v[40:43], v[242:245], v[182:185], v[40:43]
	v_mfma_f32_16x16x32_bf16 v[36:39], v[242:245], v[186:189], v[36:39]
	v_mfma_f32_16x16x32_bf16 v[32:35], v[242:245], v[190:193], v[32:35]
	ds_read_b128 v[194:197], v198 offset:64
	s_waitcnt lgkmcnt(4)
	v_mfma_f32_16x16x32_bf16 v[28:31], v[246:249], v[178:181], v[28:31]
	s_waitcnt vmcnt(2)
	ds_write_b128 v140, v[148:151] offset:36864
	v_mfma_f32_16x16x32_bf16 v[24:27], v[246:249], v[182:185], v[24:27]
	v_mfma_f32_16x16x32_bf16 v[20:23], v[246:249], v[186:189], v[20:23]
	v_mfma_f32_16x16x32_bf16 v[16:19], v[246:249], v[190:193], v[16:19]
	ds_read_b128 v[242:245], v198 offset:2368
	s_waitcnt lgkmcnt(4)
	v_mfma_f32_16x16x32_bf16 v[12:15], v[250:253], v[178:181], v[12:15]
	ds_read_b128 v[178:181], v199 offset:36928
	s_waitcnt vmcnt(1)
	ds_write_b128 v136, v[152:155] offset:36864
	v_mfma_f32_16x16x32_bf16 v[8:11], v[250:253], v[182:185], v[8:11]
	ds_read_b128 v[182:185], v199 offset:39232
	v_mfma_f32_16x16x32_bf16 v[4:7], v[250:253], v[186:189], v[4:7]
	ds_read_b128 v[186:189], v199 offset:41536
	v_mfma_f32_16x16x32_bf16 v[0:3], v[250:253], v[190:193], v[0:3]
	ds_read_b128 v[190:193], v199 offset:43840
	ds_read_b128 v[246:249], v198 offset:4672
	s_waitcnt lgkmcnt(5)
	v_mfma_f32_16x16x32_bf16 v[124:127], v[194:197], v[178:181], v[124:127]
	s_waitcnt lgkmcnt(3)
	v_mfma_f32_16x16x32_bf16 v[120:123], v[194:197], v[182:185], v[120:123]
	s_waitcnt vmcnt(0)
	ds_write_b128 v132, v[156:159] offset:36864
	s_waitcnt lgkmcnt(3)
	v_mfma_f32_16x16x32_bf16 v[116:119], v[194:197], v[186:189], v[116:119]
	s_waitcnt lgkmcnt(2)
	v_mfma_f32_16x16x32_bf16 v[112:115], v[194:197], v[190:193], v[112:115]
	v_lshl_add_u64 v[128:129], s[38:39], 0, v[162:163]
	global_load_dwordx4 v[140:143], v[128:129], off
	ds_read_b128 v[250:253], v198 offset:6976
	v_mfma_f32_16x16x32_bf16 v[108:111], v[242:245], v[178:181], v[108:111]
	v_mfma_f32_16x16x32_bf16 v[104:107], v[242:245], v[182:185], v[104:107]
	v_lshl_add_u64 v[128:129], s[38:39], 0, v[164:165]
	global_load_dwordx4 v[136:139], v[128:129], off
	v_mfma_f32_16x16x32_bf16 v[100:103], v[242:245], v[186:189], v[100:103]
	v_mfma_f32_16x16x32_bf16 v[96:99], v[242:245], v[190:193], v[96:99]
	ds_read_b128 v[194:197], v198 offset:9280
	s_waitcnt lgkmcnt(3)
; DI unsigned pk2(float lo, float hi) { f32x2 v = {lo, hi}; return __builtin_bit_cast(unsigned, __builtin_convertvector(v, bfx2)); }
; DI f32x4 mfma16(bf16x8 a, bf16x8 b, f32x4 c) { return __builtin_amdgcn_mfma_f32_16x16x32_bf16(a, b, c, 0, 0, 0); }
; template <int MI, int NJ, bool SWAP, class AP, class BP>
; DI void gemm_main(f32x4 (&acc)[MI][NJ], const AP& ap, int a_kstep, const BP& bp, int b_kstep, int nk, bf16_t* smem) {
;     ...
;   for (int kt = 0; kt < nk; ++kt) {
;     const int buf = kt & 1;
;     sstore(buf ^ 1);
;     gload(kt + 2 < nk ? kt + 2 : nk - 1);
;     __builtin_amdgcn_sched_barrier(0);
;     const bf16_t* As = smem + buf * L::STAGE + (wm * 16 * MI + l15) * LDT + quad * 8;
;     const bf16_t* Bs = smem + buf * L::STAGE + L::A_ELEMS + (wn * 16 * NJ + l15) * LDT + quad * 8;
; #pragma unroll
;     for (int ks = 0; ks < 2; ++ks) {
;       if (MI * NJ >= 32 && ks == 1) asm volatile("" ::: "memory");
;       bf16x8 b[NJ];
; #pragma unroll
;       for (int j = 0; j < NJ; ++j) b[j] = *(const bf16x8*)(Bs + j * 16 * LDT + ks * 32);
; #pragma unroll
;       for (int i = 0; i < MI; ++i) {
;         const bf16x8 a = *(const bf16x8*)(As + i * 16 * LDT + ks * 32);
; #pragma unroll
;         for (int j = 0; j < NJ; ++j) acc[i][j] = SWAP ? mfma16(b[j], a, acc[i][j]) : mfma16(a, b[j], acc[i][j]);
;       }
;     }
;     __syncthreads();
;   }
; template <int KIND> DI void mlaup_tile(const Params& p, int layer, int tm, int tn, bf16_t* smem) {
;     ...
; #pragma unroll
;     for (int i = 0; i < 8; ++i) {
;       asm volatile("" ::: "memory");
;       const int t0 = trow0 + i * 16 + quad * 4; float rs[4];
; #pragma unroll
;       for (int r = 0; r < 4; ++r) { const float* c = cssq + (size_t)(t0 + r) * 16 + 8; rs[r] = rsqrtf((c[0] + c[1] + c[2] + c[3]) * (1.f / 256.f) + EPS_); }
; #pragma unroll
;       for (int j = 0; j < 4; ++j)
;         *(u32x2*)(stg + (j * 16 + l15) * VLD + i * 16 + quad * 4) = (u32x2){pk2(acc[i][j][0] * rs[0], acc[i][j][1] * rs[1]), pk2(acc[i][j][2] * rs[2], acc[i][j][3] * rs[3])};
	v_mfma_f32_16x16x32_bf16 v[92:95], v[246:249], v[178:181], v[92:95]
	v_lshl_add_u64 v[128:129], s[38:39], 0, v[166:167]
	global_load_dwordx4 v[132:135], v[128:129], off
	v_mfma_f32_16x16x32_bf16 v[88:91], v[246:249], v[182:185], v[88:91]
	v_mfma_f32_16x16x32_bf16 v[84:87], v[246:249], v[186:189], v[84:87]
	v_lshl_add_u64 v[128:129], s[38:39], 0, v[168:169]
	s_add_u32 s38, s2, s33
	s_addc_u32 s39, s3, 0
	v_lshl_add_u64 v[144:145], s[38:39], 0, v[162:163]
	v_lshl_add_u64 v[148:149], s[38:39], 0, v[164:165]
	v_lshl_add_u64 v[152:153], s[38:39], 0, v[166:167]
	v_lshl_add_u64 v[156:157], s[38:39], 0, v[168:169]
	global_load_dwordx4 v[128:131], v[128:129], off
	v_mfma_f32_16x16x32_bf16 v[80:83], v[246:249], v[190:193], v[80:83]
	ds_read_b128 v[242:245], v198 offset:11584
	s_waitcnt lgkmcnt(2)
	v_mfma_f32_16x16x32_bf16 v[76:79], v[250:253], v[178:181], v[76:79]
	v_mfma_f32_16x16x32_bf16 v[72:75], v[250:253], v[182:185], v[72:75]
	s_nop 0
	global_load_dwordx4 v[144:147], v[144:145], off
	v_mfma_f32_16x16x32_bf16 v[68:71], v[250:253], v[186:189], v[68:71]
	v_mfma_f32_16x16x32_bf16 v[64:67], v[250:253], v[190:193], v[64:67]
	s_nop 0
	global_load_dwordx4 v[148:151], v[148:149], off
	ds_read_b128 v[246:249], v198 offset:13888
	s_waitcnt lgkmcnt(2)
	v_mfma_f32_16x16x32_bf16 v[60:63], v[194:197], v[178:181], v[60:63]
	v_mfma_f32_16x16x32_bf16 v[56:59], v[194:197], v[182:185], v[56:59]
	v_mfma_f32_16x16x32_bf16 v[52:55], v[194:197], v[186:189], v[52:55]
	s_nop 0
	global_load_dwordx4 v[152:155], v[152:153], off
	v_mfma_f32_16x16x32_bf16 v[48:51], v[194:197], v[190:193], v[48:51]
	ds_read_b128 v[250:253], v198 offset:16192
	s_waitcnt lgkmcnt(2)
	v_mfma_f32_16x16x32_bf16 v[44:47], v[242:245], v[178:181], v[44:47]
	s_nop 0
	global_load_dwordx4 v[156:159], v[156:157], off
	v_mfma_f32_16x16x32_bf16 v[40:43], v[242:245], v[182:185], v[40:43]
	v_mfma_f32_16x16x32_bf16 v[36:39], v[242:245], v[186:189], v[36:39]
	v_mfma_f32_16x16x32_bf16 v[32:35], v[242:245], v[190:193], v[32:35]
	s_waitcnt lgkmcnt(0)
	s_barrier
	s_add_i32 s8, s8, 1
	s_cmp_lg_u32 s8, 4
	s_cbranch_scc0 .Lgm12_exit
	s_and_b32 s98, s8, 1
	s_mul_i32 s98, s98, 0x12000
	v_add3_u32 v198, s98, v176, v177
	v_add3_u32 v199, s98, v171, v177
	ds_read_b128 v[194:197], v198
	ds_read_b128 v[242:245], v198 offset:2304
	v_mfma_f32_16x16x32_bf16 v[28:31], v[246:249], v[178:181], v[28:31]
	v_mfma_f32_16x16x32_bf16 v[12:15], v[250:253], v[178:181], v[12:15]
	ds_read_b128 v[178:181], v199 offset:36864
	v_mfma_f32_16x16x32_bf16 v[24:27], v[246:249], v[182:185], v[24:27]
	v_mfma_f32_16x16x32_bf16 v[8:11], v[250:253], v[182:185], v[8:11]
	ds_read_b128 v[182:185], v199 offset:39168
	v_mfma_f32_16x16x32_bf16 v[20:23], v[246:249], v[186:189], v[20:23]
	v_mfma_f32_16x16x32_bf16 v[4:7], v[250:253], v[186:189], v[4:7]
	ds_read_b128 v[186:189], v199 offset:41472
	v_mfma_f32_16x16x32_bf16 v[16:19], v[246:249], v[190:193], v[16:19]
	v_mfma_f32_16x16x32_bf16 v[0:3], v[250:253], v[190:193], v[0:3]
	ds_read_b128 v[190:193], v199 offset:43776
	s_branch .Lgm12_main
.Lgm12_exit:
	v_mfma_f32_16x16x32_bf16 v[28:31], v[246:249], v[178:181], v[28:31]
	v_mfma_f32_16x16x32_bf16 v[12:15], v[250:253], v[178:181], v[12:15]
	v_mfma_f32_16x16x32_bf16 v[24:27], v[246:249], v[182:185], v[24:27]
	v_mfma_f32_16x16x32_bf16 v[8:11], v[250:253], v[182:185], v[8:11]
	v_mfma_f32_16x16x32_bf16 v[20:23], v[246:249], v[186:189], v[20:23]
	v_mfma_f32_16x16x32_bf16 v[4:7], v[250:253], v[186:189], v[4:7]
	v_mfma_f32_16x16x32_bf16 v[16:19], v[246:249], v[190:193], v[16:19]
	v_mfma_f32_16x16x32_bf16 v[0:3], v[250:253], v[190:193], v[0:3]
	s_nop 7
	s_waitcnt vmcnt(5)
	v_mov_b32_e32 v134, v220
	s_waitcnt vmcnt(4)
	v_mov_b32_e32 v128, v220
	v_readlane_b32 s2, v241, 0
	v_ashrrev_i32_e32 v136, 6, v128
	v_ashrrev_i32_e32 v128, 1, v128
	v_and_b32_e32 v128, 0xffffff80, v128
	v_lshl_add_u32 v137, s16, 8, v128
	v_lshrrev_b32_e32 v128, 2, v134
	v_and_b32_e32 v128, 12, v128
	v_or_b32_e32 v130, v137, v128
	v_or_b32_e32 v138, 2, v130
	v_mul_lo_u32 v135, v136, s30
	v_ashrrev_i32_e32 v131, 31, v130
	v_ashrrev_i32_e32 v139, 31, v138
	s_waitcnt vmcnt(2)
	v_lshl_or_b32 v151, v128, 1, v135
	v_lshlrev_b64 v[128:129], 6, v[130:131]
	v_readlane_b32 s3, v241, 1
	v_or_b32_e32 v132, 1, v130
	v_lshlrev_b64 v[138:139], 6, v[138:139]
	v_lshl_add_u64 v[128:129], s[2:3], 0, v[128:129]
	v_ashrrev_i32_e32 v133, 31, v132
	v_lshl_add_u64 v[146:147], s[2:3], 0, v[138:139]
	v_or_b32_e32 v138, 3, v130
	v_lshlrev_b64 v[132:133], 6, v[132:133]
	v_ashrrev_i32_e32 v139, 31, v138
	v_add_co_u32_e32 v128, vcc, s34, v128
	v_lshl_add_u64 v[132:133], s[2:3], 0, v[132:133]
	v_lshlrev_b64 v[138:139], 6, v[138:139]
	v_addc_co_u32_e32 v129, vcc, 0, v129, vcc
	v_lshl_add_u64 v[148:149], s[2:3], 0, v[138:139]
	global_load_dwordx4 v[138:141], v[128:129], off offset:32
	v_add_co_u32_e32 v128, vcc, s34, v132
	v_and_b32_e32 v150, 15, v134
	s_nop 0
	v_addc_co_u32_e32 v129, vcc, 0, v133, vcc
	global_load_dwordx4 v[142:145], v[128:129], off offset:32
	s_waitcnt vmcnt(1)
	v_mov_b32_e32 v128, v138
	v_mov_b32_e32 v132, v140
	s_waitcnt vmcnt(0)
; DI unsigned pk2(float lo, float hi) { f32x2 v = {lo, hi}; return __builtin_bit_cast(unsigned, __builtin_convertvector(v, bfx2)); }
; template <int KIND> DI void mlaup_tile(const Params& p, int layer, int tm, int tn, bf16_t* smem) {
;     ...
; #pragma unroll
;     for (int i = 0; i < 8; ++i) {
;       asm volatile("" ::: "memory");
;       const int t0 = trow0 + i * 16 + quad * 4; float rs[4];
; #pragma unroll
;       for (int r = 0; r < 4; ++r) { const float* c = cssq + (size_t)(t0 + r) * 16 + 8; rs[r] = rsqrtf((c[0] + c[1] + c[2] + c[3]) * (1.f / 256.f) + EPS_); }
; #pragma unroll
;       for (int j = 0; j < 4; ++j)
;         *(u32x2*)(stg + (j * 16 + l15) * VLD + i * 16 + quad * 4) = (u32x2){pk2(acc[i][j][0] * rs[0], acc[i][j][1] * rs[1]), pk2(acc[i][j][2] * rs[2], acc[i][j][3] * rs[3])};
;     }
	v_mov_b32_e32 v129, v142
	v_mov_b32_e32 v142, v139
	v_pk_add_f32 v[128:129], v[128:129], v[142:143]
	v_mov_b32_e32 v133, v144
	v_pk_add_f32 v[128:129], v[128:129], v[132:133]
	v_mov_b32_e32 v144, v141
	v_pk_add_f32 v[132:133], v[128:129], v[144:145]
	v_mov_b64_e32 v[128:129], s[14:15]
	v_pk_fma_f32 v[132:133], v[132:133], s[12:13], v[128:129] op_sel_hi:[1,0,0]
	s_nop 0
	v_mul_f32_e32 v131, 0x4b800000, v132
	v_cmp_gt_f32_e64 s[0:1], s29, v132
	v_cmp_gt_f32_e32 vcc, s29, v133
	s_nop 0
	v_cndmask_b32_e64 v131, v132, v131, s[0:1]
	v_rsq_f32_e32 v132, v131
	v_mul_f32_e32 v131, 0x4b800000, v133
	v_cndmask_b32_e32 v131, v133, v131, vcc
	v_rsq_f32_e32 v133, v131
	s_nop 0
	v_pk_mul_f32 v[138:139], v[132:133], s[10:11] op_sel_hi:[1,0]
	s_nop 0
	v_cndmask_b32_e32 v133, v133, v139, vcc
	v_cndmask_b32_e64 v132, v132, v138, s[0:1]
	v_add_co_u32_e32 v138, vcc, s34, v146
	v_pk_mul_f32 v[124:125], v[124:125], v[132:133]
	s_nop 0
	v_addc_co_u32_e32 v139, vcc, 0, v147, vcc
	v_add_co_u32_e32 v142, vcc, s34, v148
	global_load_dwordx4 v[138:141], v[138:139], off offset:32
	s_nop 0
	v_addc_co_u32_e32 v143, vcc, 0, v149, vcc
	global_load_dwordx4 v[142:145], v[142:143], off offset:32
	v_cvt_pk_bf16_f32 v124, v124, v125
	v_pk_mul_f32 v[112:113], v[112:113], v[132:133]
	v_pk_mul_f32 v[116:117], v[116:117], v[132:133]
	v_cvt_pk_bf16_f32 v112, v112, v113
	v_cvt_pk_bf16_f32 v116, v116, v117
	v_pk_mul_f32 v[120:121], v[120:121], v[132:133]
	s_waitcnt vmcnt(1)
	v_mov_b32_e32 v146, v138
	v_cvt_pk_bf16_f32 v120, v120, v121
	s_waitcnt vmcnt(0)
	v_mov_b32_e32 v147, v142
	v_mov_b32_e32 v142, v139
	v_pk_add_f32 v[138:139], v[146:147], v[142:143]
	v_mov_b32_e32 v142, v140
	v_mov_b32_e32 v143, v144
	v_pk_add_f32 v[138:139], v[138:139], v[142:143]
	v_mov_b32_e32 v144, v141
	v_pk_add_f32 v[138:139], v[138:139], v[144:145]
	s_nop 0
	v_pk_fma_f32 v[138:139], v[138:139], s[12:13], v[128:129] op_sel_hi:[1,0,0]
	s_nop 0
	v_mul_f32_e32 v125, 0x4b800000, v138
	v_cmp_gt_f32_e64 s[0:1], s29, v138
	v_cmp_gt_f32_e32 vcc, s29, v139
	s_nop 0
	v_cndmask_b32_e64 v125, v138, v125, s[0:1]
	v_rsq_f32_e32 v138, v125
	v_mul_f32_e32 v125, 0x4b800000, v139
	v_cndmask_b32_e32 v125, v139, v125, vcc
	v_rsq_f32_e32 v139, v125
	s_nop 0
	v_pk_mul_f32 v[140:141], v[138:139], s[10:11] op_sel_hi:[1,0]
	s_nop 0
	v_cndmask_b32_e32 v139, v139, v141, vcc
	v_cndmask_b32_e64 v138, v138, v140, s[0:1]
	v_pk_mul_f32 v[126:127], v[126:127], v[138:139]
	v_pk_mul_f32 v[114:115], v[114:115], v[138:139]
	v_cvt_pk_bf16_f32 v125, v126, v127
	v_mad_u32_u24 v126, v150, s35, v151
	v_cvt_pk_bf16_f32 v113, v114, v115
	v_or_b32_e32 v114, 17, v130
	v_pk_mul_f32 v[118:119], v[118:119], v[138:139]
	ds_write_b64 v126, v[112:113] offset:13056
	v_or_b32_e32 v112, 16, v130
	v_ashrrev_i32_e32 v115, 31, v114
	v_cvt_pk_bf16_f32 v117, v118, v119
	v_ashrrev_i32_e32 v113, 31, v112
	v_lshlrev_b64 v[114:115], 6, v[114:115]
	ds_write_b64 v126, v[116:117] offset:8704
	v_lshlrev_b64 v[112:113], 6, v[112:113]
	v_lshl_add_u64 v[116:117], s[2:3], 0, v[114:115]
	v_or_b32_e32 v114, 18, v130
	v_pk_mul_f32 v[122:123], v[122:123], v[138:139]
	v_lshl_add_u64 v[112:113], s[2:3], 0, v[112:113]
	v_ashrrev_i32_e32 v115, 31, v114
	v_cvt_pk_bf16_f32 v121, v122, v123
	v_lshlrev_b64 v[114:115], 6, v[114:115]
	v_add_co_u32_e32 v112, vcc, s34, v112
	ds_write_b64 v126, v[120:121] offset:4352
	v_lshl_add_u64 v[120:121], s[2:3], 0, v[114:115]
	v_or_b32_e32 v114, 19, v130
	v_addc_co_u32_e32 v113, vcc, 0, v113, vcc
	ds_write_b64 v126, v[124:125]
	v_ashrrev_i32_e32 v115, 31, v114
	v_add_co_u32_e32 v116, vcc, s34, v116
	v_lshlrev_b64 v[114:115], 6, v[114:115]
	s_nop 0
	v_addc_co_u32_e32 v117, vcc, 0, v117, vcc
	v_lshl_add_u64 v[122:123], s[2:3], 0, v[114:115]
	global_load_dwordx4 v[112:115], v[112:113], off offset:32
	s_nop 0
	global_load_dwordx4 v[116:119], v[116:117], off offset:32
	s_waitcnt vmcnt(1)
	v_mov_b32_e32 v124, v112
	s_waitcnt vmcnt(0)
	v_mov_b32_e32 v125, v116
	v_mov_b32_e32 v116, v113
	v_pk_add_f32 v[112:113], v[124:125], v[116:117]
	v_mov_b32_e32 v116, v114
	v_mov_b32_e32 v117, v118
	v_pk_add_f32 v[112:113], v[112:113], v[116:117]
	v_mov_b32_e32 v118, v115
	v_pk_add_f32 v[112:113], v[112:113], v[118:119]
	s_nop 0
	v_pk_fma_f32 v[112:113], v[112:113], s[12:13], v[128:129] op_sel_hi:[1,0,0]
	s_nop 0
	v_mul_f32_e32 v114, 0x4b800000, v112
	v_cmp_gt_f32_e64 s[0:1], s29, v112
	v_cmp_gt_f32_e32 vcc, s29, v113
	s_nop 0
	v_cndmask_b32_e64 v112, v112, v114, s[0:1]
	v_mul_f32_e32 v114, 0x4b800000, v113
	v_cndmask_b32_e32 v113, v113, v114, vcc
	v_rsq_f32_e32 v112, v112
	v_rsq_f32_e32 v113, v113
	s_nop 0
	v_pk_mul_f32 v[114:115], v[112:113], s[10:11] op_sel_hi:[1,0]
	s_nop 0
	v_cndmask_b32_e32 v113, v113, v115, vcc
	v_cndmask_b32_e64 v112, v112, v114, s[0:1]
	v_add_co_u32_e32 v114, vcc, s34, v120
	v_pk_mul_f32 v[108:109], v[108:109], v[112:113]
	s_nop 0
	v_addc_co_u32_e32 v115, vcc, 0, v121, vcc
	v_add_co_u32_e32 v118, vcc, s34, v122
	global_load_dwordx4 v[114:117], v[114:115], off offset:32
	s_nop 0
	v_addc_co_u32_e32 v119, vcc, 0, v123, vcc
	global_load_dwordx4 v[118:121], v[118:119], off offset:32
	v_cvt_pk_bf16_f32 v108, v108, v109
	v_pk_mul_f32 v[96:97], v[96:97], v[112:113]
	v_pk_mul_f32 v[100:101], v[100:101], v[112:113]
	v_cvt_pk_bf16_f32 v96, v96, v97
	v_cvt_pk_bf16_f32 v100, v100, v101
	v_pk_mul_f32 v[104:105], v[104:105], v[112:113]
	s_waitcnt vmcnt(1)
	v_mov_b32_e32 v122, v114
	v_cvt_pk_bf16_f32 v104, v104, v105
	s_waitcnt vmcnt(0)
; DI unsigned pk2(float lo, float hi) { f32x2 v = {lo, hi}; return __builtin_bit_cast(unsigned, __builtin_convertvector(v, bfx2)); }
; template <int KIND> DI void mlaup_tile(const Params& p, int layer, int tm, int tn, bf16_t* smem) {
;     ...
; #pragma unroll
;     for (int i = 0; i < 8; ++i) {
;       asm volatile("" ::: "memory");
;       const int t0 = trow0 + i * 16 + quad * 4; float rs[4];
; #pragma unroll
;       for (int r = 0; r < 4; ++r) { const float* c = cssq + (size_t)(t0 + r) * 16 + 8; rs[r] = rsqrtf((c[0] + c[1] + c[2] + c[3]) * (1.f / 256.f) + EPS_); }
; #pragma unroll
;       for (int j = 0; j < 4; ++j)
;         *(u32x2*)(stg + (j * 16 + l15) * VLD + i * 16 + quad * 4) = (u32x2){pk2(acc[i][j][0] * rs[0], acc[i][j][1] * rs[1]), pk2(acc[i][j][2] * rs[2], acc[i][j][3] * rs[3])};
;     }
	v_mov_b32_e32 v123, v118
	v_mov_b32_e32 v118, v115
	v_pk_add_f32 v[114:115], v[122:123], v[118:119]
	v_mov_b32_e32 v118, v116
	v_mov_b32_e32 v119, v120
	v_pk_add_f32 v[114:115], v[114:115], v[118:119]
	v_mov_b32_e32 v120, v117
	v_pk_add_f32 v[114:115], v[114:115], v[120:121]
	s_nop 0
	v_pk_fma_f32 v[114:115], v[114:115], s[12:13], v[128:129] op_sel_hi:[1,0,0]
	s_nop 0
	v_mul_f32_e32 v109, 0x4b800000, v114
	v_cmp_gt_f32_e64 s[0:1], s29, v114
	v_cmp_gt_f32_e32 vcc, s29, v115
	s_nop 0
	v_cndmask_b32_e64 v109, v114, v109, s[0:1]
	v_rsq_f32_e32 v114, v109
	v_mul_f32_e32 v109, 0x4b800000, v115
	v_cndmask_b32_e32 v109, v115, v109, vcc
	v_rsq_f32_e32 v115, v109
	s_nop 0
	v_pk_mul_f32 v[116:117], v[114:115], s[10:11] op_sel_hi:[1,0]
	s_nop 0
	v_cndmask_b32_e32 v115, v115, v117, vcc
	v_cndmask_b32_e64 v114, v114, v116, s[0:1]
	v_pk_mul_f32 v[98:99], v[98:99], v[114:115]
	v_pk_mul_f32 v[102:103], v[102:103], v[114:115]
	v_cvt_pk_bf16_f32 v97, v98, v99
	v_or_b32_e32 v98, 33, v130
	ds_write_b64 v126, v[96:97] offset:13088
	v_or_b32_e32 v96, 32, v130
	v_ashrrev_i32_e32 v99, 31, v98
	v_cvt_pk_bf16_f32 v101, v102, v103
	v_ashrrev_i32_e32 v97, 31, v96
	v_lshlrev_b64 v[98:99], 6, v[98:99]
	ds_write_b64 v126, v[100:101] offset:8736
	v_lshlrev_b64 v[96:97], 6, v[96:97]
	v_lshl_add_u64 v[100:101], s[2:3], 0, v[98:99]
	v_or_b32_e32 v98, 34, v130
	v_pk_mul_f32 v[106:107], v[106:107], v[114:115]
	v_lshl_add_u64 v[96:97], s[2:3], 0, v[96:97]
	v_ashrrev_i32_e32 v99, 31, v98
	v_pk_mul_f32 v[110:111], v[110:111], v[114:115]
	v_cvt_pk_bf16_f32 v105, v106, v107
	v_lshlrev_b64 v[98:99], 6, v[98:99]
	v_add_co_u32_e32 v96, vcc, s34, v96
	v_cvt_pk_bf16_f32 v109, v110, v111
	ds_write_b64 v126, v[104:105] offset:4384
	v_lshl_add_u64 v[104:105], s[2:3], 0, v[98:99]
	v_or_b32_e32 v98, 35, v130
	v_addc_co_u32_e32 v97, vcc, 0, v97, vcc
	ds_write_b64 v126, v[108:109] offset:32
	v_ashrrev_i32_e32 v99, 31, v98
	v_add_co_u32_e32 v100, vcc, s34, v100
	v_lshlrev_b64 v[98:99], 6, v[98:99]
	s_nop 0
	v_addc_co_u32_e32 v101, vcc, 0, v101, vcc
	v_lshl_add_u64 v[106:107], s[2:3], 0, v[98:99]
	global_load_dwordx4 v[96:99], v[96:97], off offset:32
	s_nop 0
	global_load_dwordx4 v[100:103], v[100:101], off offset:32
	s_waitcnt vmcnt(1)
	v_mov_b32_e32 v108, v96
	s_waitcnt vmcnt(0)
	v_mov_b32_e32 v109, v100
	v_mov_b32_e32 v100, v97
	v_pk_add_f32 v[96:97], v[108:109], v[100:101]
	v_mov_b32_e32 v100, v98
	v_mov_b32_e32 v101, v102
	v_pk_add_f32 v[96:97], v[96:97], v[100:101]
	v_mov_b32_e32 v102, v99
	v_pk_add_f32 v[96:97], v[96:97], v[102:103]
	s_nop 0
	v_pk_fma_f32 v[96:97], v[96:97], s[12:13], v[128:129] op_sel_hi:[1,0,0]
	s_nop 0
	v_mul_f32_e32 v98, 0x4b800000, v96
	v_cmp_gt_f32_e64 s[0:1], s29, v96
	v_cmp_gt_f32_e32 vcc, s29, v97
	s_nop 0
	v_cndmask_b32_e64 v96, v96, v98, s[0:1]
	v_mul_f32_e32 v98, 0x4b800000, v97
	v_cndmask_b32_e32 v97, v97, v98, vcc
	v_rsq_f32_e32 v96, v96
	v_rsq_f32_e32 v97, v97
	s_nop 0
	v_pk_mul_f32 v[98:99], v[96:97], s[10:11] op_sel_hi:[1,0]
	s_nop 0
	v_cndmask_b32_e32 v97, v97, v99, vcc
	v_cndmask_b32_e64 v96, v96, v98, s[0:1]
	v_add_co_u32_e32 v98, vcc, s34, v104
	v_pk_mul_f32 v[92:93], v[92:93], v[96:97]
	s_nop 0
	v_addc_co_u32_e32 v99, vcc, 0, v105, vcc
	v_add_co_u32_e32 v102, vcc, s34, v106
	global_load_dwordx4 v[98:101], v[98:99], off offset:32
	s_nop 0
	v_addc_co_u32_e32 v103, vcc, 0, v107, vcc
	global_load_dwordx4 v[102:105], v[102:103], off offset:32
	v_cvt_pk_bf16_f32 v92, v92, v93
	v_pk_mul_f32 v[80:81], v[80:81], v[96:97]
	v_pk_mul_f32 v[84:85], v[84:85], v[96:97]
	v_cvt_pk_bf16_f32 v80, v80, v81
	v_cvt_pk_bf16_f32 v84, v84, v85
	v_pk_mul_f32 v[88:89], v[88:89], v[96:97]
	s_waitcnt vmcnt(1)
	v_mov_b32_e32 v106, v98
	v_cvt_pk_bf16_f32 v88, v88, v89
	s_waitcnt vmcnt(0)
	v_mov_b32_e32 v107, v102
	v_mov_b32_e32 v102, v99
	v_pk_add_f32 v[98:99], v[106:107], v[102:103]
	v_mov_b32_e32 v102, v100
	v_mov_b32_e32 v103, v104
	v_pk_add_f32 v[98:99], v[98:99], v[102:103]
	v_mov_b32_e32 v104, v101
	v_pk_add_f32 v[98:99], v[98:99], v[104:105]
	s_nop 0
	v_pk_fma_f32 v[98:99], v[98:99], s[12:13], v[128:129] op_sel_hi:[1,0,0]
	s_nop 0
	v_mul_f32_e32 v93, 0x4b800000, v98
	v_cmp_gt_f32_e64 s[0:1], s29, v98
	v_cmp_gt_f32_e32 vcc, s29, v99
	s_nop 0
	v_cndmask_b32_e64 v93, v98, v93, s[0:1]
	v_rsq_f32_e32 v98, v93
	v_mul_f32_e32 v93, 0x4b800000, v99
	v_cndmask_b32_e32 v93, v99, v93, vcc
	v_rsq_f32_e32 v99, v93
	s_nop 0
	v_pk_mul_f32 v[100:101], v[98:99], s[10:11] op_sel_hi:[1,0]
	s_nop 0
	v_cndmask_b32_e32 v99, v99, v101, vcc
	v_cndmask_b32_e64 v98, v98, v100, s[0:1]
	v_pk_mul_f32 v[82:83], v[82:83], v[98:99]
	v_pk_mul_f32 v[86:87], v[86:87], v[98:99]
	v_cvt_pk_bf16_f32 v81, v82, v83
	v_or_b32_e32 v82, 49, v130
	ds_write_b64 v126, v[80:81] offset:13120
	v_or_b32_e32 v80, 48, v130
	v_ashrrev_i32_e32 v83, 31, v82
	v_cvt_pk_bf16_f32 v85, v86, v87
	v_ashrrev_i32_e32 v81, 31, v80
	v_lshlrev_b64 v[82:83], 6, v[82:83]
	ds_write_b64 v126, v[84:85] offset:8768
	v_lshlrev_b64 v[80:81], 6, v[80:81]
	v_lshl_add_u64 v[84:85], s[2:3], 0, v[82:83]
	v_or_b32_e32 v82, 50, v130
	v_pk_mul_f32 v[90:91], v[90:91], v[98:99]
	v_lshl_add_u64 v[80:81], s[2:3], 0, v[80:81]
	v_ashrrev_i32_e32 v83, 31, v82
	v_pk_mul_f32 v[94:95], v[94:95], v[98:99]
	v_cvt_pk_bf16_f32 v89, v90, v91
	v_lshlrev_b64 v[82:83], 6, v[82:83]
	v_add_co_u32_e32 v80, vcc, s34, v80
	v_cvt_pk_bf16_f32 v93, v94, v95
	ds_write_b64 v126, v[88:89] offset:4416
	v_lshl_add_u64 v[88:89], s[2:3], 0, v[82:83]
	v_or_b32_e32 v82, 51, v130
	v_addc_co_u32_e32 v81, vcc, 0, v81, vcc
	ds_write_b64 v126, v[92:93] offset:64
	v_ashrrev_i32_e32 v83, 31, v82
	v_add_co_u32_e32 v84, vcc, s34, v84
	v_lshlrev_b64 v[82:83], 6, v[82:83]
	s_nop 0
	v_addc_co_u32_e32 v85, vcc, 0, v85, vcc
	v_lshl_add_u64 v[90:91], s[2:3], 0, v[82:83]
	global_load_dwordx4 v[80:83], v[80:81], off offset:32
	s_nop 0
	global_load_dwordx4 v[84:87], v[84:85], off offset:32
	s_waitcnt vmcnt(1)
; DI unsigned pk2(float lo, float hi) { f32x2 v = {lo, hi}; return __builtin_bit_cast(unsigned, __builtin_convertvector(v, bfx2)); }
; template <int KIND> DI void mlaup_tile(const Params& p, int layer, int tm, int tn, bf16_t* smem) {
;     ...
; #pragma unroll
;     for (int i = 0; i < 8; ++i) {
;       asm volatile("" ::: "memory");
;       const int t0 = trow0 + i * 16 + quad * 4; float rs[4];
; #pragma unroll
;       for (int r = 0; r < 4; ++r) { const float* c = cssq + (size_t)(t0 + r) * 16 + 8; rs[r] = rsqrtf((c[0] + c[1] + c[2] + c[3]) * (1.f / 256.f) + EPS_); }
; #pragma unroll
;       for (int j = 0; j < 4; ++j)
;         *(u32x2*)(stg + (j * 16 + l15) * VLD + i * 16 + quad * 4) = (u32x2){pk2(acc[i][j][0] * rs[0], acc[i][j][1] * rs[1]), pk2(acc[i][j][2] * rs[2], acc[i][j][3] * rs[3])};
;     }
	v_mov_b32_e32 v92, v80
	s_waitcnt vmcnt(0)
	v_mov_b32_e32 v93, v84
	v_mov_b32_e32 v84, v81
	v_pk_add_f32 v[80:81], v[92:93], v[84:85]
	v_mov_b32_e32 v84, v82
	v_mov_b32_e32 v85, v86
	v_pk_add_f32 v[80:81], v[80:81], v[84:85]
	v_mov_b32_e32 v86, v83
	v_pk_add_f32 v[80:81], v[80:81], v[86:87]
	s_nop 0
	v_pk_fma_f32 v[80:81], v[80:81], s[12:13], v[128:129] op_sel_hi:[1,0,0]
	s_nop 0
	v_mul_f32_e32 v82, 0x4b800000, v80
	v_cmp_gt_f32_e64 s[0:1], s29, v80
	v_cmp_gt_f32_e32 vcc, s29, v81
	s_nop 0
	v_cndmask_b32_e64 v80, v80, v82, s[0:1]
	v_mul_f32_e32 v82, 0x4b800000, v81
	v_cndmask_b32_e32 v81, v81, v82, vcc
	v_rsq_f32_e32 v80, v80
	v_rsq_f32_e32 v81, v81
	s_nop 0
	v_pk_mul_f32 v[82:83], v[80:81], s[10:11] op_sel_hi:[1,0]
	s_nop 0
	v_cndmask_b32_e32 v81, v81, v83, vcc
	v_cndmask_b32_e64 v80, v80, v82, s[0:1]
	v_add_co_u32_e32 v82, vcc, s34, v88
	v_pk_mul_f32 v[76:77], v[76:77], v[80:81]
	s_nop 0
	v_addc_co_u32_e32 v83, vcc, 0, v89, vcc
	v_add_co_u32_e32 v86, vcc, s34, v90
	global_load_dwordx4 v[82:85], v[82:83], off offset:32
	s_nop 0
	v_addc_co_u32_e32 v87, vcc, 0, v91, vcc
	global_load_dwordx4 v[86:89], v[86:87], off offset:32
	v_cvt_pk_bf16_f32 v76, v76, v77
	v_pk_mul_f32 v[64:65], v[64:65], v[80:81]
	v_pk_mul_f32 v[68:69], v[68:69], v[80:81]
	v_cvt_pk_bf16_f32 v64, v64, v65
	v_cvt_pk_bf16_f32 v68, v68, v69
	v_pk_mul_f32 v[72:73], v[72:73], v[80:81]
	s_waitcnt vmcnt(1)
	v_mov_b32_e32 v90, v82
	v_cvt_pk_bf16_f32 v72, v72, v73
	s_waitcnt vmcnt(0)
	v_mov_b32_e32 v91, v86
	v_mov_b32_e32 v86, v83
	v_pk_add_f32 v[82:83], v[90:91], v[86:87]
	v_mov_b32_e32 v86, v84
	v_mov_b32_e32 v87, v88
	v_pk_add_f32 v[82:83], v[82:83], v[86:87]
	v_mov_b32_e32 v88, v85
	v_pk_add_f32 v[82:83], v[82:83], v[88:89]
	s_nop 0
	v_pk_fma_f32 v[82:83], v[82:83], s[12:13], v[128:129] op_sel_hi:[1,0,0]
	s_nop 0
	v_mul_f32_e32 v77, 0x4b800000, v82
	v_cmp_gt_f32_e64 s[0:1], s29, v82
	v_cmp_gt_f32_e32 vcc, s29, v83
	s_nop 0
	v_cndmask_b32_e64 v77, v82, v77, s[0:1]
	v_rsq_f32_e32 v82, v77
	v_mul_f32_e32 v77, 0x4b800000, v83
	v_cndmask_b32_e32 v77, v83, v77, vcc
	v_rsq_f32_e32 v83, v77
	s_nop 0
	v_pk_mul_f32 v[84:85], v[82:83], s[10:11] op_sel_hi:[1,0]
	s_nop 0
	v_cndmask_b32_e32 v83, v83, v85, vcc
	v_cndmask_b32_e64 v82, v82, v84, s[0:1]
	v_pk_mul_f32 v[66:67], v[66:67], v[82:83]
	v_pk_mul_f32 v[70:71], v[70:71], v[82:83]
	v_cvt_pk_bf16_f32 v65, v66, v67
	v_or_b32_e32 v66, 0x41, v130
	ds_write_b64 v126, v[64:65] offset:13152
	v_or_b32_e32 v64, 64, v130
	v_ashrrev_i32_e32 v67, 31, v66
	v_cvt_pk_bf16_f32 v69, v70, v71
	v_ashrrev_i32_e32 v65, 31, v64
	v_lshlrev_b64 v[66:67], 6, v[66:67]
	ds_write_b64 v126, v[68:69] offset:8800
	v_lshlrev_b64 v[64:65], 6, v[64:65]
	v_lshl_add_u64 v[68:69], s[2:3], 0, v[66:67]
	v_or_b32_e32 v66, 0x42, v130
	v_pk_mul_f32 v[74:75], v[74:75], v[82:83]
	v_lshl_add_u64 v[64:65], s[2:3], 0, v[64:65]
	v_ashrrev_i32_e32 v67, 31, v66
	v_pk_mul_f32 v[78:79], v[78:79], v[82:83]
	v_cvt_pk_bf16_f32 v73, v74, v75
	v_lshlrev_b64 v[66:67], 6, v[66:67]
	v_add_co_u32_e32 v64, vcc, s34, v64
	v_cvt_pk_bf16_f32 v77, v78, v79
	ds_write_b64 v126, v[72:73] offset:4448
	v_lshl_add_u64 v[72:73], s[2:3], 0, v[66:67]
	v_or_b32_e32 v66, 0x43, v130
	v_addc_co_u32_e32 v65, vcc, 0, v65, vcc
	ds_write_b64 v126, v[76:77] offset:96
	v_ashrrev_i32_e32 v67, 31, v66
	v_add_co_u32_e32 v68, vcc, s34, v68
	v_lshlrev_b64 v[66:67], 6, v[66:67]
	s_nop 0
	v_addc_co_u32_e32 v69, vcc, 0, v69, vcc
	v_lshl_add_u64 v[74:75], s[2:3], 0, v[66:67]
	global_load_dwordx4 v[64:67], v[64:65], off offset:32
	s_nop 0
	global_load_dwordx4 v[68:71], v[68:69], off offset:32
	s_waitcnt vmcnt(1)
	v_mov_b32_e32 v76, v64
	s_waitcnt vmcnt(0)
	v_mov_b32_e32 v77, v68
	v_mov_b32_e32 v68, v65
	v_pk_add_f32 v[64:65], v[76:77], v[68:69]
	v_mov_b32_e32 v68, v66
	v_mov_b32_e32 v69, v70
	v_pk_add_f32 v[64:65], v[64:65], v[68:69]
	v_mov_b32_e32 v70, v67
	v_pk_add_f32 v[64:65], v[64:65], v[70:71]
	s_nop 0
	v_pk_fma_f32 v[64:65], v[64:65], s[12:13], v[128:129] op_sel_hi:[1,0,0]
	s_nop 0
	v_mul_f32_e32 v66, 0x4b800000, v64
	v_cmp_gt_f32_e64 s[0:1], s29, v64
	v_cmp_gt_f32_e32 vcc, s29, v65
	s_nop 0
	v_cndmask_b32_e64 v64, v64, v66, s[0:1]
	v_mul_f32_e32 v66, 0x4b800000, v65
	v_cndmask_b32_e32 v65, v65, v66, vcc
	v_rsq_f32_e32 v64, v64
	v_rsq_f32_e32 v65, v65
	s_nop 0
	v_pk_mul_f32 v[66:67], v[64:65], s[10:11] op_sel_hi:[1,0]
	s_nop 0
	v_cndmask_b32_e32 v65, v65, v67, vcc
	v_cndmask_b32_e64 v64, v64, v66, s[0:1]
	v_add_co_u32_e32 v66, vcc, s34, v72
	v_pk_mul_f32 v[60:61], v[60:61], v[64:65]
	s_nop 0
	v_addc_co_u32_e32 v67, vcc, 0, v73, vcc
	v_add_co_u32_e32 v70, vcc, s34, v74
	global_load_dwordx4 v[66:69], v[66:67], off offset:32
	s_nop 0
	v_addc_co_u32_e32 v71, vcc, 0, v75, vcc
	global_load_dwordx4 v[70:73], v[70:71], off offset:32
	v_cvt_pk_bf16_f32 v60, v60, v61
	v_pk_mul_f32 v[48:49], v[48:49], v[64:65]
	v_pk_mul_f32 v[52:53], v[52:53], v[64:65]
	v_cvt_pk_bf16_f32 v48, v48, v49
	v_cvt_pk_bf16_f32 v52, v52, v53
	v_pk_mul_f32 v[56:57], v[56:57], v[64:65]
	s_waitcnt vmcnt(1)
	v_mov_b32_e32 v74, v66
	v_cvt_pk_bf16_f32 v56, v56, v57
	s_waitcnt vmcnt(0)
; DI unsigned pk2(float lo, float hi) { f32x2 v = {lo, hi}; return __builtin_bit_cast(unsigned, __builtin_convertvector(v, bfx2)); }
; template <int KIND> DI void mlaup_tile(const Params& p, int layer, int tm, int tn, bf16_t* smem) {
;     ...
; #pragma unroll
;     for (int i = 0; i < 8; ++i) {
;       asm volatile("" ::: "memory");
;       const int t0 = trow0 + i * 16 + quad * 4; float rs[4];
; #pragma unroll
;       for (int r = 0; r < 4; ++r) { const float* c = cssq + (size_t)(t0 + r) * 16 + 8; rs[r] = rsqrtf((c[0] + c[1] + c[2] + c[3]) * (1.f / 256.f) + EPS_); }
; #pragma unroll
;       for (int j = 0; j < 4; ++j)
;         *(u32x2*)(stg + (j * 16 + l15) * VLD + i * 16 + quad * 4) = (u32x2){pk2(acc[i][j][0] * rs[0], acc[i][j][1] * rs[1]), pk2(acc[i][j][2] * rs[2], acc[i][j][3] * rs[3])};
;     }
	v_mov_b32_e32 v75, v70
	v_mov_b32_e32 v70, v67
	v_pk_add_f32 v[66:67], v[74:75], v[70:71]
	v_mov_b32_e32 v70, v68
	v_mov_b32_e32 v71, v72
	v_pk_add_f32 v[66:67], v[66:67], v[70:71]
	v_mov_b32_e32 v72, v69
	v_pk_add_f32 v[66:67], v[66:67], v[72:73]
	s_nop 0
	v_pk_fma_f32 v[66:67], v[66:67], s[12:13], v[128:129] op_sel_hi:[1,0,0]
	s_nop 0
	v_mul_f32_e32 v61, 0x4b800000, v66
	v_cmp_gt_f32_e64 s[0:1], s29, v66
	v_cmp_gt_f32_e32 vcc, s29, v67
	s_nop 0
	v_cndmask_b32_e64 v61, v66, v61, s[0:1]
	v_rsq_f32_e32 v66, v61
	v_mul_f32_e32 v61, 0x4b800000, v67
	v_cndmask_b32_e32 v61, v67, v61, vcc
	v_rsq_f32_e32 v67, v61
	s_nop 0
	v_pk_mul_f32 v[68:69], v[66:67], s[10:11] op_sel_hi:[1,0]
	s_nop 0
	v_cndmask_b32_e32 v67, v67, v69, vcc
	v_cndmask_b32_e64 v66, v66, v68, s[0:1]
	v_pk_mul_f32 v[50:51], v[50:51], v[66:67]
	v_pk_mul_f32 v[54:55], v[54:55], v[66:67]
	v_cvt_pk_bf16_f32 v49, v50, v51
	v_or_b32_e32 v50, 0x51, v130
	ds_write_b64 v126, v[48:49] offset:13184
	v_or_b32_e32 v48, 0x50, v130
	v_ashrrev_i32_e32 v51, 31, v50
	v_cvt_pk_bf16_f32 v53, v54, v55
	v_ashrrev_i32_e32 v49, 31, v48
	v_lshlrev_b64 v[50:51], 6, v[50:51]
	ds_write_b64 v126, v[52:53] offset:8832
	v_lshlrev_b64 v[48:49], 6, v[48:49]
	v_lshl_add_u64 v[52:53], s[2:3], 0, v[50:51]
	v_or_b32_e32 v50, 0x52, v130
	v_pk_mul_f32 v[58:59], v[58:59], v[66:67]
	v_lshl_add_u64 v[48:49], s[2:3], 0, v[48:49]
	v_ashrrev_i32_e32 v51, 31, v50
	v_pk_mul_f32 v[62:63], v[62:63], v[66:67]
	v_cvt_pk_bf16_f32 v57, v58, v59
	v_lshlrev_b64 v[50:51], 6, v[50:51]
	v_add_co_u32_e32 v48, vcc, s34, v48
	v_cvt_pk_bf16_f32 v61, v62, v63
	ds_write_b64 v126, v[56:57] offset:4480
	v_lshl_add_u64 v[56:57], s[2:3], 0, v[50:51]
	v_or_b32_e32 v50, 0x53, v130
	v_addc_co_u32_e32 v49, vcc, 0, v49, vcc
	ds_write_b64 v126, v[60:61] offset:128
	v_ashrrev_i32_e32 v51, 31, v50
	v_add_co_u32_e32 v52, vcc, s34, v52
	v_lshlrev_b64 v[50:51], 6, v[50:51]
	s_nop 0
	v_addc_co_u32_e32 v53, vcc, 0, v53, vcc
	v_lshl_add_u64 v[58:59], s[2:3], 0, v[50:51]
	global_load_dwordx4 v[48:51], v[48:49], off offset:32
	s_nop 0
	global_load_dwordx4 v[52:55], v[52:53], off offset:32
	s_waitcnt vmcnt(1)
	v_mov_b32_e32 v60, v48
	s_waitcnt vmcnt(0)
	v_mov_b32_e32 v61, v52
	v_mov_b32_e32 v52, v49
	v_pk_add_f32 v[48:49], v[60:61], v[52:53]
	v_mov_b32_e32 v52, v50
	v_mov_b32_e32 v53, v54
	v_pk_add_f32 v[48:49], v[48:49], v[52:53]
	v_mov_b32_e32 v54, v51
	v_pk_add_f32 v[48:49], v[48:49], v[54:55]
	s_nop 0
	v_pk_fma_f32 v[48:49], v[48:49], s[12:13], v[128:129] op_sel_hi:[1,0,0]
	s_nop 0
	v_mul_f32_e32 v50, 0x4b800000, v48
	v_cmp_gt_f32_e64 s[0:1], s29, v48
	v_cmp_gt_f32_e32 vcc, s29, v49
	s_nop 0
	v_cndmask_b32_e64 v48, v48, v50, s[0:1]
	v_mul_f32_e32 v50, 0x4b800000, v49
	v_cndmask_b32_e32 v49, v49, v50, vcc
	v_rsq_f32_e32 v48, v48
	v_rsq_f32_e32 v49, v49
	s_nop 0
	v_pk_mul_f32 v[50:51], v[48:49], s[10:11] op_sel_hi:[1,0]
	s_nop 0
	v_cndmask_b32_e32 v49, v49, v51, vcc
	v_cndmask_b32_e64 v48, v48, v50, s[0:1]
	v_add_co_u32_e32 v50, vcc, s34, v56
	v_pk_mul_f32 v[44:45], v[44:45], v[48:49]
	s_nop 0
	v_addc_co_u32_e32 v51, vcc, 0, v57, vcc
	v_add_co_u32_e32 v54, vcc, s34, v58
	global_load_dwordx4 v[50:53], v[50:51], off offset:32
	s_nop 0
	v_addc_co_u32_e32 v55, vcc, 0, v59, vcc
	global_load_dwordx4 v[54:57], v[54:55], off offset:32
	v_cvt_pk_bf16_f32 v44, v44, v45
	v_pk_mul_f32 v[32:33], v[32:33], v[48:49]
	v_pk_mul_f32 v[36:37], v[36:37], v[48:49]
	v_cvt_pk_bf16_f32 v32, v32, v33
	v_cvt_pk_bf16_f32 v36, v36, v37
	v_pk_mul_f32 v[40:41], v[40:41], v[48:49]
	s_waitcnt vmcnt(1)
	v_mov_b32_e32 v58, v50
	v_cvt_pk_bf16_f32 v40, v40, v41
	s_waitcnt vmcnt(0)
	v_mov_b32_e32 v59, v54
	v_mov_b32_e32 v54, v51
	v_pk_add_f32 v[50:51], v[58:59], v[54:55]
	v_mov_b32_e32 v54, v52
	v_mov_b32_e32 v55, v56
	v_pk_add_f32 v[50:51], v[50:51], v[54:55]
	v_mov_b32_e32 v56, v53
	v_pk_add_f32 v[50:51], v[50:51], v[56:57]
	s_nop 0
	v_pk_fma_f32 v[50:51], v[50:51], s[12:13], v[128:129] op_sel_hi:[1,0,0]
	s_nop 0
	v_mul_f32_e32 v45, 0x4b800000, v50
	v_cmp_gt_f32_e64 s[0:1], s29, v50
	v_cmp_gt_f32_e32 vcc, s29, v51
	s_nop 0
	v_cndmask_b32_e64 v45, v50, v45, s[0:1]
	v_rsq_f32_e32 v50, v45
	v_mul_f32_e32 v45, 0x4b800000, v51
	v_cndmask_b32_e32 v45, v51, v45, vcc
	v_rsq_f32_e32 v51, v45
	s_nop 0
	v_pk_mul_f32 v[52:53], v[50:51], s[10:11] op_sel_hi:[1,0]
	s_nop 0
	v_cndmask_b32_e32 v51, v51, v53, vcc
	v_cndmask_b32_e64 v50, v50, v52, s[0:1]
	v_pk_mul_f32 v[34:35], v[34:35], v[50:51]
	v_pk_mul_f32 v[38:39], v[38:39], v[50:51]
	v_cvt_pk_bf16_f32 v33, v34, v35
	v_or_b32_e32 v34, 0x61, v130
	ds_write_b64 v126, v[32:33] offset:13216
	v_or_b32_e32 v32, 0x60, v130
	v_ashrrev_i32_e32 v35, 31, v34
	v_cvt_pk_bf16_f32 v37, v38, v39
	v_ashrrev_i32_e32 v33, 31, v32
	v_lshlrev_b64 v[34:35], 6, v[34:35]
	ds_write_b64 v126, v[36:37] offset:8864
	v_lshlrev_b64 v[32:33], 6, v[32:33]
	v_lshl_add_u64 v[36:37], s[2:3], 0, v[34:35]
	v_or_b32_e32 v34, 0x62, v130
	v_pk_mul_f32 v[42:43], v[42:43], v[50:51]
	v_lshl_add_u64 v[32:33], s[2:3], 0, v[32:33]
	v_ashrrev_i32_e32 v35, 31, v34
	v_pk_mul_f32 v[46:47], v[46:47], v[50:51]
	v_cvt_pk_bf16_f32 v41, v42, v43
	v_lshlrev_b64 v[34:35], 6, v[34:35]
	v_add_co_u32_e32 v32, vcc, s34, v32
	v_cvt_pk_bf16_f32 v45, v46, v47
	ds_write_b64 v126, v[40:41] offset:4512
	v_lshl_add_u64 v[40:41], s[2:3], 0, v[34:35]
	v_or_b32_e32 v34, 0x63, v130
	v_addc_co_u32_e32 v33, vcc, 0, v33, vcc
	ds_write_b64 v126, v[44:45] offset:160
	v_ashrrev_i32_e32 v35, 31, v34
	v_add_co_u32_e32 v36, vcc, s34, v36
	v_lshlrev_b64 v[34:35], 6, v[34:35]
	s_nop 0
	v_addc_co_u32_e32 v37, vcc, 0, v37, vcc
	v_lshl_add_u64 v[42:43], s[2:3], 0, v[34:35]
	global_load_dwordx4 v[32:35], v[32:33], off offset:32
	s_nop 0
	global_load_dwordx4 v[36:39], v[36:37], off offset:32
	s_waitcnt vmcnt(1)
; DI unsigned pk2(float lo, float hi) { f32x2 v = {lo, hi}; return __builtin_bit_cast(unsigned, __builtin_convertvector(v, bfx2)); }
; template <int KIND> DI void mlaup_tile(const Params& p, int layer, int tm, int tn, bf16_t* smem) {
;     ...
; #pragma unroll
;     for (int i = 0; i < 8; ++i) {
;       asm volatile("" ::: "memory");
;       const int t0 = trow0 + i * 16 + quad * 4; float rs[4];
; #pragma unroll
;       for (int r = 0; r < 4; ++r) { const float* c = cssq + (size_t)(t0 + r) * 16 + 8; rs[r] = rsqrtf((c[0] + c[1] + c[2] + c[3]) * (1.f / 256.f) + EPS_); }
; #pragma unroll
;       for (int j = 0; j < 4; ++j)
;         *(u32x2*)(stg + (j * 16 + l15) * VLD + i * 16 + quad * 4) = (u32x2){pk2(acc[i][j][0] * rs[0], acc[i][j][1] * rs[1]), pk2(acc[i][j][2] * rs[2], acc[i][j][3] * rs[3])};
;     }
	v_mov_b32_e32 v44, v32
	s_waitcnt vmcnt(0)
	v_mov_b32_e32 v45, v36
	v_mov_b32_e32 v36, v33
	v_pk_add_f32 v[32:33], v[44:45], v[36:37]
	v_mov_b32_e32 v36, v34
	v_mov_b32_e32 v37, v38
	v_pk_add_f32 v[32:33], v[32:33], v[36:37]
	v_mov_b32_e32 v38, v35
	v_pk_add_f32 v[32:33], v[32:33], v[38:39]
	s_nop 0
	v_pk_fma_f32 v[32:33], v[32:33], s[12:13], v[128:129] op_sel_hi:[1,0,0]
	s_nop 0
	v_mul_f32_e32 v34, 0x4b800000, v32
	v_cmp_gt_f32_e64 s[0:1], s29, v32
	v_cmp_gt_f32_e32 vcc, s29, v33
	s_nop 0
	v_cndmask_b32_e64 v32, v32, v34, s[0:1]
	v_mul_f32_e32 v34, 0x4b800000, v33
	v_cndmask_b32_e32 v33, v33, v34, vcc
	v_rsq_f32_e32 v32, v32
	v_rsq_f32_e32 v33, v33
	s_nop 0
	v_pk_mul_f32 v[34:35], v[32:33], s[10:11] op_sel_hi:[1,0]
	s_nop 0
	v_cndmask_b32_e32 v33, v33, v35, vcc
	v_cndmask_b32_e64 v32, v32, v34, s[0:1]
	v_add_co_u32_e32 v34, vcc, s34, v40
	v_pk_mul_f32 v[28:29], v[28:29], v[32:33]
	s_nop 0
	v_addc_co_u32_e32 v35, vcc, 0, v41, vcc
	v_add_co_u32_e32 v38, vcc, s34, v42
	global_load_dwordx4 v[34:37], v[34:35], off offset:32
	s_nop 0
	v_addc_co_u32_e32 v39, vcc, 0, v43, vcc
	global_load_dwordx4 v[38:41], v[38:39], off offset:32
	v_cvt_pk_bf16_f32 v28, v28, v29
	v_pk_mul_f32 v[16:17], v[16:17], v[32:33]
	v_pk_mul_f32 v[20:21], v[20:21], v[32:33]
	v_cvt_pk_bf16_f32 v16, v16, v17
	v_cvt_pk_bf16_f32 v20, v20, v21
	v_pk_mul_f32 v[24:25], v[24:25], v[32:33]
	s_waitcnt vmcnt(1)
	v_mov_b32_e32 v42, v34
	v_cvt_pk_bf16_f32 v24, v24, v25
	s_waitcnt vmcnt(0)
	v_mov_b32_e32 v43, v38
	v_mov_b32_e32 v38, v35
	v_pk_add_f32 v[34:35], v[42:43], v[38:39]
	v_mov_b32_e32 v38, v36
	v_mov_b32_e32 v39, v40
	v_pk_add_f32 v[34:35], v[34:35], v[38:39]
	v_mov_b32_e32 v40, v37
	v_pk_add_f32 v[34:35], v[34:35], v[40:41]
	s_nop 0
	v_pk_fma_f32 v[34:35], v[34:35], s[12:13], v[128:129] op_sel_hi:[1,0,0]
	s_nop 0
	v_mul_f32_e32 v29, 0x4b800000, v34
	v_cmp_gt_f32_e64 s[0:1], s29, v34
	v_cmp_gt_f32_e32 vcc, s29, v35
	s_nop 0
	v_cndmask_b32_e64 v29, v34, v29, s[0:1]
	v_rsq_f32_e32 v34, v29
	v_mul_f32_e32 v29, 0x4b800000, v35
	v_cndmask_b32_e32 v29, v35, v29, vcc
	v_rsq_f32_e32 v35, v29
	s_nop 0
	v_pk_mul_f32 v[36:37], v[34:35], s[10:11] op_sel_hi:[1,0]
	s_nop 0
	v_cndmask_b32_e32 v35, v35, v37, vcc
	v_cndmask_b32_e64 v34, v34, v36, s[0:1]
	v_pk_mul_f32 v[18:19], v[18:19], v[34:35]
	v_pk_mul_f32 v[22:23], v[22:23], v[34:35]
	v_cvt_pk_bf16_f32 v17, v18, v19
	v_or_b32_e32 v18, 0x71, v130
	ds_write_b64 v126, v[16:17] offset:13248
	v_or_b32_e32 v16, 0x70, v130
	v_ashrrev_i32_e32 v19, 31, v18
	v_cvt_pk_bf16_f32 v21, v22, v23
	v_ashrrev_i32_e32 v17, 31, v16
	v_lshlrev_b64 v[18:19], 6, v[18:19]
	ds_write_b64 v126, v[20:21] offset:8896
	v_lshlrev_b64 v[16:17], 6, v[16:17]
	v_lshl_add_u64 v[20:21], s[2:3], 0, v[18:19]
	v_or_b32_e32 v18, 0x72, v130
	v_pk_mul_f32 v[26:27], v[26:27], v[34:35]
	v_lshl_add_u64 v[16:17], s[2:3], 0, v[16:17]
	v_ashrrev_i32_e32 v19, 31, v18
	v_pk_mul_f32 v[30:31], v[30:31], v[34:35]
	v_cvt_pk_bf16_f32 v25, v26, v27
	v_lshlrev_b64 v[18:19], 6, v[18:19]
	v_add_co_u32_e32 v16, vcc, s34, v16
	v_cvt_pk_bf16_f32 v29, v30, v31
	ds_write_b64 v126, v[24:25] offset:4544
	v_lshl_add_u64 v[24:25], s[2:3], 0, v[18:19]
	v_or_b32_e32 v18, 0x73, v130
	v_addc_co_u32_e32 v17, vcc, 0, v17, vcc
	ds_write_b64 v126, v[28:29] offset:192
	v_ashrrev_i32_e32 v19, 31, v18
	v_add_co_u32_e32 v20, vcc, s34, v20
	v_lshlrev_b64 v[18:19], 6, v[18:19]
	s_nop 0
	v_addc_co_u32_e32 v21, vcc, 0, v21, vcc
	v_lshl_add_u64 v[26:27], s[2:3], 0, v[18:19]
	global_load_dwordx4 v[16:19], v[16:17], off offset:32
	s_nop 0
	global_load_dwordx4 v[20:23], v[20:21], off offset:32
	s_waitcnt vmcnt(1)
	v_mov_b32_e32 v28, v16
	s_waitcnt vmcnt(0)
	v_mov_b32_e32 v29, v20
	v_mov_b32_e32 v20, v17
	v_pk_add_f32 v[16:17], v[28:29], v[20:21]
	v_mov_b32_e32 v20, v18
	v_mov_b32_e32 v21, v22
	v_pk_add_f32 v[16:17], v[16:17], v[20:21]
	v_mov_b32_e32 v22, v19
	v_pk_add_f32 v[16:17], v[16:17], v[22:23]
	s_nop 0
	v_pk_fma_f32 v[16:17], v[16:17], s[12:13], v[128:129] op_sel_hi:[1,0,0]
	s_nop 0
	v_mul_f32_e32 v18, 0x4b800000, v16
	v_cmp_gt_f32_e64 s[0:1], s29, v16
	v_cmp_gt_f32_e32 vcc, s29, v17
	s_nop 0
	v_cndmask_b32_e64 v16, v16, v18, s[0:1]
	v_mul_f32_e32 v18, 0x4b800000, v17
	v_cndmask_b32_e32 v17, v17, v18, vcc
	v_rsq_f32_e32 v16, v16
	v_rsq_f32_e32 v17, v17
	s_nop 0
	v_pk_mul_f32 v[18:19], v[16:17], s[10:11] op_sel_hi:[1,0]
	s_nop 0
	v_cndmask_b32_e32 v17, v17, v19, vcc
	v_cndmask_b32_e64 v16, v16, v18, s[0:1]
	v_add_co_u32_e32 v18, vcc, s34, v24
	v_pk_mul_f32 v[12:13], v[12:13], v[16:17]
	s_nop 0
	v_addc_co_u32_e32 v19, vcc, 0, v25, vcc
	v_add_co_u32_e32 v22, vcc, s34, v26
	global_load_dwordx4 v[18:21], v[18:19], off offset:32
	s_nop 0
	v_addc_co_u32_e32 v23, vcc, 0, v27, vcc
	global_load_dwordx4 v[22:25], v[22:23], off offset:32
	v_cvt_pk_bf16_f32 v12, v12, v13
	v_pk_mul_f32 v[0:1], v[0:1], v[16:17]
	v_pk_mul_f32 v[8:9], v[8:9], v[16:17]
	v_cvt_pk_bf16_f32 v0, v0, v1
	v_pk_mul_f32 v[4:5], v[4:5], v[16:17]
	v_cvt_pk_bf16_f32 v8, v8, v9
	v_cvt_pk_bf16_f32 v4, v4, v5
	s_waitcnt vmcnt(1)
	v_mov_b32_e32 v26, v18
	s_waitcnt vmcnt(0)
; DI unsigned pk2(float lo, float hi) { f32x2 v = {lo, hi}; return __builtin_bit_cast(unsigned, __builtin_convertvector(v, bfx2)); }
; template <int ROWS, int COLS, int LD> DI void stage_out(const bf16_t* stg, bf16_t* dst, size_t ld, int lane) {
;   asm volatile("s_waitcnt lgkmcnt(0)" ::: "memory");
;   constexpr int CPR = COLS / 8, IT = ROWS * CPR / 64;
; #pragma unroll
;   for (int it = 0; it < IT; ++it) {
;     const int idx = it * 64 + lane, r = idx / CPR, c = idx % CPR;
;     __builtin_nontemporal_store(*(const u32x4*)(stg + r * LD + c * 8), (u32x4*)(dst + (size_t)r * ld + c * 8));
;   }
; template <int KIND> DI void mlaup_tile(const Params& p, int layer, int tm, int tn, bf16_t* smem) {
;     ...
; #pragma unroll
;     for (int i = 0; i < 8; ++i) {
;       asm volatile("" ::: "memory");
;       const int t0 = trow0 + i * 16 + quad * 4; float rs[4];
; #pragma unroll
;       for (int r = 0; r < 4; ++r) { const float* c = cssq + (size_t)(t0 + r) * 16 + 8; rs[r] = rsqrtf((c[0] + c[1] + c[2] + c[3]) * (1.f / 256.f) + EPS_); }
; #pragma unroll
;       for (int j = 0; j < 4; ++j)
;         *(u32x2*)(stg + (j * 16 + l15) * VLD + i * 16 + quad * 4) = (u32x2){pk2(acc[i][j][0] * rs[0], acc[i][j][1] * rs[1]), pk2(acc[i][j][2] * rs[2], acc[i][j][3] * rs[3])};
;     }
;     stage_out<64, 128, VLD>(stg, dst + ((size_t)((trow0 >> 12) * 8 + h) * 64) * S_ + (trow0 & 4095), (size_t)S_, lane);
	v_mov_b32_e32 v27, v22
	v_mov_b32_e32 v22, v19
	v_pk_add_f32 v[18:19], v[26:27], v[22:23]
	v_mov_b32_e32 v22, v20
	v_mov_b32_e32 v23, v24
	v_pk_add_f32 v[18:19], v[18:19], v[22:23]
	v_mov_b32_e32 v24, v21
	v_pk_add_f32 v[18:19], v[18:19], v[24:25]
	s_nop 0
	v_pk_fma_f32 v[18:19], v[18:19], s[12:13], v[128:129] op_sel_hi:[1,0,0]
	s_nop 0
	v_mul_f32_e32 v13, 0x4b800000, v18
	v_cmp_gt_f32_e64 s[0:1], s29, v18
	v_cmp_gt_f32_e32 vcc, s29, v19
	s_nop 0
	v_cndmask_b32_e64 v13, v18, v13, s[0:1]
	v_rsq_f32_e32 v18, v13
	v_mul_f32_e32 v13, 0x4b800000, v19
	v_cndmask_b32_e32 v13, v19, v13, vcc
	v_rsq_f32_e32 v19, v13
	s_nop 0
	v_pk_mul_f32 v[20:21], v[18:19], s[10:11] op_sel_hi:[1,0]
	s_nop 0
	v_cndmask_b32_e32 v19, v19, v21, vcc
	v_cndmask_b32_e64 v18, v18, v20, s[0:1]
	v_pk_mul_f32 v[2:3], v[2:3], v[18:19]
	s_lshl_b32 s0, s36, 2
	v_cvt_pk_bf16_f32 v1, v2, v3
	ds_write_b64 v126, v[0:1] offset:13280
	s_sub_i32 s0, s0, 20
	v_ashrrev_i32_e32 v1, 9, v137
	v_and_or_b32 v0, v136, 3, s0
	v_and_b32_e32 v1, -8, v1
	v_add_u32_e32 v0, v0, v1
	v_ashrrev_i32_e32 v1, 31, v0
	v_readlane_b32 s0, v237, 31
	v_lshlrev_b64 v[0:1], 19, v[0:1]
	v_readlane_b32 s1, v237, 32
	v_and_b32_e32 v2, 0xf80, v137
	v_pk_mul_f32 v[14:15], v[14:15], v[18:19]
	v_pk_mul_f32 v[10:11], v[10:11], v[18:19]
	v_pk_mul_f32 v[6:7], v[6:7], v[18:19]
	v_lshl_add_u64 v[0:1], s[0:1], 0, v[0:1]
	v_lshlrev_b32_e32 v160, 1, v2
	v_lshlrev_b32_e32 v2, 4, v134
	v_cvt_pk_bf16_f32 v13, v14, v15
	v_cvt_pk_bf16_f32 v9, v10, v11
	v_cvt_pk_bf16_f32 v5, v6, v7
	v_lshl_add_u64 v[0:1], v[0:1], 0, v[160:161]
	v_and_b32_e32 v160, 0xf0, v2
	ds_write_b64 v126, v[12:13] offset:224
	ds_write_b64 v126, v[8:9] offset:4576
	ds_write_b64 v126, v[4:5] offset:8928
	v_or_b32_e32 v2, v135, v160
	v_bfe_u32 v6, v134, 4, 2
	s_waitcnt lgkmcnt(0)
	v_mad_u32_u24 v8, v6, s35, v2
	v_lshl_add_u64 v[4:5], v[0:1], 0, v[160:161]
	ds_read_b128 v[0:3], v8
	v_lshlrev_b32_e32 v160, 13, v6
	v_lshl_add_u64 v[6:7], v[4:5], 0, v[160:161]
	s_waitcnt lgkmcnt(0)
	global_store_dwordx4 v[6:7], v[0:3], off nt
	ds_read_b128 v[0:3], v8 offset:1088
	v_or_b32_e32 v6, 0x8000, v160
	v_mov_b32_e32 v7, v161
	v_lshl_add_u64 v[6:7], v[4:5], 0, v[6:7]
	s_waitcnt lgkmcnt(0)
	global_store_dwordx4 v[6:7], v[0:3], off nt
	ds_read_b128 v[0:3], v8 offset:2176
	v_or_b32_e32 v6, 0x10000, v160
	v_mov_b32_e32 v7, v161
	v_lshl_add_u64 v[6:7], v[4:5], 0, v[6:7]
	s_waitcnt lgkmcnt(0)
	global_store_dwordx4 v[6:7], v[0:3], off nt
	ds_read_b128 v[0:3], v8 offset:3264
	v_or_b32_e32 v6, 0x18000, v160
	v_mov_b32_e32 v7, v161
	v_lshl_add_u64 v[6:7], v[4:5], 0, v[6:7]
	s_waitcnt lgkmcnt(0)
	global_store_dwordx4 v[6:7], v[0:3], off nt
	ds_read_b128 v[0:3], v8 offset:4352
	v_or_b32_e32 v6, 0x20000, v160
	v_mov_b32_e32 v7, v161
	v_lshl_add_u64 v[6:7], v[4:5], 0, v[6:7]
	s_waitcnt lgkmcnt(0)
	global_store_dwordx4 v[6:7], v[0:3], off nt
	ds_read_b128 v[0:3], v8 offset:5440
	v_or_b32_e32 v6, 0x28000, v160
	v_mov_b32_e32 v7, v161
	v_lshl_add_u64 v[6:7], v[4:5], 0, v[6:7]
	s_waitcnt lgkmcnt(0)
	global_store_dwordx4 v[6:7], v[0:3], off nt
	ds_read_b128 v[0:3], v8 offset:6528
	v_or_b32_e32 v6, 0x30000, v160
	v_mov_b32_e32 v7, v161
	v_lshl_add_u64 v[6:7], v[4:5], 0, v[6:7]
	s_waitcnt lgkmcnt(0)
	global_store_dwordx4 v[6:7], v[0:3], off nt
	ds_read_b128 v[0:3], v8 offset:7616
	v_or_b32_e32 v6, 0x38000, v160
	v_mov_b32_e32 v7, v161
	v_lshl_add_u64 v[6:7], v[4:5], 0, v[6:7]
	s_waitcnt lgkmcnt(0)
	global_store_dwordx4 v[6:7], v[0:3], off nt
	ds_read_b128 v[0:3], v8 offset:8704
	v_or_b32_e32 v6, 0x40000, v160
	v_mov_b32_e32 v7, v161
	v_lshl_add_u64 v[6:7], v[4:5], 0, v[6:7]
	s_waitcnt lgkmcnt(0)
	global_store_dwordx4 v[6:7], v[0:3], off nt
	ds_read_b128 v[0:3], v8 offset:9792
	v_or_b32_e32 v6, 0x48000, v160
	v_mov_b32_e32 v7, v161
	v_lshl_add_u64 v[6:7], v[4:5], 0, v[6:7]
	s_waitcnt lgkmcnt(0)
	global_store_dwordx4 v[6:7], v[0:3], off nt
	ds_read_b128 v[0:3], v8 offset:10880
	v_or_b32_e32 v6, 0x50000, v160
	v_mov_b32_e32 v7, v161
	v_lshl_add_u64 v[6:7], v[4:5], 0, v[6:7]
	s_waitcnt lgkmcnt(0)
	global_store_dwordx4 v[6:7], v[0:3], off nt
	ds_read_b128 v[0:3], v8 offset:11968
	v_or_b32_e32 v6, 0x58000, v160
	v_mov_b32_e32 v7, v161
	v_lshl_add_u64 v[6:7], v[4:5], 0, v[6:7]
	s_waitcnt lgkmcnt(0)
	global_store_dwordx4 v[6:7], v[0:3], off nt
	ds_read_b128 v[0:3], v8 offset:13056
	v_or_b32_e32 v6, 0x60000, v160
	v_mov_b32_e32 v7, v161
	v_lshl_add_u64 v[6:7], v[4:5], 0, v[6:7]
	s_waitcnt lgkmcnt(0)
	global_store_dwordx4 v[6:7], v[0:3], off nt
	ds_read_b128 v[0:3], v8 offset:14144
	v_or_b32_e32 v6, 0x68000, v160
	v_mov_b32_e32 v7, v161
	v_lshl_add_u64 v[6:7], v[4:5], 0, v[6:7]
	s_waitcnt lgkmcnt(0)
	global_store_dwordx4 v[6:7], v[0:3], off nt
	ds_read_b128 v[0:3], v8 offset:15232
	v_or_b32_e32 v6, 0x70000, v160
	v_mov_b32_e32 v7, v161
	v_lshl_add_u64 v[6:7], v[4:5], 0, v[6:7]
	v_or_b32_e32 v160, 0x78000, v160
	s_waitcnt lgkmcnt(0)
	global_store_dwordx4 v[6:7], v[0:3], off nt
	ds_read_b128 v[0:3], v8 offset:16320
	v_lshl_add_u64 v[4:5], v[4:5], 0, v[160:161]
	s_waitcnt lgkmcnt(0)
	global_store_dwordx4 v[4:5], v[0:3], off nt
	s_barrier
	s_branch .LBB0_1405

; DI f32x4 mfma16(bf16x8 a, bf16x8 b, f32x4 c) { return __builtin_amdgcn_mfma_f32_16x16x32_bf16(a, b, c, 0, 0, 0); }
; template <int MI, int NJ, bool SWAP, class AP, class BP>
; DI void gemm_main(f32x4 (&acc)[MI][NJ], const AP& ap, int a_kstep, const BP& bp, int b_kstep, int nk, bf16_t* smem) {
;     ...
;   for (int kt = 0; kt < nk; ++kt) {
;     const int buf = kt & 1;
;     sstore(buf ^ 1);
;     gload(kt + 2 < nk ? kt + 2 : nk - 1);
;     __builtin_amdgcn_sched_barrier(0);
;     const bf16_t* As = smem + buf * L::STAGE + (wm * 16 * MI + l15) * LDT + quad * 8;
;     const bf16_t* Bs = smem + buf * L::STAGE + L::A_ELEMS + (wn * 16 * NJ + l15) * LDT + quad * 8;
; #pragma unroll
;     for (int ks = 0; ks < 2; ++ks) {
;       if (MI * NJ >= 32 && ks == 1) asm volatile("" ::: "memory");
;       bf16x8 b[NJ];
; #pragma unroll
;       for (int j = 0; j < NJ; ++j) b[j] = *(const bf16x8*)(Bs + j * 16 * LDT + ks * 32);
; #pragma unroll
;       for (int i = 0; i < MI; ++i) {
;         const bf16x8 a = *(const bf16x8*)(As + i * 16 * LDT + ks * 32);
; #pragma unroll
;         for (int j = 0; j < NJ; ++j) acc[i][j] = SWAP ? mfma16(b[j], a, acc[i][j]) : mfma16(a, b[j], acc[i][j]);
;       }
;     }
.Lgm13_main:
	ds_read_b128 v[242:245], v177 offset:4608
	s_waitcnt lgkmcnt(4)
	v_mfma_f32_16x16x32_bf16 v[156:159], v[178:181], v[194:197], v[156:159]
	s_waitcnt lgkmcnt(3)
	v_mfma_f32_16x16x32_bf16 v[152:155], v[182:185], v[194:197], v[152:155]
	s_waitcnt lgkmcnt(2)
	v_mfma_f32_16x16x32_bf16 v[148:151], v[186:189], v[194:197], v[148:151]
	s_waitcnt lgkmcnt(1)
	v_mfma_f32_16x16x32_bf16 v[144:147], v[190:193], v[194:197], v[144:147]
	s_and_b32 s15, s1, 1
	s_min_u32 s16, s1, 13
	s_xor_b32 s17, s15, 1
	s_lshl_b32 s26, s16, 7
	s_mul_i32 s17, s17, 0x12000
	s_add_u32 s16, s2, s26
	v_add3_u32 v250, s17, v172, v170
	v_add3_u32 v251, s17, v174, v170
	v_add3_u32 v252, s17, v175, v170
	v_add3_u32 v253, s17, v176, v170
	s_addc_u32 s17, s3, 0
	s_waitcnt vmcnt(7)
	ds_write_b128 v250, v[112:115]
	ds_read_b128 v[246:249], v177 offset:6912
	v_mfma_f32_16x16x32_bf16 v[108:111], v[178:181], v[198:201], v[108:111]
	v_mfma_f32_16x16x32_bf16 v[104:107], v[182:185], v[198:201], v[104:107]
	v_mfma_f32_16x16x32_bf16 v[100:103], v[186:189], v[198:201], v[100:103]
	v_mfma_f32_16x16x32_bf16 v[96:99], v[190:193], v[198:201], v[96:99]
	s_waitcnt vmcnt(6)
	ds_write_b128 v251, v[116:119]
	ds_read_b128 v[194:197], v177 offset:9216
	s_waitcnt lgkmcnt(4)
	v_mfma_f32_16x16x32_bf16 v[92:95], v[178:181], v[242:245], v[92:95]
	v_mfma_f32_16x16x32_bf16 v[88:91], v[182:185], v[242:245], v[88:91]
	v_mfma_f32_16x16x32_bf16 v[84:87], v[186:189], v[242:245], v[84:87]
	v_mfma_f32_16x16x32_bf16 v[80:83], v[190:193], v[242:245], v[80:83]
	ds_read_b128 v[198:201], v177 offset:11520
	s_waitcnt lgkmcnt(3)
	v_mfma_f32_16x16x32_bf16 v[76:79], v[178:181], v[246:249], v[76:79]
	s_waitcnt vmcnt(5)
	ds_write_b128 v252, v[120:123]
	v_mfma_f32_16x16x32_bf16 v[72:75], v[182:185], v[246:249], v[72:75]
	v_mfma_f32_16x16x32_bf16 v[68:71], v[186:189], v[246:249], v[68:71]
	v_mfma_f32_16x16x32_bf16 v[64:67], v[190:193], v[246:249], v[64:67]
	ds_read_b128 v[242:245], v177 offset:13824
	s_waitcnt lgkmcnt(3)
	v_mfma_f32_16x16x32_bf16 v[60:63], v[178:181], v[194:197], v[60:63]
	s_waitcnt vmcnt(4)
	ds_write_b128 v253, v[124:127]
	v_mfma_f32_16x16x32_bf16 v[56:59], v[182:185], v[194:197], v[56:59]
	v_mfma_f32_16x16x32_bf16 v[52:55], v[186:189], v[194:197], v[52:55]
	v_mfma_f32_16x16x32_bf16 v[48:51], v[190:193], v[194:197], v[48:51]
	ds_read_b128 v[246:249], v177 offset:16128
	s_waitcnt lgkmcnt(4)
	v_mfma_f32_16x16x32_bf16 v[44:47], v[178:181], v[198:201], v[44:47]
	s_waitcnt vmcnt(3)
	ds_write_b128 v250, v[128:131] offset:36864
	v_mfma_f32_16x16x32_bf16 v[40:43], v[182:185], v[198:201], v[40:43]
	v_mfma_f32_16x16x32_bf16 v[36:39], v[186:189], v[198:201], v[36:39]
	v_mfma_f32_16x16x32_bf16 v[32:35], v[190:193], v[198:201], v[32:35]
	ds_read_b128 v[194:197], v177 offset:64
	s_waitcnt lgkmcnt(4)
	v_mfma_f32_16x16x32_bf16 v[28:31], v[178:181], v[242:245], v[28:31]
	s_waitcnt vmcnt(2)
	ds_write_b128 v251, v[132:135] offset:36864
	v_mfma_f32_16x16x32_bf16 v[24:27], v[182:185], v[242:245], v[24:27]
	v_mfma_f32_16x16x32_bf16 v[20:23], v[186:189], v[242:245], v[20:23]
	v_mfma_f32_16x16x32_bf16 v[16:19], v[190:193], v[242:245], v[16:19]
	ds_read_b128 v[198:201], v177 offset:2368
	s_waitcnt lgkmcnt(4)
	v_mfma_f32_16x16x32_bf16 v[8:11], v[178:181], v[246:249], v[8:11]
	ds_read_b128 v[178:181], v202 offset:36928
	s_waitcnt vmcnt(1)
	ds_write_b128 v252, v[136:139] offset:36864
	v_mfma_f32_16x16x32_bf16 v[4:7], v[182:185], v[246:249], v[4:7]
	ds_read_b128 v[182:185], v202 offset:39232
	v_mfma_f32_16x16x32_bf16 v[0:3], v[186:189], v[246:249], v[0:3]
	ds_read_b128 v[186:189], v202 offset:41536
	v_mfma_f32_16x16x32_bf16 v[12:15], v[190:193], v[246:249], v[12:15]
	ds_read_b128 v[190:193], v202 offset:43840
	ds_read_b128 v[242:245], v177 offset:4672
	s_waitcnt lgkmcnt(5)
	v_mfma_f32_16x16x32_bf16 v[156:159], v[178:181], v[194:197], v[156:159]
	s_waitcnt lgkmcnt(3)
	v_mfma_f32_16x16x32_bf16 v[152:155], v[182:185], v[194:197], v[152:155]
	s_waitcnt vmcnt(0)
	ds_write_b128 v253, v[140:143] offset:36864
	s_waitcnt lgkmcnt(3)
	v_mfma_f32_16x16x32_bf16 v[148:151], v[186:189], v[194:197], v[148:151]
	s_waitcnt lgkmcnt(2)
	v_mfma_f32_16x16x32_bf16 v[144:147], v[190:193], v[194:197], v[144:147]
	v_lshl_add_u64 v[112:113], s[16:17], 0, v[162:163]
	v_lshl_add_u64 v[116:117], s[16:17], 0, v[164:165]
	v_lshl_add_u64 v[120:121], s[16:17], 0, v[166:167]
	v_lshl_add_u64 v[124:125], s[16:17], 0, v[168:169]
	s_add_u32 s16, s12, s26
	s_addc_u32 s17, s13, 0
	v_lshl_add_u64 v[128:129], s[16:17], 0, v[162:163]
	v_lshl_add_u64 v[132:133], s[16:17], 0, v[164:165]
	v_lshl_add_u64 v[136:137], s[16:17], 0, v[166:167]
	v_lshl_add_u64 v[140:141], s[16:17], 0, v[168:169]
	global_load_dwordx4 v[112:115], v[112:113], off offset:256
	ds_read_b128 v[246:249], v177 offset:6976
	v_mfma_f32_16x16x32_bf16 v[108:111], v[178:181], v[198:201], v[108:111]
	v_mfma_f32_16x16x32_bf16 v[104:107], v[182:185], v[198:201], v[104:107]
	s_nop 0
	global_load_dwordx4 v[116:119], v[116:117], off offset:256
	v_mfma_f32_16x16x32_bf16 v[100:103], v[186:189], v[198:201], v[100:103]
	v_mfma_f32_16x16x32_bf16 v[96:99], v[190:193], v[198:201], v[96:99]
	ds_read_b128 v[194:197], v177 offset:9280
	s_waitcnt lgkmcnt(3)
	v_mfma_f32_16x16x32_bf16 v[92:95], v[178:181], v[242:245], v[92:95]
	s_nop 0
	global_load_dwordx4 v[120:123], v[120:121], off offset:256
	v_mfma_f32_16x16x32_bf16 v[88:91], v[182:185], v[242:245], v[88:91]
	v_mfma_f32_16x16x32_bf16 v[84:87], v[186:189], v[242:245], v[84:87]
	s_nop 0
	global_load_dwordx4 v[124:127], v[124:125], off offset:256
	v_mfma_f32_16x16x32_bf16 v[80:83], v[190:193], v[242:245], v[80:83]
	ds_read_b128 v[198:201], v177 offset:11584
	s_waitcnt lgkmcnt(2)
	v_mfma_f32_16x16x32_bf16 v[76:79], v[178:181], v[246:249], v[76:79]
	v_mfma_f32_16x16x32_bf16 v[72:75], v[182:185], v[246:249], v[72:75]
	s_nop 0
	global_load_dwordx4 v[128:131], v[128:129], off offset:256
	v_mfma_f32_16x16x32_bf16 v[68:71], v[186:189], v[246:249], v[68:71]
	v_mfma_f32_16x16x32_bf16 v[64:67], v[190:193], v[246:249], v[64:67]
	s_nop 0
	global_load_dwordx4 v[132:135], v[132:133], off offset:256
	ds_read_b128 v[242:245], v177 offset:13888
	s_waitcnt lgkmcnt(2)
	v_mfma_f32_16x16x32_bf16 v[60:63], v[178:181], v[194:197], v[60:63]
	v_mfma_f32_16x16x32_bf16 v[56:59], v[182:185], v[194:197], v[56:59]
	v_mfma_f32_16x16x32_bf16 v[52:55], v[186:189], v[194:197], v[52:55]
	s_nop 0
	global_load_dwordx4 v[136:139], v[136:137], off offset:256
	v_mfma_f32_16x16x32_bf16 v[48:51], v[190:193], v[194:197], v[48:51]
	ds_read_b128 v[246:249], v177 offset:16192
	s_waitcnt lgkmcnt(2)
	v_mfma_f32_16x16x32_bf16 v[44:47], v[178:181], v[198:201], v[44:47]
	s_nop 0
	global_load_dwordx4 v[140:143], v[140:141], off offset:256
	v_mfma_f32_16x16x32_bf16 v[40:43], v[182:185], v[198:201], v[40:43]
	v_mfma_f32_16x16x32_bf16 v[36:39], v[186:189], v[198:201], v[36:39]
	v_mfma_f32_16x16x32_bf16 v[32:35], v[190:193], v[198:201], v[32:35]
	s_waitcnt lgkmcnt(0)
	s_barrier
; DI f32x4 mfma16(bf16x8 a, bf16x8 b, f32x4 c) { return __builtin_amdgcn_mfma_f32_16x16x32_bf16(a, b, c, 0, 0, 0); }
; template <int MI, int NJ, bool SWAP, class AP, class BP>
; DI void gemm_main(f32x4 (&acc)[MI][NJ], const AP& ap, int a_kstep, const BP& bp, int b_kstep, int nk, bf16_t* smem) {
;     ...
;   for (int kt = 0; kt < nk; ++kt) {
;     const int buf = kt & 1;
;     sstore(buf ^ 1);
;     gload(kt + 2 < nk ? kt + 2 : nk - 1);
;     __builtin_amdgcn_sched_barrier(0);
;     const bf16_t* As = smem + buf * L::STAGE + (wm * 16 * MI + l15) * LDT + quad * 8;
;     const bf16_t* Bs = smem + buf * L::STAGE + L::A_ELEMS + (wn * 16 * NJ + l15) * LDT + quad * 8;
; #pragma unroll
;     for (int ks = 0; ks < 2; ++ks) {
;       if (MI * NJ >= 32 && ks == 1) asm volatile("" ::: "memory");
;       bf16x8 b[NJ];
; #pragma unroll
;       for (int j = 0; j < NJ; ++j) b[j] = *(const bf16x8*)(Bs + j * 16 * LDT + ks * 32);
; #pragma unroll
;       for (int i = 0; i < MI; ++i) {
;         const bf16x8 a = *(const bf16x8*)(As + i * 16 * LDT + ks * 32);
; #pragma unroll
;         for (int j = 0; j < NJ; ++j) acc[i][j] = SWAP ? mfma16(b[j], a, acc[i][j]) : mfma16(a, b[j], acc[i][j]);
;       }
;     }
;     __syncthreads();
;   }
	s_add_i32 s1, s1, 1
	s_cmp_lg_u32 s1, 16
	s_cbranch_scc0 .Lgm13_exit
	s_and_b32 s98, s1, 1
	s_mul_i32 s98, s98, 0x12000
	v_add3_u32 v202, s98, v160, v173
	v_add3_u32 v177, s98, v171, v173
	ds_read_b128 v[194:197], v177
	ds_read_b128 v[198:201], v177 offset:2304
	v_mfma_f32_16x16x32_bf16 v[28:31], v[178:181], v[242:245], v[28:31]
	v_mfma_f32_16x16x32_bf16 v[8:11], v[178:181], v[246:249], v[8:11]
	ds_read_b128 v[178:181], v202 offset:36864
	v_mfma_f32_16x16x32_bf16 v[24:27], v[182:185], v[242:245], v[24:27]
	v_mfma_f32_16x16x32_bf16 v[4:7], v[182:185], v[246:249], v[4:7]
	ds_read_b128 v[182:185], v202 offset:39168
	v_mfma_f32_16x16x32_bf16 v[20:23], v[186:189], v[242:245], v[20:23]
	v_mfma_f32_16x16x32_bf16 v[0:3], v[186:189], v[246:249], v[0:3]
	ds_read_b128 v[186:189], v202 offset:41472
	v_mfma_f32_16x16x32_bf16 v[16:19], v[190:193], v[242:245], v[16:19]
	v_mfma_f32_16x16x32_bf16 v[12:15], v[190:193], v[246:249], v[12:15]
	ds_read_b128 v[190:193], v202 offset:43776
	s_branch .Lgm13_main

; DI f32x4 mfma16(bf16x8 a, bf16x8 b, f32x4 c) { return __builtin_amdgcn_mfma_f32_16x16x32_bf16(a, b, c, 0, 0, 0); }
; template <int MI, int NJ, bool SWAP, class AP, class BP>
; DI void gemm_main(f32x4 (&acc)[MI][NJ], const AP& ap, int a_kstep, const BP& bp, int b_kstep, int nk, bf16_t* smem) {
;     ...
;   auto sstore = [&](int buf) {
;     bf16_t* As = smem + buf * L::STAGE; bf16_t* Bs = As + L::A_ELEMS;
; #pragma unroll
;     for (int i = 0; i < CA; ++i) { const int c = tid + NTHR * i; *(u32x4*)(As + (c >> 3) * LDT + (c & 7) * 8) = oka[i] ? ra[i] : (u32x4){0u, 0u, 0u, 0u}; }
; #pragma unroll
;     for (int i = 0; i < CB; ++i) { const int c = tid + NTHR * i; *(u32x4*)(Bs + (c >> 3) * LDT + (c & 7) * 8) = rb[i]; }
;   };
;   gload(0); sstore(0); gload(nk > 1 ? 1 : 0); __syncthreads();
; #pragma unroll 1
;   for (int kt = 0; kt < nk; ++kt) {
;     const int buf = kt & 1;
;     sstore(buf ^ 1);
;     gload(kt + 2 < nk ? kt + 2 : nk - 1);
;     __builtin_amdgcn_sched_barrier(0);
;     const bf16_t* As = smem + buf * L::STAGE + (wm * 16 * MI + l15) * LDT + quad * 8;
;     const bf16_t* Bs = smem + buf * L::STAGE + L::A_ELEMS + (wn * 16 * NJ + l15) * LDT + quad * 8;
; #pragma unroll
;     for (int ks = 0; ks < 2; ++ks) {
;       if (MI * NJ >= 32 && ks == 1) asm volatile("" ::: "memory");
;       bf16x8 b[NJ];
; #pragma unroll
;       for (int j = 0; j < NJ; ++j) b[j] = *(const bf16x8*)(Bs + j * 16 * LDT + ks * 32);
; #pragma unroll
;       for (int i = 0; i < MI; ++i) {
;         const bf16x8 a = *(const bf16x8*)(As + i * 16 * LDT + ks * 32);
; #pragma unroll
;         for (int j = 0; j < NJ; ++j) acc[i][j] = SWAP ? mfma16(b[j], a, acc[i][j]) : mfma16(a, b[j], acc[i][j]);
;       }
;     }
.Lgm14_main:
	ds_read_b128 v[242:245], v181 offset:4608
	s_waitcnt lgkmcnt(4)
	v_mfma_f32_16x16x32_bf16 v[156:159], v[182:185], v[198:201], v[156:159]
	s_waitcnt lgkmcnt(3)
	v_mfma_f32_16x16x32_bf16 v[152:155], v[186:189], v[198:201], v[152:155]
	s_waitcnt lgkmcnt(2)
	v_mfma_f32_16x16x32_bf16 v[148:151], v[190:193], v[198:201], v[148:151]
	s_waitcnt lgkmcnt(1)
	v_mfma_f32_16x16x32_bf16 v[144:147], v[194:197], v[198:201], v[144:147]
	s_and_b32 s46, s43, 1
	s_min_u32 s44, s43, 13
	s_xor_b32 s45, s46, 1
	s_lshl_b32 s47, s44, 7
	s_mul_i32 s45, s45, 0x12000
	s_waitcnt vmcnt(7)
	v_cndmask_b32_e32 v143, 0, v143, vcc
	v_cndmask_b32_e32 v142, 0, v142, vcc
	v_cndmask_b32_e32 v141, 0, v141, vcc
	v_cndmask_b32_e32 v140, 0, v140, vcc
	s_add_u32 s44, s18, s47
	v_add3_u32 v250, s45, v172, v169
	s_waitcnt vmcnt(6)
	v_cndmask_b32_e64 v131, 0, v131, s[0:1]
	v_cndmask_b32_e64 v130, 0, v130, s[0:1]
	v_cndmask_b32_e64 v129, 0, v129, s[0:1]
	v_cndmask_b32_e64 v128, 0, v128, s[0:1]
	s_waitcnt vmcnt(5)
	v_cndmask_b32_e64 v115, 0, v115, s[2:3]
	v_cndmask_b32_e64 v114, 0, v114, s[2:3]
	v_cndmask_b32_e64 v113, 0, v113, s[2:3]
	v_cndmask_b32_e64 v112, 0, v112, s[2:3]
	s_waitcnt vmcnt(4)
	v_cndmask_b32_e64 v135, 0, v135, s[4:5]
	v_cndmask_b32_e64 v134, 0, v134, s[4:5]
	v_cndmask_b32_e64 v133, 0, v133, s[4:5]
	v_cndmask_b32_e64 v132, 0, v132, s[4:5]
	v_add3_u32 v251, s45, v173, v169
	v_add3_u32 v252, s45, v174, v169
	v_add3_u32 v253, s45, v175, v169
	s_addc_u32 s45, s19, 0
	ds_write_b128 v250, v[140:143]
	ds_read_b128 v[246:249], v181 offset:6912
	v_mfma_f32_16x16x32_bf16 v[108:111], v[182:185], v[202:205], v[108:111]
	v_mfma_f32_16x16x32_bf16 v[104:107], v[186:189], v[202:205], v[104:107]
	v_mfma_f32_16x16x32_bf16 v[100:103], v[190:193], v[202:205], v[100:103]
	v_mfma_f32_16x16x32_bf16 v[96:99], v[194:197], v[202:205], v[96:99]
	ds_write_b128 v251, v[128:131]
	ds_read_b128 v[198:201], v181 offset:9216
	s_waitcnt lgkmcnt(4)
	v_mfma_f32_16x16x32_bf16 v[92:95], v[182:185], v[242:245], v[92:95]
	v_mfma_f32_16x16x32_bf16 v[88:91], v[186:189], v[242:245], v[88:91]
	v_mfma_f32_16x16x32_bf16 v[84:87], v[190:193], v[242:245], v[84:87]
	v_mfma_f32_16x16x32_bf16 v[80:83], v[194:197], v[242:245], v[80:83]
	ds_read_b128 v[202:205], v181 offset:11520
	s_waitcnt lgkmcnt(3)
	v_mfma_f32_16x16x32_bf16 v[76:79], v[182:185], v[246:249], v[76:79]
	ds_write_b128 v252, v[112:115]
	v_mfma_f32_16x16x32_bf16 v[72:75], v[186:189], v[246:249], v[72:75]
	v_mfma_f32_16x16x32_bf16 v[68:71], v[190:193], v[246:249], v[68:71]
	v_mfma_f32_16x16x32_bf16 v[64:67], v[194:197], v[246:249], v[64:67]
	ds_read_b128 v[242:245], v181 offset:13824
	s_waitcnt lgkmcnt(3)
	v_mfma_f32_16x16x32_bf16 v[60:63], v[182:185], v[198:201], v[60:63]
	ds_write_b128 v253, v[132:135]
	v_mfma_f32_16x16x32_bf16 v[56:59], v[186:189], v[198:201], v[56:59]
	v_mfma_f32_16x16x32_bf16 v[52:55], v[190:193], v[198:201], v[52:55]
	v_mfma_f32_16x16x32_bf16 v[48:51], v[194:197], v[198:201], v[48:51]
	ds_read_b128 v[246:249], v181 offset:16128
	s_waitcnt lgkmcnt(4)
	v_mfma_f32_16x16x32_bf16 v[44:47], v[182:185], v[202:205], v[44:47]
	s_waitcnt vmcnt(3)
	ds_write_b128 v250, v[116:119] offset:36864
	v_mfma_f32_16x16x32_bf16 v[40:43], v[186:189], v[202:205], v[40:43]
	v_mfma_f32_16x16x32_bf16 v[36:39], v[190:193], v[202:205], v[36:39]
	v_mfma_f32_16x16x32_bf16 v[32:35], v[194:197], v[202:205], v[32:35]
	ds_read_b128 v[198:201], v181 offset:64
	s_waitcnt lgkmcnt(4)
	v_mfma_f32_16x16x32_bf16 v[28:31], v[182:185], v[242:245], v[28:31]
	s_waitcnt vmcnt(2)
	ds_write_b128 v251, v[120:123] offset:36864
	v_mfma_f32_16x16x32_bf16 v[24:27], v[186:189], v[242:245], v[24:27]
	v_mfma_f32_16x16x32_bf16 v[20:23], v[190:193], v[242:245], v[20:23]
	v_mfma_f32_16x16x32_bf16 v[12:15], v[194:197], v[242:245], v[12:15]
	ds_read_b128 v[202:205], v181 offset:2368
	s_waitcnt lgkmcnt(4)
	v_mfma_f32_16x16x32_bf16 v[8:11], v[182:185], v[246:249], v[8:11]
	ds_read_b128 v[182:185], v206 offset:36928
	s_waitcnt vmcnt(1)
; DI f32x4 mfma16(bf16x8 a, bf16x8 b, f32x4 c) { return __builtin_amdgcn_mfma_f32_16x16x32_bf16(a, b, c, 0, 0, 0); }
; template <int MI, int NJ, bool SWAP, class AP, class BP>
; DI void gemm_main(f32x4 (&acc)[MI][NJ], const AP& ap, int a_kstep, const BP& bp, int b_kstep, int nk, bf16_t* smem) {
;     ...
;   for (int kt = 0; kt < nk; ++kt) {
;     const int buf = kt & 1;
;     sstore(buf ^ 1);
;     gload(kt + 2 < nk ? kt + 2 : nk - 1);
;     __builtin_amdgcn_sched_barrier(0);
;     const bf16_t* As = smem + buf * L::STAGE + (wm * 16 * MI + l15) * LDT + quad * 8;
;     const bf16_t* Bs = smem + buf * L::STAGE + L::A_ELEMS + (wn * 16 * NJ + l15) * LDT + quad * 8;
; #pragma unroll
;     for (int ks = 0; ks < 2; ++ks) {
;       if (MI * NJ >= 32 && ks == 1) asm volatile("" ::: "memory");
;       bf16x8 b[NJ];
; #pragma unroll
;       for (int j = 0; j < NJ; ++j) b[j] = *(const bf16x8*)(Bs + j * 16 * LDT + ks * 32);
; #pragma unroll
;       for (int i = 0; i < MI; ++i) {
;         const bf16x8 a = *(const bf16x8*)(As + i * 16 * LDT + ks * 32);
; #pragma unroll
;         for (int j = 0; j < NJ; ++j) acc[i][j] = SWAP ? mfma16(b[j], a, acc[i][j]) : mfma16(a, b[j], acc[i][j]);
;       }
;     }
;     __syncthreads();
;   }
	ds_write_b128 v252, v[124:127] offset:36864
	v_mfma_f32_16x16x32_bf16 v[4:7], v[186:189], v[246:249], v[4:7]
	ds_read_b128 v[186:189], v206 offset:39232
	v_mfma_f32_16x16x32_bf16 v[0:3], v[190:193], v[246:249], v[0:3]
	ds_read_b128 v[190:193], v206 offset:41536
	v_mfma_f32_16x16x32_bf16 v[16:19], v[194:197], v[246:249], v[16:19]
	ds_read_b128 v[194:197], v206 offset:43840
	ds_read_b128 v[242:245], v181 offset:4672
	s_waitcnt lgkmcnt(5)
	v_mfma_f32_16x16x32_bf16 v[156:159], v[182:185], v[198:201], v[156:159]
	s_waitcnt lgkmcnt(3)
	v_mfma_f32_16x16x32_bf16 v[152:155], v[186:189], v[198:201], v[152:155]
	s_waitcnt vmcnt(0)
	ds_write_b128 v253, v[136:139] offset:36864
	s_waitcnt lgkmcnt(3)
	v_mfma_f32_16x16x32_bf16 v[148:151], v[190:193], v[198:201], v[148:151]
	s_waitcnt lgkmcnt(2)
	v_mfma_f32_16x16x32_bf16 v[144:147], v[194:197], v[198:201], v[144:147]
	global_load_dwordx4 v[140:143], v176, s[44:45] offset:256
	ds_read_b128 v[246:249], v181 offset:6976
	v_mfma_f32_16x16x32_bf16 v[108:111], v[182:185], v[202:205], v[108:111]
	v_mfma_f32_16x16x32_bf16 v[104:107], v[186:189], v[202:205], v[104:107]
	global_load_dwordx4 v[128:131], v177, s[44:45] offset:256
	v_mfma_f32_16x16x32_bf16 v[100:103], v[190:193], v[202:205], v[100:103]
	v_mfma_f32_16x16x32_bf16 v[96:99], v[194:197], v[202:205], v[96:99]
	ds_read_b128 v[198:201], v181 offset:9280
	s_waitcnt lgkmcnt(3)
	v_mfma_f32_16x16x32_bf16 v[92:95], v[182:185], v[242:245], v[92:95]
	global_load_dwordx4 v[112:115], v178, s[44:45] offset:256
	v_mfma_f32_16x16x32_bf16 v[88:91], v[186:189], v[242:245], v[88:91]
	v_mfma_f32_16x16x32_bf16 v[84:87], v[190:193], v[242:245], v[84:87]
	global_load_dwordx4 v[132:135], v179, s[44:45] offset:256
	v_mfma_f32_16x16x32_bf16 v[80:83], v[194:197], v[242:245], v[80:83]
	ds_read_b128 v[202:205], v181 offset:11584
	s_waitcnt lgkmcnt(2)
	v_mfma_f32_16x16x32_bf16 v[76:79], v[182:185], v[246:249], v[76:79]
	v_mfma_f32_16x16x32_bf16 v[72:75], v[186:189], v[246:249], v[72:75]
	s_add_u32 s44, s20, s47
	s_addc_u32 s45, s21, 0
	v_lshl_add_u64 v[116:117], v[160:161], 1, s[44:45]
	v_lshl_add_u64 v[120:121], v[162:163], 1, s[44:45]
	v_lshl_add_u64 v[124:125], v[164:165], 1, s[44:45]
	v_lshl_add_u64 v[136:137], v[166:167], 1, s[44:45]
	global_load_dwordx4 v[116:119], v[116:117], off offset:256
	v_mfma_f32_16x16x32_bf16 v[68:71], v[190:193], v[246:249], v[68:71]
	v_mfma_f32_16x16x32_bf16 v[64:67], v[194:197], v[246:249], v[64:67]
	s_nop 0
	global_load_dwordx4 v[120:123], v[120:121], off offset:256
	ds_read_b128 v[242:245], v181 offset:13888
	s_waitcnt lgkmcnt(2)
	v_mfma_f32_16x16x32_bf16 v[60:63], v[182:185], v[198:201], v[60:63]
	v_mfma_f32_16x16x32_bf16 v[56:59], v[186:189], v[198:201], v[56:59]
	v_mfma_f32_16x16x32_bf16 v[52:55], v[190:193], v[198:201], v[52:55]
	s_nop 0
	global_load_dwordx4 v[124:127], v[124:125], off offset:256
	v_mfma_f32_16x16x32_bf16 v[48:51], v[194:197], v[198:201], v[48:51]
	ds_read_b128 v[246:249], v181 offset:16192
	s_waitcnt lgkmcnt(2)
	v_mfma_f32_16x16x32_bf16 v[44:47], v[182:185], v[202:205], v[44:47]
	s_nop 0
	global_load_dwordx4 v[136:139], v[136:137], off offset:256
	v_mfma_f32_16x16x32_bf16 v[40:43], v[186:189], v[202:205], v[40:43]
	v_mfma_f32_16x16x32_bf16 v[36:39], v[190:193], v[202:205], v[36:39]
	v_mfma_f32_16x16x32_bf16 v[32:35], v[194:197], v[202:205], v[32:35]
	s_waitcnt lgkmcnt(0)
	s_barrier
	s_add_i32 s43, s43, 1
	s_cmp_lg_u32 s43, 16
	s_cbranch_scc0 .Lgm14_exit
	s_and_b32 s98, s43, 1
	s_mul_i32 s98, s98, 0x12000
	v_add3_u32 v206, s98, v171, v180
	v_add3_u32 v181, s98, v170, v180
	ds_read_b128 v[198:201], v181
	ds_read_b128 v[202:205], v181 offset:2304
	v_mfma_f32_16x16x32_bf16 v[28:31], v[182:185], v[242:245], v[28:31]
	v_mfma_f32_16x16x32_bf16 v[8:11], v[182:185], v[246:249], v[8:11]
	ds_read_b128 v[182:185], v206 offset:36864
	v_mfma_f32_16x16x32_bf16 v[24:27], v[186:189], v[242:245], v[24:27]
	v_mfma_f32_16x16x32_bf16 v[4:7], v[186:189], v[246:249], v[4:7]
	ds_read_b128 v[186:189], v206 offset:39168
	v_mfma_f32_16x16x32_bf16 v[20:23], v[190:193], v[242:245], v[20:23]
	v_mfma_f32_16x16x32_bf16 v[0:3], v[190:193], v[246:249], v[0:3]
	ds_read_b128 v[190:193], v206 offset:41472
	v_mfma_f32_16x16x32_bf16 v[12:15], v[194:197], v[242:245], v[12:15]
	v_mfma_f32_16x16x32_bf16 v[16:19], v[194:197], v[246:249], v[16:19]
	ds_read_b128 v[194:197], v206 offset:43776
	s_branch .Lgm14_main

; DI f32x4 mfma16(bf16x8 a, bf16x8 b, f32x4 c) { return __builtin_amdgcn_mfma_f32_16x16x32_bf16(a, b, c, 0, 0, 0); }
; template <int MI, int NJ, bool SWAP, class AP, class BP>
; DI void gemm_main(f32x4 (&acc)[MI][NJ], const AP& ap, int a_kstep, const BP& bp, int b_kstep, int nk, bf16_t* smem) {
;     ...
;   for (int kt = 0; kt < nk; ++kt) {
;     const int buf = kt & 1;
;     sstore(buf ^ 1);
;     gload(kt + 2 < nk ? kt + 2 : nk - 1);
;     __builtin_amdgcn_sched_barrier(0);
;     const bf16_t* As = smem + buf * L::STAGE + (wm * 16 * MI + l15) * LDT + quad * 8;
;     const bf16_t* Bs = smem + buf * L::STAGE + L::A_ELEMS + (wn * 16 * NJ + l15) * LDT + quad * 8;
; #pragma unroll
;     for (int ks = 0; ks < 2; ++ks) {
;       if (MI * NJ >= 32 && ks == 1) asm volatile("" ::: "memory");
;       bf16x8 b[NJ];
; #pragma unroll
;       for (int j = 0; j < NJ; ++j) b[j] = *(const bf16x8*)(Bs + j * 16 * LDT + ks * 32);
; #pragma unroll
;       for (int i = 0; i < MI; ++i) {
;         const bf16x8 a = *(const bf16x8*)(As + i * 16 * LDT + ks * 32);
; #pragma unroll
;         for (int j = 0; j < NJ; ++j) acc[i][j] = SWAP ? mfma16(b[j], a, acc[i][j]) : mfma16(a, b[j], acc[i][j]);
;       }
;     }
;     __syncthreads();
;   }
.Lgm15_main:
	ds_read_b128 v[242:245], v177 offset:4608
	s_waitcnt lgkmcnt(4)
	v_mfma_f32_16x16x32_bf16 v[156:159], v[178:181], v[194:197], v[156:159]
	s_waitcnt lgkmcnt(3)
	v_mfma_f32_16x16x32_bf16 v[152:155], v[182:185], v[194:197], v[152:155]
	s_waitcnt lgkmcnt(2)
	v_mfma_f32_16x16x32_bf16 v[148:151], v[186:189], v[194:197], v[148:151]
	s_waitcnt lgkmcnt(1)
	v_mfma_f32_16x16x32_bf16 v[144:147], v[190:193], v[194:197], v[144:147]
	s_and_b32 s17, s16, 1
	s_min_u32 s18, s16, 41
	s_xor_b32 s19, s17, 1
	s_lshl_b32 s20, s18, 7
	s_mul_i32 s19, s19, 0x12000
	s_add_u32 s18, s2, s20
	v_add3_u32 v250, s19, v172, v170
	v_add3_u32 v251, s19, v173, v170
	v_add3_u32 v252, s19, v174, v170
	v_add3_u32 v253, s19, v175, v170
	s_addc_u32 s19, s3, 0
	s_waitcnt vmcnt(7)
	ds_write_b128 v250, v[112:115]
	ds_read_b128 v[246:249], v177 offset:6912
	v_mfma_f32_16x16x32_bf16 v[108:111], v[178:181], v[198:201], v[108:111]
	v_mfma_f32_16x16x32_bf16 v[104:107], v[182:185], v[198:201], v[104:107]
	v_mfma_f32_16x16x32_bf16 v[100:103], v[186:189], v[198:201], v[100:103]
	v_mfma_f32_16x16x32_bf16 v[96:99], v[190:193], v[198:201], v[96:99]
	s_waitcnt vmcnt(6)
	ds_write_b128 v251, v[116:119]
	ds_read_b128 v[194:197], v177 offset:9216
	s_waitcnt lgkmcnt(4)
	v_mfma_f32_16x16x32_bf16 v[92:95], v[178:181], v[242:245], v[92:95]
	v_mfma_f32_16x16x32_bf16 v[88:91], v[182:185], v[242:245], v[88:91]
	v_mfma_f32_16x16x32_bf16 v[84:87], v[186:189], v[242:245], v[84:87]
	v_mfma_f32_16x16x32_bf16 v[80:83], v[190:193], v[242:245], v[80:83]
	ds_read_b128 v[198:201], v177 offset:11520
	s_waitcnt lgkmcnt(3)
	v_mfma_f32_16x16x32_bf16 v[76:79], v[178:181], v[246:249], v[76:79]
	s_waitcnt vmcnt(5)
	ds_write_b128 v252, v[120:123]
	v_mfma_f32_16x16x32_bf16 v[72:75], v[182:185], v[246:249], v[72:75]
	v_mfma_f32_16x16x32_bf16 v[68:71], v[186:189], v[246:249], v[68:71]
	v_mfma_f32_16x16x32_bf16 v[64:67], v[190:193], v[246:249], v[64:67]
	ds_read_b128 v[242:245], v177 offset:13824
	s_waitcnt lgkmcnt(3)
	v_mfma_f32_16x16x32_bf16 v[60:63], v[178:181], v[194:197], v[60:63]
	s_waitcnt vmcnt(4)
	ds_write_b128 v253, v[124:127]
	v_mfma_f32_16x16x32_bf16 v[56:59], v[182:185], v[194:197], v[56:59]
	v_mfma_f32_16x16x32_bf16 v[52:55], v[186:189], v[194:197], v[52:55]
	v_mfma_f32_16x16x32_bf16 v[48:51], v[190:193], v[194:197], v[48:51]
	ds_read_b128 v[246:249], v177 offset:16128
	s_waitcnt lgkmcnt(4)
	v_mfma_f32_16x16x32_bf16 v[44:47], v[178:181], v[198:201], v[44:47]
	s_waitcnt vmcnt(3)
	ds_write_b128 v250, v[128:131] offset:36864
	v_mfma_f32_16x16x32_bf16 v[40:43], v[182:185], v[198:201], v[40:43]
	v_mfma_f32_16x16x32_bf16 v[36:39], v[186:189], v[198:201], v[36:39]
	v_mfma_f32_16x16x32_bf16 v[32:35], v[190:193], v[198:201], v[32:35]
	ds_read_b128 v[194:197], v177 offset:64
	s_waitcnt lgkmcnt(4)
	v_mfma_f32_16x16x32_bf16 v[28:31], v[178:181], v[242:245], v[28:31]
	s_waitcnt vmcnt(2)
	ds_write_b128 v251, v[132:135] offset:36864
	v_mfma_f32_16x16x32_bf16 v[24:27], v[182:185], v[242:245], v[24:27]
	v_mfma_f32_16x16x32_bf16 v[20:23], v[186:189], v[242:245], v[20:23]
	v_mfma_f32_16x16x32_bf16 v[16:19], v[190:193], v[242:245], v[16:19]
	ds_read_b128 v[198:201], v177 offset:2368
	s_waitcnt lgkmcnt(4)
	v_mfma_f32_16x16x32_bf16 v[8:11], v[178:181], v[246:249], v[8:11]
	ds_read_b128 v[178:181], v202 offset:36928
	s_waitcnt vmcnt(1)
	ds_write_b128 v252, v[136:139] offset:36864
	v_mfma_f32_16x16x32_bf16 v[4:7], v[182:185], v[246:249], v[4:7]
	ds_read_b128 v[182:185], v202 offset:39232
	v_mfma_f32_16x16x32_bf16 v[0:3], v[186:189], v[246:249], v[0:3]
	ds_read_b128 v[186:189], v202 offset:41536
	v_mfma_f32_16x16x32_bf16 v[12:15], v[190:193], v[246:249], v[12:15]
	ds_read_b128 v[190:193], v202 offset:43840
	ds_read_b128 v[242:245], v177 offset:4672
	s_waitcnt lgkmcnt(5)
	v_mfma_f32_16x16x32_bf16 v[156:159], v[178:181], v[194:197], v[156:159]
	s_waitcnt lgkmcnt(3)
	v_mfma_f32_16x16x32_bf16 v[152:155], v[182:185], v[194:197], v[152:155]
	s_waitcnt vmcnt(0)
	ds_write_b128 v253, v[140:143] offset:36864
	s_waitcnt lgkmcnt(3)
	v_mfma_f32_16x16x32_bf16 v[148:151], v[186:189], v[194:197], v[148:151]
	s_waitcnt lgkmcnt(2)
	v_mfma_f32_16x16x32_bf16 v[144:147], v[190:193], v[194:197], v[144:147]
	v_lshl_add_u64 v[112:113], s[18:19], 0, v[162:163]
	v_lshl_add_u64 v[116:117], s[18:19], 0, v[164:165]
	v_lshl_add_u64 v[120:121], s[18:19], 0, v[166:167]
	v_lshl_add_u64 v[124:125], s[18:19], 0, v[168:169]
	s_add_u32 s18, s4, s20
	s_addc_u32 s19, s5, 0
	v_lshl_add_u64 v[128:129], s[18:19], 0, v[162:163]
	v_lshl_add_u64 v[132:133], s[18:19], 0, v[164:165]
	v_lshl_add_u64 v[136:137], s[18:19], 0, v[166:167]
	v_lshl_add_u64 v[140:141], s[18:19], 0, v[168:169]
	global_load_dwordx4 v[112:115], v[112:113], off offset:256
	ds_read_b128 v[246:249], v177 offset:6976
	v_mfma_f32_16x16x32_bf16 v[108:111], v[178:181], v[198:201], v[108:111]
	v_mfma_f32_16x16x32_bf16 v[104:107], v[182:185], v[198:201], v[104:107]
	s_nop 0
	global_load_dwordx4 v[116:119], v[116:117], off offset:256
	v_mfma_f32_16x16x32_bf16 v[100:103], v[186:189], v[198:201], v[100:103]
	v_mfma_f32_16x16x32_bf16 v[96:99], v[190:193], v[198:201], v[96:99]
	ds_read_b128 v[194:197], v177 offset:9280
	s_waitcnt lgkmcnt(3)
	v_mfma_f32_16x16x32_bf16 v[92:95], v[178:181], v[242:245], v[92:95]
	s_nop 0
	global_load_dwordx4 v[120:123], v[120:121], off offset:256
	v_mfma_f32_16x16x32_bf16 v[88:91], v[182:185], v[242:245], v[88:91]
	v_mfma_f32_16x16x32_bf16 v[84:87], v[186:189], v[242:245], v[84:87]
	s_nop 0
	global_load_dwordx4 v[124:127], v[124:125], off offset:256
	v_mfma_f32_16x16x32_bf16 v[80:83], v[190:193], v[242:245], v[80:83]
	ds_read_b128 v[198:201], v177 offset:11584
	s_waitcnt lgkmcnt(2)
	v_mfma_f32_16x16x32_bf16 v[76:79], v[178:181], v[246:249], v[76:79]
	v_mfma_f32_16x16x32_bf16 v[72:75], v[182:185], v[246:249], v[72:75]
	s_nop 0
	global_load_dwordx4 v[128:131], v[128:129], off offset:256
	v_mfma_f32_16x16x32_bf16 v[68:71], v[186:189], v[246:249], v[68:71]
	v_mfma_f32_16x16x32_bf16 v[64:67], v[190:193], v[246:249], v[64:67]
	s_nop 0
	global_load_dwordx4 v[132:135], v[132:133], off offset:256
	ds_read_b128 v[242:245], v177 offset:13888
	s_waitcnt lgkmcnt(2)
	v_mfma_f32_16x16x32_bf16 v[60:63], v[178:181], v[194:197], v[60:63]
	v_mfma_f32_16x16x32_bf16 v[56:59], v[182:185], v[194:197], v[56:59]
	v_mfma_f32_16x16x32_bf16 v[52:55], v[186:189], v[194:197], v[52:55]
	s_nop 0
	global_load_dwordx4 v[136:139], v[136:137], off offset:256
	v_mfma_f32_16x16x32_bf16 v[48:51], v[190:193], v[194:197], v[48:51]
	ds_read_b128 v[246:249], v177 offset:16192
	s_waitcnt lgkmcnt(2)
	v_mfma_f32_16x16x32_bf16 v[44:47], v[178:181], v[198:201], v[44:47]
	s_nop 0
	global_load_dwordx4 v[140:143], v[140:141], off offset:256
	v_mfma_f32_16x16x32_bf16 v[40:43], v[182:185], v[198:201], v[40:43]
	v_mfma_f32_16x16x32_bf16 v[36:39], v[186:189], v[198:201], v[36:39]
	v_mfma_f32_16x16x32_bf16 v[32:35], v[190:193], v[198:201], v[32:35]
	s_waitcnt lgkmcnt(0)
	s_barrier
; DI f32x4 mfma16(bf16x8 a, bf16x8 b, f32x4 c) { return __builtin_amdgcn_mfma_f32_16x16x32_bf16(a, b, c, 0, 0, 0); }
; template <int MI, int NJ, bool SWAP, class AP, class BP>
; DI void gemm_main(f32x4 (&acc)[MI][NJ], const AP& ap, int a_kstep, const BP& bp, int b_kstep, int nk, bf16_t* smem) {
;     ...
;   for (int kt = 0; kt < nk; ++kt) {
;     const int buf = kt & 1;
;     sstore(buf ^ 1);
;     gload(kt + 2 < nk ? kt + 2 : nk - 1);
;     __builtin_amdgcn_sched_barrier(0);
;     const bf16_t* As = smem + buf * L::STAGE + (wm * 16 * MI + l15) * LDT + quad * 8;
;     const bf16_t* Bs = smem + buf * L::STAGE + L::A_ELEMS + (wn * 16 * NJ + l15) * LDT + quad * 8;
; #pragma unroll
;     for (int ks = 0; ks < 2; ++ks) {
;       if (MI * NJ >= 32 && ks == 1) asm volatile("" ::: "memory");
;       bf16x8 b[NJ];
; #pragma unroll
;       for (int j = 0; j < NJ; ++j) b[j] = *(const bf16x8*)(Bs + j * 16 * LDT + ks * 32);
; #pragma unroll
;       for (int i = 0; i < MI; ++i) {
;         const bf16x8 a = *(const bf16x8*)(As + i * 16 * LDT + ks * 32);
; #pragma unroll
;         for (int j = 0; j < NJ; ++j) acc[i][j] = SWAP ? mfma16(b[j], a, acc[i][j]) : mfma16(a, b[j], acc[i][j]);
;       }
	s_add_i32 s16, s16, 1
	s_cmp_lg_u32 s16, 44
	s_cbranch_scc0 .Lgm15_exit
	s_and_b32 s98, s16, 1
	s_mul_i32 s98, s98, 0x12000
	v_add3_u32 v202, s98, v160, v176
	v_add3_u32 v177, s98, v171, v176
	ds_read_b128 v[194:197], v177
	ds_read_b128 v[198:201], v177 offset:2304
	v_mfma_f32_16x16x32_bf16 v[28:31], v[178:181], v[242:245], v[28:31]
	v_mfma_f32_16x16x32_bf16 v[8:11], v[178:181], v[246:249], v[8:11]
	ds_read_b128 v[178:181], v202 offset:36864
	v_mfma_f32_16x16x32_bf16 v[24:27], v[182:185], v[242:245], v[24:27]
	v_mfma_f32_16x16x32_bf16 v[4:7], v[182:185], v[246:249], v[4:7]
	ds_read_b128 v[182:185], v202 offset:39168
	v_mfma_f32_16x16x32_bf16 v[20:23], v[186:189], v[242:245], v[20:23]
	v_mfma_f32_16x16x32_bf16 v[0:3], v[186:189], v[246:249], v[0:3]
	ds_read_b128 v[186:189], v202 offset:41472
	v_mfma_f32_16x16x32_bf16 v[16:19], v[190:193], v[242:245], v[16:19]
	v_mfma_f32_16x16x32_bf16 v[12:15], v[190:193], v[246:249], v[12:15]
	ds_read_b128 v[190:193], v202 offset:43776
	s_branch .Lgm15_main
